# K-loops: removed mid-block s_setprio 0/1 blips (40 pairs)
# speedup vs baseline: 1.0374x; 1.0002x over previous
.LBB0_205:
	s_add_u32 s22, s20, 0xfffc0080
	s_addc_u32 s23, s21, -1
	s_add_i32 s74, 0, 0x10000
	s_cmp_eq_u32 s73, 12
	s_cselect_b32 s25, s15, s23
	s_cselect_b32 s24, s37, s22
	s_cselect_b32 s23, s11, s72
	s_cselect_b32 s22, s40, s41
	s_add_i32 s76, 0, 0x14000
	v_add_u32_e32 v156, s74, v145
	v_add_u32_e32 v172, s76, v145
	ds_read_b128 v[140:143], v156
	ds_read_b128 v[148:151], v156 offset:1024
	ds_read_b128 v[152:155], v156 offset:2048
	ds_read_b128 v[156:159], v156 offset:3072
	ds_read_b128 v[160:163], v172
	ds_read_b128 v[164:167], v172 offset:1024
	ds_read_b128 v[168:171], v172 offset:2048
	ds_read_b128 v[172:175], v172 offset:3072
	v_lshl_add_u64 v[208:209], s[20:21], 0, v[138:139]
	s_add_i32 m0, s26, 0xc000
	ds_read_b128 v[176:179], v147
	ds_read_b128 v[180:183], v147 offset:1024
	ds_read_b128 v[184:187], v147 offset:2048
	ds_read_b128 v[188:191], v147 offset:3072
	ds_read_b128 v[192:195], v147 offset:4096
	ds_read_b128 v[196:199], v147 offset:5120
	ds_read_b128 v[200:203], v147 offset:6144
	ds_read_b128 v[204:207], v147 offset:7168
	global_load_lds_dwordx4 v[208:209], off
	v_lshl_add_u64 v[208:209], s[20:21], 0, v[136:137]
	s_add_i32 m0, s26, 0xe000
	s_nop 0
	global_load_lds_dwordx4 v[208:209], off
	s_waitcnt vmcnt(8)
	s_waitcnt lgkmcnt(0)
	s_barrier
	s_setprio 1
	s_waitcnt lgkmcnt(0)
	v_mfma_f32_16x16x32_bf16 v[126:129], v[140:143], v[176:179], v[126:129]
	v_mfma_f32_16x16x32_bf16 v[122:125], v[152:155], v[176:179], v[122:125]
	v_mfma_f32_16x16x32_bf16 v[118:121], v[140:143], v[184:187], v[118:121]
	v_mfma_f32_16x16x32_bf16 v[110:113], v[152:155], v[184:187], v[110:113]
	v_mfma_f32_16x16x32_bf16 v[102:105], v[140:143], v[192:195], v[102:105]
	v_mfma_f32_16x16x32_bf16 v[94:97], v[152:155], v[192:195], v[94:97]
	v_mfma_f32_16x16x32_bf16 v[86:89], v[140:143], v[200:203], v[86:89]
	v_mfma_f32_16x16x32_bf16 v[78:81], v[152:155], v[200:203], v[78:81]
	v_mfma_f32_16x16x32_bf16 v[126:129], v[148:151], v[180:183], v[126:129]
	v_mfma_f32_16x16x32_bf16 v[122:125], v[156:159], v[180:183], v[122:125]
	v_mfma_f32_16x16x32_bf16 v[118:121], v[148:151], v[188:191], v[118:121]
	v_mfma_f32_16x16x32_bf16 v[110:113], v[156:159], v[188:191], v[110:113]
	v_mfma_f32_16x16x32_bf16 v[102:105], v[148:151], v[196:199], v[102:105]
	v_mfma_f32_16x16x32_bf16 v[94:97], v[156:159], v[196:199], v[94:97]
	v_mfma_f32_16x16x32_bf16 v[86:89], v[148:151], v[204:207], v[86:89]
	v_mfma_f32_16x16x32_bf16 v[78:81], v[156:159], v[204:207], v[78:81]
	v_mfma_f32_16x16x32_bf16 v[114:117], v[160:163], v[176:179], v[114:117]
	v_mfma_f32_16x16x32_bf16 v[106:109], v[168:171], v[176:179], v[106:109]
	v_mfma_f32_16x16x32_bf16 v[98:101], v[160:163], v[184:187], v[98:101]
	v_mfma_f32_16x16x32_bf16 v[90:93], v[168:171], v[184:187], v[90:93]
	v_mfma_f32_16x16x32_bf16 v[82:85], v[160:163], v[192:195], v[82:85]
	v_mfma_f32_16x16x32_bf16 v[74:77], v[168:171], v[192:195], v[74:77]
	v_mfma_f32_16x16x32_bf16 v[70:73], v[160:163], v[200:203], v[70:73]
	v_mfma_f32_16x16x32_bf16 v[66:69], v[168:171], v[200:203], v[66:69]
	v_mfma_f32_16x16x32_bf16 v[114:117], v[164:167], v[180:183], v[114:117]
	v_mfma_f32_16x16x32_bf16 v[106:109], v[172:175], v[180:183], v[106:109]
	v_mfma_f32_16x16x32_bf16 v[98:101], v[164:167], v[188:191], v[98:101]
	v_mfma_f32_16x16x32_bf16 v[90:93], v[172:175], v[188:191], v[90:93]
	v_mfma_f32_16x16x32_bf16 v[82:85], v[164:167], v[196:199], v[82:85]
	v_mfma_f32_16x16x32_bf16 v[74:77], v[172:175], v[196:199], v[74:77]
	v_mfma_f32_16x16x32_bf16 v[70:73], v[164:167], v[204:207], v[70:73]
	v_mfma_f32_16x16x32_bf16 v[66:69], v[172:175], v[204:207], v[66:69]
	s_setprio 0
	s_barrier
	s_add_i32 s74, s74, s12
	v_lshl_add_u64 v[208:209], s[22:23], 0, v[0:1]
	s_mov_b32 m0, s74
	ds_read_b128 v[176:179], v147 offset:16384
	ds_read_b128 v[180:183], v147 offset:17408
	ds_read_b128 v[184:187], v147 offset:18432
	ds_read_b128 v[188:191], v147 offset:19456
	ds_read_b128 v[192:195], v147 offset:20480
	ds_read_b128 v[196:199], v147 offset:21504
	ds_read_b128 v[200:203], v147 offset:22528
	ds_read_b128 v[204:207], v147 offset:23552
	global_load_lds_dwordx4 v[208:209], off
	s_add_i32 m0, s74, 0x2000
	s_add_u32 s74, s22, 0x40000
	v_lshl_add_u64 v[214:215], s[22:23], 0, v[130:131]
	s_addc_u32 s75, s23, 0
	s_add_i32 s76, s76, s12
	global_load_lds_dwordx4 v[214:215], off
	v_lshl_add_u64 v[216:217], s[74:75], 0, v[0:1]
	s_mov_b32 m0, s76
	v_lshl_add_u64 v[218:219], s[24:25], 0, v[132:133]
	global_load_lds_dwordx4 v[216:217], off
	v_lshl_add_u64 v[216:217], s[74:75], 0, v[130:131]
	s_add_i32 m0, s76, 0x2000
	s_nop 0
	global_load_lds_dwordx4 v[216:217], off
	v_lshl_add_u64 v[216:217], s[24:25], 0, v[134:135]
	s_mov_b32 m0, s26
	s_nop 0
	global_load_lds_dwordx4 v[216:217], off
	s_mov_b32 m0, s27
	s_nop 0
	global_load_lds_dwordx4 v[218:219], off
	s_waitcnt vmcnt(8)
	s_waitcnt lgkmcnt(0)
	s_barrier
	s_setprio 1
	s_waitcnt lgkmcnt(0)
	v_mfma_f32_16x16x32_bf16 v[62:65], v[140:143], v[176:179], v[62:65]
	v_mfma_f32_16x16x32_bf16 v[58:61], v[152:155], v[176:179], v[58:61]
	v_mfma_f32_16x16x32_bf16 v[54:57], v[140:143], v[184:187], v[54:57]
	v_mfma_f32_16x16x32_bf16 v[46:49], v[152:155], v[184:187], v[46:49]
	v_mfma_f32_16x16x32_bf16 v[38:41], v[140:143], v[192:195], v[38:41]
	v_mfma_f32_16x16x32_bf16 v[30:33], v[152:155], v[192:195], v[30:33]
	v_mfma_f32_16x16x32_bf16 v[22:25], v[140:143], v[200:203], v[22:25]
	v_mfma_f32_16x16x32_bf16 v[14:17], v[152:155], v[200:203], v[14:17]
	v_mfma_f32_16x16x32_bf16 v[62:65], v[148:151], v[180:183], v[62:65]
	v_mfma_f32_16x16x32_bf16 v[58:61], v[156:159], v[180:183], v[58:61]
	v_mfma_f32_16x16x32_bf16 v[54:57], v[148:151], v[188:191], v[54:57]
	v_mfma_f32_16x16x32_bf16 v[46:49], v[156:159], v[188:191], v[46:49]
	v_mfma_f32_16x16x32_bf16 v[38:41], v[148:151], v[196:199], v[38:41]
	v_mfma_f32_16x16x32_bf16 v[30:33], v[156:159], v[196:199], v[30:33]
	v_mfma_f32_16x16x32_bf16 v[22:25], v[148:151], v[204:207], v[22:25]
	v_mfma_f32_16x16x32_bf16 v[14:17], v[156:159], v[204:207], v[14:17]
	v_mfma_f32_16x16x32_bf16 v[50:53], v[160:163], v[176:179], v[50:53]
	v_mfma_f32_16x16x32_bf16 v[42:45], v[168:171], v[176:179], v[42:45]
	v_mfma_f32_16x16x32_bf16 v[34:37], v[160:163], v[184:187], v[34:37]
	v_mfma_f32_16x16x32_bf16 v[26:29], v[168:171], v[184:187], v[26:29]
	v_mfma_f32_16x16x32_bf16 v[18:21], v[160:163], v[192:195], v[18:21]
	v_mfma_f32_16x16x32_bf16 v[10:13], v[168:171], v[192:195], v[10:13]
	v_mfma_f32_16x16x32_bf16 v[6:9], v[160:163], v[200:203], v[6:9]
	v_mfma_f32_16x16x32_bf16 v[2:5], v[168:171], v[200:203], v[2:5]
	v_mfma_f32_16x16x32_bf16 v[50:53], v[164:167], v[180:183], v[50:53]
	v_mfma_f32_16x16x32_bf16 v[42:45], v[172:175], v[180:183], v[42:45]
	v_mfma_f32_16x16x32_bf16 v[34:37], v[164:167], v[188:191], v[34:37]
	v_mfma_f32_16x16x32_bf16 v[26:29], v[172:175], v[188:191], v[26:29]
	v_mfma_f32_16x16x32_bf16 v[18:21], v[164:167], v[196:199], v[18:21]
	v_mfma_f32_16x16x32_bf16 v[10:13], v[172:175], v[196:199], v[10:13]
	v_mfma_f32_16x16x32_bf16 v[6:9], v[164:167], v[204:207], v[6:9]
	v_mfma_f32_16x16x32_bf16 v[2:5], v[172:175], v[204:207], v[2:5]
	s_setprio 0
	s_barrier
	s_add_i32 s74, 0, 0x18000
	s_add_i32 s75, 0, 0x1c000
	v_add_u32_e32 v156, s74, v145
	v_add_u32_e32 v172, s75, v145
	ds_read_b128 v[140:143], v156
	ds_read_b128 v[148:151], v156 offset:1024
	ds_read_b128 v[152:155], v156 offset:2048
	ds_read_b128 v[156:159], v156 offset:3072
	ds_read_b128 v[160:163], v172
	ds_read_b128 v[164:167], v172 offset:1024
	ds_read_b128 v[168:171], v172 offset:2048
	ds_read_b128 v[172:175], v172 offset:3072
	s_add_u32 s24, s24, 0x40000
	s_addc_u32 s25, s25, 0
	s_mov_b32 m0, s28
	v_lshl_add_u64 v[220:221], s[24:25], 0, v[134:135]
	ds_read_b128 v[176:179], v147 offset:32768
	ds_read_b128 v[180:183], v147 offset:33792
	ds_read_b128 v[184:187], v147 offset:34816
	ds_read_b128 v[188:191], v147 offset:35840
	ds_read_b128 v[192:195], v147 offset:36864
	ds_read_b128 v[196:199], v147 offset:37888
	ds_read_b128 v[200:203], v147 offset:38912
	ds_read_b128 v[204:207], v147 offset:39936
	global_load_lds_dwordx4 v[220:221], off
	v_lshl_add_u64 v[220:221], s[24:25], 0, v[132:133]
	s_mov_b32 m0, s29
	s_nop 0
	global_load_lds_dwordx4 v[220:221], off
	s_waitcnt vmcnt(8)
	s_waitcnt lgkmcnt(0)
	s_barrier
	s_setprio 1
	s_waitcnt lgkmcnt(0)
	v_mfma_f32_16x16x32_bf16 v[126:129], v[140:143], v[176:179], v[126:129]
	v_mfma_f32_16x16x32_bf16 v[122:125], v[152:155], v[176:179], v[122:125]
	v_mfma_f32_16x16x32_bf16 v[118:121], v[140:143], v[184:187], v[118:121]
	v_mfma_f32_16x16x32_bf16 v[110:113], v[152:155], v[184:187], v[110:113]
	v_mfma_f32_16x16x32_bf16 v[102:105], v[140:143], v[192:195], v[102:105]
	v_mfma_f32_16x16x32_bf16 v[94:97], v[152:155], v[192:195], v[94:97]
	v_mfma_f32_16x16x32_bf16 v[86:89], v[140:143], v[200:203], v[86:89]
	v_mfma_f32_16x16x32_bf16 v[78:81], v[152:155], v[200:203], v[78:81]
	v_mfma_f32_16x16x32_bf16 v[126:129], v[148:151], v[180:183], v[126:129]
	v_mfma_f32_16x16x32_bf16 v[122:125], v[156:159], v[180:183], v[122:125]
	v_mfma_f32_16x16x32_bf16 v[118:121], v[148:151], v[188:191], v[118:121]
	v_mfma_f32_16x16x32_bf16 v[110:113], v[156:159], v[188:191], v[110:113]
	v_mfma_f32_16x16x32_bf16 v[102:105], v[148:151], v[196:199], v[102:105]
	v_mfma_f32_16x16x32_bf16 v[94:97], v[156:159], v[196:199], v[94:97]
	v_mfma_f32_16x16x32_bf16 v[86:89], v[148:151], v[204:207], v[86:89]
	v_mfma_f32_16x16x32_bf16 v[78:81], v[156:159], v[204:207], v[78:81]
	v_mfma_f32_16x16x32_bf16 v[114:117], v[160:163], v[176:179], v[114:117]
	v_mfma_f32_16x16x32_bf16 v[106:109], v[168:171], v[176:179], v[106:109]
	v_mfma_f32_16x16x32_bf16 v[98:101], v[160:163], v[184:187], v[98:101]
	v_mfma_f32_16x16x32_bf16 v[90:93], v[168:171], v[184:187], v[90:93]
	v_mfma_f32_16x16x32_bf16 v[82:85], v[160:163], v[192:195], v[82:85]
	v_mfma_f32_16x16x32_bf16 v[74:77], v[168:171], v[192:195], v[74:77]
	v_mfma_f32_16x16x32_bf16 v[70:73], v[160:163], v[200:203], v[70:73]
	v_mfma_f32_16x16x32_bf16 v[66:69], v[168:171], v[200:203], v[66:69]
	v_mfma_f32_16x16x32_bf16 v[114:117], v[164:167], v[180:183], v[114:117]
	v_mfma_f32_16x16x32_bf16 v[106:109], v[172:175], v[180:183], v[106:109]
	v_mfma_f32_16x16x32_bf16 v[98:101], v[164:167], v[188:191], v[98:101]
	v_mfma_f32_16x16x32_bf16 v[90:93], v[172:175], v[188:191], v[90:93]
	v_mfma_f32_16x16x32_bf16 v[82:85], v[164:167], v[196:199], v[82:85]
	v_mfma_f32_16x16x32_bf16 v[74:77], v[172:175], v[196:199], v[74:77]
	v_mfma_f32_16x16x32_bf16 v[70:73], v[164:167], v[204:207], v[70:73]
	v_mfma_f32_16x16x32_bf16 v[66:69], v[172:175], v[204:207], v[66:69]
	s_setprio 0
	s_barrier
	s_add_i32 s24, s74, s12
	v_lshl_add_u64 v[208:209], v[208:209], 0, s[50:51]
	s_mov_b32 m0, s24
	ds_read_b128 v[176:179], v147 offset:49152
	ds_read_b128 v[180:183], v147 offset:50176
	ds_read_b128 v[184:187], v147 offset:51200
	ds_read_b128 v[188:191], v147 offset:52224
	ds_read_b128 v[192:195], v147 offset:53248
	ds_read_b128 v[196:199], v147 offset:54272
	ds_read_b128 v[200:203], v147 offset:55296
	ds_read_b128 v[204:207], v147 offset:56320
	global_load_lds_dwordx4 v[208:209], off
	s_add_i32 m0, s24, 0x2000
	s_add_u32 s22, s22, 0x40080
	v_lshl_add_u64 v[208:209], v[214:215], 0, s[50:51]
	s_addc_u32 s23, s23, 0
	s_add_i32 s24, s75, s12
	global_load_lds_dwordx4 v[208:209], off
	v_lshl_add_u64 v[208:209], s[22:23], 0, v[0:1]
	s_mov_b32 m0, s24
	s_nop 0
	global_load_lds_dwordx4 v[208:209], off
	v_lshl_add_u64 v[208:209], s[22:23], 0, v[130:131]
	s_add_i32 m0, s24, 0x2000
	s_nop 0
	global_load_lds_dwordx4 v[208:209], off
	v_lshl_add_u64 v[208:209], v[216:217], 0, s[50:51]
	s_mov_b32 m0, s30
	s_nop 0
	global_load_lds_dwordx4 v[208:209], off
	v_lshl_add_u64 v[208:209], v[218:219], 0, s[50:51]
	s_mov_b32 m0, s31
	s_nop 0
	global_load_lds_dwordx4 v[208:209], off
	s_waitcnt vmcnt(8)
	s_waitcnt lgkmcnt(0)
	s_barrier
	s_setprio 1
	s_waitcnt lgkmcnt(0)
	v_mfma_f32_16x16x32_bf16 v[62:65], v[140:143], v[176:179], v[62:65]
	v_mfma_f32_16x16x32_bf16 v[58:61], v[152:155], v[176:179], v[58:61]
	v_mfma_f32_16x16x32_bf16 v[54:57], v[140:143], v[184:187], v[54:57]
	v_mfma_f32_16x16x32_bf16 v[46:49], v[152:155], v[184:187], v[46:49]
	v_mfma_f32_16x16x32_bf16 v[38:41], v[140:143], v[192:195], v[38:41]
	v_mfma_f32_16x16x32_bf16 v[30:33], v[152:155], v[192:195], v[30:33]
	v_mfma_f32_16x16x32_bf16 v[22:25], v[140:143], v[200:203], v[22:25]
	v_mfma_f32_16x16x32_bf16 v[14:17], v[152:155], v[200:203], v[14:17]
	v_mfma_f32_16x16x32_bf16 v[62:65], v[148:151], v[180:183], v[62:65]
	v_mfma_f32_16x16x32_bf16 v[58:61], v[156:159], v[180:183], v[58:61]
	v_mfma_f32_16x16x32_bf16 v[54:57], v[148:151], v[188:191], v[54:57]
	v_mfma_f32_16x16x32_bf16 v[46:49], v[156:159], v[188:191], v[46:49]
	v_mfma_f32_16x16x32_bf16 v[38:41], v[148:151], v[196:199], v[38:41]
	v_mfma_f32_16x16x32_bf16 v[30:33], v[156:159], v[196:199], v[30:33]
	v_mfma_f32_16x16x32_bf16 v[22:25], v[148:151], v[204:207], v[22:25]
	v_mfma_f32_16x16x32_bf16 v[14:17], v[156:159], v[204:207], v[14:17]
	v_mfma_f32_16x16x32_bf16 v[50:53], v[160:163], v[176:179], v[50:53]
	v_mfma_f32_16x16x32_bf16 v[42:45], v[168:171], v[176:179], v[42:45]
	v_mfma_f32_16x16x32_bf16 v[34:37], v[160:163], v[184:187], v[34:37]
	v_mfma_f32_16x16x32_bf16 v[26:29], v[168:171], v[184:187], v[26:29]
	v_mfma_f32_16x16x32_bf16 v[18:21], v[160:163], v[192:195], v[18:21]
	v_mfma_f32_16x16x32_bf16 v[10:13], v[168:171], v[192:195], v[10:13]
	v_mfma_f32_16x16x32_bf16 v[6:9], v[160:163], v[200:203], v[6:9]
	v_mfma_f32_16x16x32_bf16 v[2:5], v[168:171], v[200:203], v[2:5]
	v_mfma_f32_16x16x32_bf16 v[50:53], v[164:167], v[180:183], v[50:53]
	v_mfma_f32_16x16x32_bf16 v[42:45], v[172:175], v[180:183], v[42:45]
	v_mfma_f32_16x16x32_bf16 v[34:37], v[164:167], v[188:191], v[34:37]
	v_mfma_f32_16x16x32_bf16 v[26:29], v[172:175], v[188:191], v[26:29]
	v_mfma_f32_16x16x32_bf16 v[18:21], v[164:167], v[196:199], v[18:21]
	v_mfma_f32_16x16x32_bf16 v[10:13], v[172:175], v[196:199], v[10:13]
	v_mfma_f32_16x16x32_bf16 v[6:9], v[164:167], v[204:207], v[6:9]
	v_mfma_f32_16x16x32_bf16 v[2:5], v[172:175], v[204:207], v[2:5]
	s_setprio 0
	s_barrier
	s_add_i32 s73, s73, 2
	s_add_u32 s41, s41, 0x100
	s_addc_u32 s72, s72, 0
	s_add_u32 s20, s20, 0x100
	s_addc_u32 s21, s21, 0
	s_cmp_gt_u32 s73, 13
	s_cbranch_scc0 .LBB0_205
	s_and_b64 vcc, exec, s[8:9]
	s_cbranch_vccz .LBB0_208
	s_barrier

.LBB0_615:
	s_add_u32 s4, s10, s30
	s_addc_u32 s5, s11, s31
	s_add_u32 s4, s4, 0x100
	s_addc_u32 s5, s5, 0
	s_add_u32 s74, s17, s30
	s_addc_u32 s75, vcc_lo, s31
	s_add_i32 s76, 0, 0x10000
	s_cmpk_eq_i32 s30, 0x700
	s_cselect_b32 s35, s25, s5
	s_cselect_b32 s34, vcc_hi, s4
	v_add_u32_e32 v147, s76, v131
	s_cselect_b32 s5, s23, s75
	s_cselect_b32 s4, s72, s74
	s_add_i32 s77, 0, 0x14000
	ds_read_b128 v[148:151], v147
	ds_read_b128 v[152:155], v147 offset:1024
	ds_read_b128 v[156:159], v147 offset:2048
	ds_read_b128 v[160:163], v147 offset:3072
	v_add_u32_e32 v147, s77, v131
	ds_read_b128 v[164:167], v147
	ds_read_b128 v[168:171], v147 offset:1024
	ds_read_b128 v[172:175], v147 offset:2048
	ds_read_b128 v[176:179], v147 offset:3072
	v_lshl_add_u64 v[208:209], v[144:145], 0, s[30:31]
	s_add_i32 m0, s71, 0xc000
	ds_read_b128 v[180:183], v146
	ds_read_b128 v[184:187], v146 offset:1024
	ds_read_b128 v[188:191], v146 offset:2048
	ds_read_b128 v[192:195], v146 offset:3072
	ds_read_b128 v[196:199], v146 offset:4096
	ds_read_b128 v[200:203], v146 offset:5120
	ds_read_b128 v[204:207], v146 offset:6144
	ds_read_b128 v[248:251], v146 offset:7168
	global_load_lds_dwordx4 v[208:209], off
	v_lshl_add_u64 v[208:209], v[142:143], 0, s[30:31]
	s_add_i32 m0, s71, 0xe000
	s_nop 0
	global_load_lds_dwordx4 v[208:209], off
	s_waitcnt vmcnt(8)
	s_waitcnt lgkmcnt(0)
	s_barrier
	s_setprio 1
	s_waitcnt lgkmcnt(0)
	v_mfma_f32_16x16x32_bf16 v[126:129], v[148:151], v[180:183], v[126:129]
	v_mfma_f32_16x16x32_bf16 v[122:125], v[156:159], v[180:183], v[122:125]
	v_mfma_f32_16x16x32_bf16 v[114:117], v[148:151], v[188:191], v[114:117]
	v_mfma_f32_16x16x32_bf16 v[106:109], v[156:159], v[188:191], v[106:109]
	v_mfma_f32_16x16x32_bf16 v[98:101], v[148:151], v[196:199], v[98:101]
	v_mfma_f32_16x16x32_bf16 v[90:93], v[156:159], v[196:199], v[90:93]
	v_mfma_f32_16x16x32_bf16 v[82:85], v[148:151], v[204:207], v[82:85]
	v_mfma_f32_16x16x32_bf16 v[74:77], v[156:159], v[204:207], v[74:77]
	v_mfma_f32_16x16x32_bf16 v[126:129], v[152:155], v[184:187], v[126:129]
	v_mfma_f32_16x16x32_bf16 v[122:125], v[160:163], v[184:187], v[122:125]
	v_mfma_f32_16x16x32_bf16 v[114:117], v[152:155], v[192:195], v[114:117]
	v_mfma_f32_16x16x32_bf16 v[106:109], v[160:163], v[192:195], v[106:109]
	v_mfma_f32_16x16x32_bf16 v[98:101], v[152:155], v[200:203], v[98:101]
	v_mfma_f32_16x16x32_bf16 v[90:93], v[160:163], v[200:203], v[90:93]
	v_mfma_f32_16x16x32_bf16 v[82:85], v[152:155], v[248:251], v[82:85]
	v_mfma_f32_16x16x32_bf16 v[74:77], v[160:163], v[248:251], v[74:77]
	v_mfma_f32_16x16x32_bf16 v[118:121], v[164:167], v[180:183], v[118:121]
	v_mfma_f32_16x16x32_bf16 v[110:113], v[172:175], v[180:183], v[110:113]
	v_mfma_f32_16x16x32_bf16 v[102:105], v[164:167], v[188:191], v[102:105]
	v_mfma_f32_16x16x32_bf16 v[94:97], v[172:175], v[188:191], v[94:97]
	v_mfma_f32_16x16x32_bf16 v[86:89], v[164:167], v[196:199], v[86:89]
	v_mfma_f32_16x16x32_bf16 v[78:81], v[172:175], v[196:199], v[78:81]
	v_mfma_f32_16x16x32_bf16 v[70:73], v[164:167], v[204:207], v[70:73]
	v_mfma_f32_16x16x32_bf16 v[66:69], v[172:175], v[204:207], v[66:69]
	v_mfma_f32_16x16x32_bf16 v[118:121], v[168:171], v[184:187], v[118:121]
	v_mfma_f32_16x16x32_bf16 v[110:113], v[176:179], v[184:187], v[110:113]
	v_mfma_f32_16x16x32_bf16 v[102:105], v[168:171], v[192:195], v[102:105]
	v_mfma_f32_16x16x32_bf16 v[94:97], v[176:179], v[192:195], v[94:97]
	v_mfma_f32_16x16x32_bf16 v[86:89], v[168:171], v[200:203], v[86:89]
	v_mfma_f32_16x16x32_bf16 v[78:81], v[176:179], v[200:203], v[78:81]
	v_mfma_f32_16x16x32_bf16 v[70:73], v[168:171], v[248:251], v[70:73]
	v_mfma_f32_16x16x32_bf16 v[66:69], v[176:179], v[248:251], v[66:69]
	s_setprio 0
	s_barrier
	s_add_i32 s74, s76, s38
	v_lshl_add_u64 v[208:209], s[4:5], 0, v[0:1]
	s_mov_b32 m0, s74
	ds_read_b128 v[180:183], v146 offset:16384
	ds_read_b128 v[184:187], v146 offset:17408
	ds_read_b128 v[188:191], v146 offset:18432
	ds_read_b128 v[192:195], v146 offset:19456
	ds_read_b128 v[196:199], v146 offset:20480
	ds_read_b128 v[200:203], v146 offset:21504
	ds_read_b128 v[204:207], v146 offset:22528
	ds_read_b128 v[248:251], v146 offset:23552
	global_load_lds_dwordx4 v[208:209], off
	s_add_i32 m0, s74, 0x2000
	s_add_u32 s74, s4, 0x40000
	v_lshl_add_u64 v[214:215], s[4:5], 0, v[132:133]
	s_addc_u32 s75, s5, 0
	s_add_i32 s76, s77, s38
	global_load_lds_dwordx4 v[214:215], off
	v_lshl_add_u64 v[218:219], s[74:75], 0, v[0:1]
	s_mov_b32 m0, s76
	v_lshl_add_u64 v[230:231], s[34:35], 0, v[134:135]
	global_load_lds_dwordx4 v[218:219], off
	v_lshl_add_u64 v[218:219], s[74:75], 0, v[132:133]
	s_add_i32 m0, s76, 0x2000
	s_nop 0
	global_load_lds_dwordx4 v[218:219], off
	v_lshl_add_u64 v[218:219], s[34:35], 0, v[136:137]
	s_mov_b32 m0, s71
	s_nop 0
	global_load_lds_dwordx4 v[218:219], off
	s_mov_b32 m0, s39
	s_nop 0
	global_load_lds_dwordx4 v[230:231], off
	s_waitcnt vmcnt(8)
	s_waitcnt lgkmcnt(0)
	s_barrier
	s_setprio 1
	s_waitcnt lgkmcnt(0)
	v_mfma_f32_16x16x32_bf16 v[62:65], v[148:151], v[180:183], v[62:65]
	v_mfma_f32_16x16x32_bf16 v[58:61], v[156:159], v[180:183], v[58:61]
	v_mfma_f32_16x16x32_bf16 v[50:53], v[148:151], v[188:191], v[50:53]
	v_mfma_f32_16x16x32_bf16 v[42:45], v[156:159], v[188:191], v[42:45]
	v_mfma_f32_16x16x32_bf16 v[34:37], v[148:151], v[196:199], v[34:37]
	v_mfma_f32_16x16x32_bf16 v[26:29], v[156:159], v[196:199], v[26:29]
	v_mfma_f32_16x16x32_bf16 v[18:21], v[148:151], v[204:207], v[18:21]
	v_mfma_f32_16x16x32_bf16 v[10:13], v[156:159], v[204:207], v[10:13]
	v_mfma_f32_16x16x32_bf16 v[62:65], v[152:155], v[184:187], v[62:65]
	v_mfma_f32_16x16x32_bf16 v[58:61], v[160:163], v[184:187], v[58:61]
	v_mfma_f32_16x16x32_bf16 v[50:53], v[152:155], v[192:195], v[50:53]
	v_mfma_f32_16x16x32_bf16 v[42:45], v[160:163], v[192:195], v[42:45]
	v_mfma_f32_16x16x32_bf16 v[34:37], v[152:155], v[200:203], v[34:37]
	v_mfma_f32_16x16x32_bf16 v[26:29], v[160:163], v[200:203], v[26:29]
	v_mfma_f32_16x16x32_bf16 v[18:21], v[152:155], v[248:251], v[18:21]
	v_mfma_f32_16x16x32_bf16 v[10:13], v[160:163], v[248:251], v[10:13]
	v_mfma_f32_16x16x32_bf16 v[54:57], v[164:167], v[180:183], v[54:57]
	v_mfma_f32_16x16x32_bf16 v[46:49], v[172:175], v[180:183], v[46:49]
	v_mfma_f32_16x16x32_bf16 v[38:41], v[164:167], v[188:191], v[38:41]
	v_mfma_f32_16x16x32_bf16 v[30:33], v[172:175], v[188:191], v[30:33]
	v_mfma_f32_16x16x32_bf16 v[22:25], v[164:167], v[196:199], v[22:25]
	v_mfma_f32_16x16x32_bf16 v[14:17], v[172:175], v[196:199], v[14:17]
	v_mfma_f32_16x16x32_bf16 v[6:9], v[164:167], v[204:207], v[6:9]
	v_mfma_f32_16x16x32_bf16 v[2:5], v[172:175], v[204:207], v[2:5]
	v_mfma_f32_16x16x32_bf16 v[54:57], v[168:171], v[184:187], v[54:57]
	v_mfma_f32_16x16x32_bf16 v[46:49], v[176:179], v[184:187], v[46:49]
	v_mfma_f32_16x16x32_bf16 v[38:41], v[168:171], v[192:195], v[38:41]
	v_mfma_f32_16x16x32_bf16 v[30:33], v[176:179], v[192:195], v[30:33]
	v_mfma_f32_16x16x32_bf16 v[22:25], v[168:171], v[200:203], v[22:25]
	v_mfma_f32_16x16x32_bf16 v[14:17], v[176:179], v[200:203], v[14:17]
	v_mfma_f32_16x16x32_bf16 v[6:9], v[168:171], v[248:251], v[6:9]
	v_mfma_f32_16x16x32_bf16 v[2:5], v[176:179], v[248:251], v[2:5]
	s_setprio 0
	s_barrier
	s_add_i32 s74, 0, 0x18000
	v_add_u32_e32 v147, s74, v131
	s_add_i32 s75, 0, 0x1c000
	ds_read_b128 v[148:151], v147
	ds_read_b128 v[152:155], v147 offset:1024
	ds_read_b128 v[156:159], v147 offset:2048
	ds_read_b128 v[160:163], v147 offset:3072
	v_add_u32_e32 v147, s75, v131
	ds_read_b128 v[164:167], v147
	ds_read_b128 v[168:171], v147 offset:1024
	ds_read_b128 v[172:175], v147 offset:2048
	ds_read_b128 v[176:179], v147 offset:3072
	s_add_u32 s34, s34, 0x40000
	s_addc_u32 s35, s35, 0
	s_mov_b32 m0, s37
	v_lshl_add_u64 v[232:233], s[34:35], 0, v[136:137]
	ds_read_b128 v[180:183], v146 offset:32768
	ds_read_b128 v[184:187], v146 offset:33792
	ds_read_b128 v[188:191], v146 offset:34816
	ds_read_b128 v[192:195], v146 offset:35840
	ds_read_b128 v[196:199], v146 offset:36864
	ds_read_b128 v[200:203], v146 offset:37888
	ds_read_b128 v[204:207], v146 offset:38912
	ds_read_b128 v[248:251], v146 offset:39936
	global_load_lds_dwordx4 v[232:233], off
	v_lshl_add_u64 v[232:233], s[34:35], 0, v[134:135]
	s_mov_b32 m0, s14
	s_nop 0
	global_load_lds_dwordx4 v[232:233], off
	s_waitcnt vmcnt(8)
	s_waitcnt lgkmcnt(0)
	s_barrier
	s_setprio 1
	s_waitcnt lgkmcnt(0)
	v_mfma_f32_16x16x32_bf16 v[126:129], v[148:151], v[180:183], v[126:129]
	v_mfma_f32_16x16x32_bf16 v[122:125], v[156:159], v[180:183], v[122:125]
	v_mfma_f32_16x16x32_bf16 v[114:117], v[148:151], v[188:191], v[114:117]
	v_mfma_f32_16x16x32_bf16 v[106:109], v[156:159], v[188:191], v[106:109]
	v_mfma_f32_16x16x32_bf16 v[98:101], v[148:151], v[196:199], v[98:101]
	v_mfma_f32_16x16x32_bf16 v[90:93], v[156:159], v[196:199], v[90:93]
	v_mfma_f32_16x16x32_bf16 v[82:85], v[148:151], v[204:207], v[82:85]
	v_mfma_f32_16x16x32_bf16 v[74:77], v[156:159], v[204:207], v[74:77]
	v_mfma_f32_16x16x32_bf16 v[126:129], v[152:155], v[184:187], v[126:129]
	v_mfma_f32_16x16x32_bf16 v[122:125], v[160:163], v[184:187], v[122:125]
	v_mfma_f32_16x16x32_bf16 v[114:117], v[152:155], v[192:195], v[114:117]
	v_mfma_f32_16x16x32_bf16 v[106:109], v[160:163], v[192:195], v[106:109]
	v_mfma_f32_16x16x32_bf16 v[98:101], v[152:155], v[200:203], v[98:101]
	v_mfma_f32_16x16x32_bf16 v[90:93], v[160:163], v[200:203], v[90:93]
	v_mfma_f32_16x16x32_bf16 v[82:85], v[152:155], v[248:251], v[82:85]
	v_mfma_f32_16x16x32_bf16 v[74:77], v[160:163], v[248:251], v[74:77]
	v_mfma_f32_16x16x32_bf16 v[118:121], v[164:167], v[180:183], v[118:121]
	v_mfma_f32_16x16x32_bf16 v[110:113], v[172:175], v[180:183], v[110:113]
	v_mfma_f32_16x16x32_bf16 v[102:105], v[164:167], v[188:191], v[102:105]
	v_mfma_f32_16x16x32_bf16 v[94:97], v[172:175], v[188:191], v[94:97]
	v_mfma_f32_16x16x32_bf16 v[86:89], v[164:167], v[196:199], v[86:89]
	v_mfma_f32_16x16x32_bf16 v[78:81], v[172:175], v[196:199], v[78:81]
	v_mfma_f32_16x16x32_bf16 v[70:73], v[164:167], v[204:207], v[70:73]
	v_mfma_f32_16x16x32_bf16 v[66:69], v[172:175], v[204:207], v[66:69]
	v_mfma_f32_16x16x32_bf16 v[118:121], v[168:171], v[184:187], v[118:121]
	v_mfma_f32_16x16x32_bf16 v[110:113], v[176:179], v[184:187], v[110:113]
	v_mfma_f32_16x16x32_bf16 v[102:105], v[168:171], v[192:195], v[102:105]
	v_mfma_f32_16x16x32_bf16 v[94:97], v[176:179], v[192:195], v[94:97]
	v_mfma_f32_16x16x32_bf16 v[86:89], v[168:171], v[200:203], v[86:89]
	v_mfma_f32_16x16x32_bf16 v[78:81], v[176:179], v[200:203], v[78:81]
	v_mfma_f32_16x16x32_bf16 v[70:73], v[168:171], v[248:251], v[70:73]
	v_mfma_f32_16x16x32_bf16 v[66:69], v[176:179], v[248:251], v[66:69]
	s_setprio 0
	s_barrier
	s_add_i32 s34, s74, s38
	v_lshl_add_u64 v[208:209], v[208:209], 0, s[50:51]
	s_mov_b32 m0, s34
	ds_read_b128 v[180:183], v146 offset:49152
	ds_read_b128 v[184:187], v146 offset:50176
	ds_read_b128 v[188:191], v146 offset:51200
	ds_read_b128 v[192:195], v146 offset:52224
	ds_read_b128 v[196:199], v146 offset:53248
	ds_read_b128 v[200:203], v146 offset:54272
	ds_read_b128 v[204:207], v146 offset:55296
	ds_read_b128 v[248:251], v146 offset:56320
	global_load_lds_dwordx4 v[208:209], off
	s_add_i32 m0, s34, 0x2000
	s_add_u32 s4, s4, 0x40080
	v_lshl_add_u64 v[208:209], v[214:215], 0, s[50:51]
	s_addc_u32 s5, s5, 0
	s_add_i32 s34, s75, s38
	global_load_lds_dwordx4 v[208:209], off
	v_lshl_add_u64 v[208:209], s[4:5], 0, v[0:1]
	s_mov_b32 m0, s34
	s_nop 0
	global_load_lds_dwordx4 v[208:209], off
	v_lshl_add_u64 v[208:209], s[4:5], 0, v[132:133]
	s_add_i32 m0, s34, 0x2000
	s_nop 0
	global_load_lds_dwordx4 v[208:209], off
	v_lshl_add_u64 v[208:209], v[218:219], 0, s[50:51]
	s_mov_b32 m0, s15
	s_nop 0
	global_load_lds_dwordx4 v[208:209], off
	v_lshl_add_u64 v[208:209], v[230:231], 0, s[50:51]
	s_mov_b32 m0, s12
	s_nop 0
	global_load_lds_dwordx4 v[208:209], off
	s_waitcnt vmcnt(8)
	s_waitcnt lgkmcnt(0)
	s_barrier
	s_setprio 1
	s_waitcnt lgkmcnt(0)
	v_mfma_f32_16x16x32_bf16 v[62:65], v[148:151], v[180:183], v[62:65]
	v_mfma_f32_16x16x32_bf16 v[58:61], v[156:159], v[180:183], v[58:61]
	v_mfma_f32_16x16x32_bf16 v[50:53], v[148:151], v[188:191], v[50:53]
	v_mfma_f32_16x16x32_bf16 v[42:45], v[156:159], v[188:191], v[42:45]
	v_mfma_f32_16x16x32_bf16 v[34:37], v[148:151], v[196:199], v[34:37]
	v_mfma_f32_16x16x32_bf16 v[26:29], v[156:159], v[196:199], v[26:29]
	v_mfma_f32_16x16x32_bf16 v[18:21], v[148:151], v[204:207], v[18:21]
	v_mfma_f32_16x16x32_bf16 v[10:13], v[156:159], v[204:207], v[10:13]
	v_mfma_f32_16x16x32_bf16 v[62:65], v[152:155], v[184:187], v[62:65]
	v_mfma_f32_16x16x32_bf16 v[58:61], v[160:163], v[184:187], v[58:61]
	v_mfma_f32_16x16x32_bf16 v[50:53], v[152:155], v[192:195], v[50:53]
	v_mfma_f32_16x16x32_bf16 v[42:45], v[160:163], v[192:195], v[42:45]
	v_mfma_f32_16x16x32_bf16 v[34:37], v[152:155], v[200:203], v[34:37]
	v_mfma_f32_16x16x32_bf16 v[26:29], v[160:163], v[200:203], v[26:29]
	v_mfma_f32_16x16x32_bf16 v[18:21], v[152:155], v[248:251], v[18:21]
	v_mfma_f32_16x16x32_bf16 v[10:13], v[160:163], v[248:251], v[10:13]
	v_mfma_f32_16x16x32_bf16 v[54:57], v[164:167], v[180:183], v[54:57]
	v_mfma_f32_16x16x32_bf16 v[46:49], v[172:175], v[180:183], v[46:49]
	v_mfma_f32_16x16x32_bf16 v[38:41], v[164:167], v[188:191], v[38:41]
	v_mfma_f32_16x16x32_bf16 v[30:33], v[172:175], v[188:191], v[30:33]
	v_mfma_f32_16x16x32_bf16 v[22:25], v[164:167], v[196:199], v[22:25]
	v_mfma_f32_16x16x32_bf16 v[14:17], v[172:175], v[196:199], v[14:17]
	v_mfma_f32_16x16x32_bf16 v[6:9], v[164:167], v[204:207], v[6:9]
	v_mfma_f32_16x16x32_bf16 v[2:5], v[172:175], v[204:207], v[2:5]
	v_mfma_f32_16x16x32_bf16 v[54:57], v[168:171], v[184:187], v[54:57]
	v_mfma_f32_16x16x32_bf16 v[46:49], v[176:179], v[184:187], v[46:49]
	v_mfma_f32_16x16x32_bf16 v[38:41], v[168:171], v[192:195], v[38:41]
	v_mfma_f32_16x16x32_bf16 v[30:33], v[176:179], v[192:195], v[30:33]
	v_mfma_f32_16x16x32_bf16 v[22:25], v[168:171], v[200:203], v[22:25]
	v_mfma_f32_16x16x32_bf16 v[14:17], v[176:179], v[200:203], v[14:17]
	v_mfma_f32_16x16x32_bf16 v[6:9], v[168:171], v[248:251], v[6:9]
	v_mfma_f32_16x16x32_bf16 v[2:5], v[176:179], v[248:251], v[2:5]
	s_setprio 0
	s_barrier
	s_add_i32 s73, s73, 2
	s_add_u32 s30, s30, 0x100
	s_addc_u32 s31, s31, 0
	s_cmp_gt_u32 s73, 13
	s_cbranch_scc0 .LBB0_615
	s_add_u32 s4, s17, 0xffffff00
	s_addc_u32 s5, vcc_lo, -1
	s_andn2_b64 vcc, exec, s[8:9]
	s_cbranch_vccnz .LBB0_618
	v_mov_b32_e32 v2, 0
	s_mov_b32 s18, s22
	s_mov_b32 s20, s24
	s_mov_b64 s[10:11], s[28:29]
	s_mov_b32 s21, s16
	v_mov_b32_e32 v3, v2
	v_mov_b32_e32 v4, v2
	v_mov_b32_e32 v5, v2
	v_mov_b32_e32 v6, v2
	v_mov_b32_e32 v7, v2
	v_mov_b32_e32 v8, v2
	v_mov_b32_e32 v9, v2
	v_mov_b32_e32 v14, v2
	v_mov_b32_e32 v15, v2
	v_mov_b32_e32 v16, v2
	v_mov_b32_e32 v17, v2
	v_mov_b32_e32 v22, v2
	v_mov_b32_e32 v23, v2
	v_mov_b32_e32 v24, v2
	v_mov_b32_e32 v25, v2
	v_mov_b32_e32 v30, v2
	v_mov_b32_e32 v31, v2
	v_mov_b32_e32 v32, v2
	v_mov_b32_e32 v33, v2
	v_mov_b32_e32 v38, v2
	v_mov_b32_e32 v39, v2
	v_mov_b32_e32 v40, v2
	v_mov_b32_e32 v41, v2
	v_mov_b32_e32 v46, v2
	v_mov_b32_e32 v47, v2
	v_mov_b32_e32 v48, v2
	v_mov_b32_e32 v49, v2
	v_mov_b32_e32 v54, v2
	v_mov_b32_e32 v55, v2
	v_mov_b32_e32 v56, v2
	v_mov_b32_e32 v57, v2
	v_mov_b32_e32 v10, v2
	v_mov_b32_e32 v11, v2
	v_mov_b32_e32 v12, v2
	v_mov_b32_e32 v13, v2
	v_mov_b32_e32 v18, v2
	v_mov_b32_e32 v19, v2
	v_mov_b32_e32 v20, v2
	v_mov_b32_e32 v21, v2
	v_mov_b32_e32 v26, v2
	v_mov_b32_e32 v27, v2
	v_mov_b32_e32 v28, v2
	v_mov_b32_e32 v29, v2
	v_mov_b32_e32 v34, v2
	v_mov_b32_e32 v35, v2
	v_mov_b32_e32 v36, v2
	v_mov_b32_e32 v37, v2
	v_mov_b32_e32 v42, v2
	v_mov_b32_e32 v43, v2
	v_mov_b32_e32 v44, v2
	v_mov_b32_e32 v45, v2
	v_mov_b32_e32 v50, v2
	v_mov_b32_e32 v51, v2
	v_mov_b32_e32 v52, v2
	v_mov_b32_e32 v53, v2
	v_mov_b32_e32 v58, v2
	v_mov_b32_e32 v59, v2
	v_mov_b32_e32 v60, v2
	v_mov_b32_e32 v61, v2
	v_mov_b32_e32 v62, v2
	v_mov_b32_e32 v63, v2
	v_mov_b32_e32 v64, v2
	v_mov_b32_e32 v65, v2
	v_mov_b32_e32 v66, v2
	v_mov_b32_e32 v67, v2
	v_mov_b32_e32 v68, v2
	v_mov_b32_e32 v69, v2
	v_mov_b32_e32 v70, v2
	v_mov_b32_e32 v71, v2
	v_mov_b32_e32 v72, v2
	v_mov_b32_e32 v73, v2
	v_mov_b32_e32 v78, v2
	v_mov_b32_e32 v79, v2
	v_mov_b32_e32 v80, v2
	v_mov_b32_e32 v81, v2
	v_mov_b32_e32 v86, v2
	v_mov_b32_e32 v87, v2
	v_mov_b32_e32 v88, v2
	v_mov_b32_e32 v89, v2
	v_mov_b32_e32 v94, v2
	v_mov_b32_e32 v95, v2
	v_mov_b32_e32 v96, v2
	v_mov_b32_e32 v97, v2
	v_mov_b32_e32 v102, v2
	v_mov_b32_e32 v103, v2
	v_mov_b32_e32 v104, v2
	v_mov_b32_e32 v105, v2
	v_mov_b32_e32 v110, v2
	v_mov_b32_e32 v111, v2
	v_mov_b32_e32 v112, v2
	v_mov_b32_e32 v113, v2
	v_mov_b32_e32 v118, v2
	v_mov_b32_e32 v119, v2
	v_mov_b32_e32 v120, v2
	v_mov_b32_e32 v121, v2
	v_mov_b32_e32 v74, v2
	v_mov_b32_e32 v75, v2
	v_mov_b32_e32 v76, v2
	v_mov_b32_e32 v77, v2
	v_mov_b32_e32 v82, v2
	v_mov_b32_e32 v83, v2
	v_mov_b32_e32 v84, v2
	v_mov_b32_e32 v85, v2
	v_mov_b32_e32 v90, v2
	v_mov_b32_e32 v91, v2
	v_mov_b32_e32 v92, v2
	v_mov_b32_e32 v93, v2
	v_mov_b32_e32 v98, v2
	v_mov_b32_e32 v99, v2
	v_mov_b32_e32 v100, v2
	v_mov_b32_e32 v101, v2
	v_mov_b32_e32 v106, v2
	v_mov_b32_e32 v107, v2
	v_mov_b32_e32 v108, v2
	v_mov_b32_e32 v109, v2
	v_mov_b32_e32 v114, v2
	v_mov_b32_e32 v115, v2
	v_mov_b32_e32 v116, v2
	v_mov_b32_e32 v117, v2
	v_mov_b32_e32 v122, v2
	v_mov_b32_e32 v123, v2
	v_mov_b32_e32 v124, v2
	v_mov_b32_e32 v125, v2
	v_mov_b32_e32 v126, v2
	v_mov_b32_e32 v127, v2
	v_mov_b32_e32 v128, v2
	v_mov_b32_e32 v129, v2
	s_andn2_b64 vcc, exec, s[6:7]
	s_cbranch_vccnz .LBB0_619
	s_branch .LBB0_620

.LBB0_720:
	s_add_u32 s4, s10, s34
	s_addc_u32 s5, s11, s35
	s_add_u32 s4, s4, 0x100
	s_addc_u32 s5, s5, 0
	s_add_u32 s74, s17, s34
	s_addc_u32 s75, vcc_lo, s35
	s_add_i32 s76, 0, 0x10000
	s_cmpk_eq_i32 s34, 0x700
	s_cselect_b32 s37, s27, s5
	s_cselect_b32 s36, vcc_hi, s4
	v_add_u32_e32 v147, s76, v131
	s_cselect_b32 s5, s25, s75
	s_cselect_b32 s4, s72, s74
	s_add_i32 s77, 0, 0x14000
	ds_read_b128 v[148:151], v147
	ds_read_b128 v[152:155], v147 offset:1024
	ds_read_b128 v[156:159], v147 offset:2048
	ds_read_b128 v[160:163], v147 offset:3072
	v_add_u32_e32 v147, s77, v131
	ds_read_b128 v[164:167], v147
	ds_read_b128 v[168:171], v147 offset:1024
	ds_read_b128 v[172:175], v147 offset:2048
	ds_read_b128 v[176:179], v147 offset:3072
	v_lshl_add_u64 v[208:209], v[144:145], 0, s[34:35]
	s_add_i32 m0, s23, 0xc000
	ds_read_b128 v[180:183], v146
	ds_read_b128 v[184:187], v146 offset:1024
	ds_read_b128 v[188:191], v146 offset:2048
	ds_read_b128 v[192:195], v146 offset:3072
	ds_read_b128 v[196:199], v146 offset:4096
	ds_read_b128 v[200:203], v146 offset:5120
	ds_read_b128 v[204:207], v146 offset:6144
	ds_read_b128 v[218:221], v146 offset:7168
	global_load_lds_dwordx4 v[208:209], off
	v_lshl_add_u64 v[208:209], v[142:143], 0, s[34:35]
	s_add_i32 m0, s23, 0xe000
	s_nop 0
	global_load_lds_dwordx4 v[208:209], off
	s_waitcnt vmcnt(8)
	s_waitcnt lgkmcnt(0)
	s_barrier
	s_setprio 1
	s_waitcnt lgkmcnt(0)
	v_mfma_f32_16x16x32_bf16 v[126:129], v[148:151], v[180:183], v[126:129]
	v_mfma_f32_16x16x32_bf16 v[122:125], v[156:159], v[180:183], v[122:125]
	v_mfma_f32_16x16x32_bf16 v[118:121], v[148:151], v[188:191], v[118:121]
	v_mfma_f32_16x16x32_bf16 v[110:113], v[156:159], v[188:191], v[110:113]
	v_mfma_f32_16x16x32_bf16 v[102:105], v[148:151], v[196:199], v[102:105]
	v_mfma_f32_16x16x32_bf16 v[94:97], v[156:159], v[196:199], v[94:97]
	v_mfma_f32_16x16x32_bf16 v[86:89], v[148:151], v[204:207], v[86:89]
	v_mfma_f32_16x16x32_bf16 v[78:81], v[156:159], v[204:207], v[78:81]
	v_mfma_f32_16x16x32_bf16 v[126:129], v[152:155], v[184:187], v[126:129]
	v_mfma_f32_16x16x32_bf16 v[122:125], v[160:163], v[184:187], v[122:125]
	v_mfma_f32_16x16x32_bf16 v[118:121], v[152:155], v[192:195], v[118:121]
	v_mfma_f32_16x16x32_bf16 v[110:113], v[160:163], v[192:195], v[110:113]
	v_mfma_f32_16x16x32_bf16 v[102:105], v[152:155], v[200:203], v[102:105]
	v_mfma_f32_16x16x32_bf16 v[94:97], v[160:163], v[200:203], v[94:97]
	v_mfma_f32_16x16x32_bf16 v[86:89], v[152:155], v[218:221], v[86:89]
	v_mfma_f32_16x16x32_bf16 v[78:81], v[160:163], v[218:221], v[78:81]
	v_mfma_f32_16x16x32_bf16 v[114:117], v[164:167], v[180:183], v[114:117]
	v_mfma_f32_16x16x32_bf16 v[106:109], v[172:175], v[180:183], v[106:109]
	v_mfma_f32_16x16x32_bf16 v[98:101], v[164:167], v[188:191], v[98:101]
	v_mfma_f32_16x16x32_bf16 v[90:93], v[172:175], v[188:191], v[90:93]
	v_mfma_f32_16x16x32_bf16 v[82:85], v[164:167], v[196:199], v[82:85]
	v_mfma_f32_16x16x32_bf16 v[74:77], v[172:175], v[196:199], v[74:77]
	v_mfma_f32_16x16x32_bf16 v[70:73], v[164:167], v[204:207], v[70:73]
	v_mfma_f32_16x16x32_bf16 v[66:69], v[172:175], v[204:207], v[66:69]
	v_mfma_f32_16x16x32_bf16 v[114:117], v[168:171], v[184:187], v[114:117]
	v_mfma_f32_16x16x32_bf16 v[106:109], v[176:179], v[184:187], v[106:109]
	v_mfma_f32_16x16x32_bf16 v[98:101], v[168:171], v[192:195], v[98:101]
	v_mfma_f32_16x16x32_bf16 v[90:93], v[176:179], v[192:195], v[90:93]
	v_mfma_f32_16x16x32_bf16 v[82:85], v[168:171], v[200:203], v[82:85]
	v_mfma_f32_16x16x32_bf16 v[74:77], v[176:179], v[200:203], v[74:77]
	v_mfma_f32_16x16x32_bf16 v[70:73], v[168:171], v[218:221], v[70:73]
	v_mfma_f32_16x16x32_bf16 v[66:69], v[176:179], v[218:221], v[66:69]
	s_setprio 0
	s_barrier
	s_add_i32 s74, s76, s22
	v_lshl_add_u64 v[208:209], s[4:5], 0, v[0:1]
	s_mov_b32 m0, s74
	ds_read_b128 v[180:183], v146 offset:16384
	ds_read_b128 v[184:187], v146 offset:17408
	ds_read_b128 v[188:191], v146 offset:18432
	ds_read_b128 v[192:195], v146 offset:19456
	ds_read_b128 v[196:199], v146 offset:20480
	ds_read_b128 v[200:203], v146 offset:21504
	ds_read_b128 v[204:207], v146 offset:22528
	ds_read_b128 v[218:221], v146 offset:23552
	global_load_lds_dwordx4 v[208:209], off
	s_add_i32 m0, s74, 0x2000
	s_add_u32 s74, s4, 0x40000
	v_lshl_add_u64 v[214:215], s[4:5], 0, v[132:133]
	s_addc_u32 s75, s5, 0
	s_add_i32 s76, s77, s22
	global_load_lds_dwordx4 v[214:215], off
	v_lshl_add_u64 v[230:231], s[74:75], 0, v[0:1]
	s_mov_b32 m0, s76
	v_lshl_add_u64 v[232:233], s[36:37], 0, v[134:135]
	global_load_lds_dwordx4 v[230:231], off
	v_lshl_add_u64 v[230:231], s[74:75], 0, v[132:133]
	s_add_i32 m0, s76, 0x2000
	s_nop 0
	global_load_lds_dwordx4 v[230:231], off
	v_lshl_add_u64 v[230:231], s[36:37], 0, v[136:137]
	s_mov_b32 m0, s23
	s_nop 0
	global_load_lds_dwordx4 v[230:231], off
	s_mov_b32 m0, s39
	s_nop 0
	global_load_lds_dwordx4 v[232:233], off
	s_waitcnt vmcnt(8)
	s_waitcnt lgkmcnt(0)
	s_barrier
	s_setprio 1
	s_waitcnt lgkmcnt(0)
	v_mfma_f32_16x16x32_bf16 v[62:65], v[148:151], v[180:183], v[62:65]
	v_mfma_f32_16x16x32_bf16 v[58:61], v[156:159], v[180:183], v[58:61]
	v_mfma_f32_16x16x32_bf16 v[46:49], v[148:151], v[188:191], v[46:49]
	v_mfma_f32_16x16x32_bf16 v[42:45], v[156:159], v[188:191], v[42:45]
	v_mfma_f32_16x16x32_bf16 v[30:33], v[148:151], v[196:199], v[30:33]
	v_mfma_f32_16x16x32_bf16 v[26:29], v[156:159], v[196:199], v[26:29]
	v_mfma_f32_16x16x32_bf16 v[14:17], v[148:151], v[204:207], v[14:17]
	v_mfma_f32_16x16x32_bf16 v[10:13], v[156:159], v[204:207], v[10:13]
	v_mfma_f32_16x16x32_bf16 v[62:65], v[152:155], v[184:187], v[62:65]
	v_mfma_f32_16x16x32_bf16 v[58:61], v[160:163], v[184:187], v[58:61]
	v_mfma_f32_16x16x32_bf16 v[46:49], v[152:155], v[192:195], v[46:49]
	v_mfma_f32_16x16x32_bf16 v[42:45], v[160:163], v[192:195], v[42:45]
	v_mfma_f32_16x16x32_bf16 v[30:33], v[152:155], v[200:203], v[30:33]
	v_mfma_f32_16x16x32_bf16 v[26:29], v[160:163], v[200:203], v[26:29]
	v_mfma_f32_16x16x32_bf16 v[14:17], v[152:155], v[218:221], v[14:17]
	v_mfma_f32_16x16x32_bf16 v[10:13], v[160:163], v[218:221], v[10:13]
	v_mfma_f32_16x16x32_bf16 v[54:57], v[164:167], v[180:183], v[54:57]
	v_mfma_f32_16x16x32_bf16 v[50:53], v[172:175], v[180:183], v[50:53]
	v_mfma_f32_16x16x32_bf16 v[38:41], v[164:167], v[188:191], v[38:41]
	v_mfma_f32_16x16x32_bf16 v[34:37], v[172:175], v[188:191], v[34:37]
	v_mfma_f32_16x16x32_bf16 v[22:25], v[164:167], v[196:199], v[22:25]
	v_mfma_f32_16x16x32_bf16 v[18:21], v[172:175], v[196:199], v[18:21]
	v_mfma_f32_16x16x32_bf16 v[6:9], v[164:167], v[204:207], v[6:9]
	v_mfma_f32_16x16x32_bf16 v[2:5], v[172:175], v[204:207], v[2:5]
	v_mfma_f32_16x16x32_bf16 v[54:57], v[168:171], v[184:187], v[54:57]
	v_mfma_f32_16x16x32_bf16 v[50:53], v[176:179], v[184:187], v[50:53]
	v_mfma_f32_16x16x32_bf16 v[38:41], v[168:171], v[192:195], v[38:41]
	v_mfma_f32_16x16x32_bf16 v[34:37], v[176:179], v[192:195], v[34:37]
	v_mfma_f32_16x16x32_bf16 v[22:25], v[168:171], v[200:203], v[22:25]
	v_mfma_f32_16x16x32_bf16 v[18:21], v[176:179], v[200:203], v[18:21]
	v_mfma_f32_16x16x32_bf16 v[6:9], v[168:171], v[218:221], v[6:9]
	v_mfma_f32_16x16x32_bf16 v[2:5], v[176:179], v[218:221], v[2:5]
	s_setprio 0
	s_barrier
	s_add_i32 s74, 0, 0x18000
	v_add_u32_e32 v147, s74, v131
	s_add_i32 s75, 0, 0x1c000
	ds_read_b128 v[148:151], v147
	ds_read_b128 v[152:155], v147 offset:1024
	ds_read_b128 v[156:159], v147 offset:2048
	ds_read_b128 v[160:163], v147 offset:3072
	v_add_u32_e32 v147, s75, v131
	ds_read_b128 v[164:167], v147
	ds_read_b128 v[168:171], v147 offset:1024
	ds_read_b128 v[172:175], v147 offset:2048
	ds_read_b128 v[176:179], v147 offset:3072
	s_add_u32 s36, s36, 0x40000
	s_addc_u32 s37, s37, 0
	s_mov_b32 m0, s38
	v_lshl_add_u64 v[234:235], s[36:37], 0, v[136:137]
	ds_read_b128 v[180:183], v146 offset:32768
	ds_read_b128 v[184:187], v146 offset:33792
	ds_read_b128 v[188:191], v146 offset:34816
	ds_read_b128 v[192:195], v146 offset:35840
	ds_read_b128 v[196:199], v146 offset:36864
	ds_read_b128 v[200:203], v146 offset:37888
	ds_read_b128 v[204:207], v146 offset:38912
	ds_read_b128 v[218:221], v146 offset:39936
	global_load_lds_dwordx4 v[234:235], off
	v_lshl_add_u64 v[234:235], s[36:37], 0, v[134:135]
	s_mov_b32 m0, s14
	s_nop 0
	global_load_lds_dwordx4 v[234:235], off
	s_waitcnt vmcnt(8)
	s_waitcnt lgkmcnt(0)
	s_barrier
	s_setprio 1
	s_waitcnt lgkmcnt(0)
	v_mfma_f32_16x16x32_bf16 v[126:129], v[148:151], v[180:183], v[126:129]
	v_mfma_f32_16x16x32_bf16 v[122:125], v[156:159], v[180:183], v[122:125]
	v_mfma_f32_16x16x32_bf16 v[118:121], v[148:151], v[188:191], v[118:121]
	v_mfma_f32_16x16x32_bf16 v[110:113], v[156:159], v[188:191], v[110:113]
	v_mfma_f32_16x16x32_bf16 v[102:105], v[148:151], v[196:199], v[102:105]
	v_mfma_f32_16x16x32_bf16 v[94:97], v[156:159], v[196:199], v[94:97]
	v_mfma_f32_16x16x32_bf16 v[86:89], v[148:151], v[204:207], v[86:89]
	v_mfma_f32_16x16x32_bf16 v[78:81], v[156:159], v[204:207], v[78:81]
	v_mfma_f32_16x16x32_bf16 v[126:129], v[152:155], v[184:187], v[126:129]
	v_mfma_f32_16x16x32_bf16 v[122:125], v[160:163], v[184:187], v[122:125]
	v_mfma_f32_16x16x32_bf16 v[118:121], v[152:155], v[192:195], v[118:121]
	v_mfma_f32_16x16x32_bf16 v[110:113], v[160:163], v[192:195], v[110:113]
	v_mfma_f32_16x16x32_bf16 v[102:105], v[152:155], v[200:203], v[102:105]
	v_mfma_f32_16x16x32_bf16 v[94:97], v[160:163], v[200:203], v[94:97]
	v_mfma_f32_16x16x32_bf16 v[86:89], v[152:155], v[218:221], v[86:89]
	v_mfma_f32_16x16x32_bf16 v[78:81], v[160:163], v[218:221], v[78:81]
	v_mfma_f32_16x16x32_bf16 v[114:117], v[164:167], v[180:183], v[114:117]
	v_mfma_f32_16x16x32_bf16 v[106:109], v[172:175], v[180:183], v[106:109]
	v_mfma_f32_16x16x32_bf16 v[98:101], v[164:167], v[188:191], v[98:101]
	v_mfma_f32_16x16x32_bf16 v[90:93], v[172:175], v[188:191], v[90:93]
	v_mfma_f32_16x16x32_bf16 v[82:85], v[164:167], v[196:199], v[82:85]
	v_mfma_f32_16x16x32_bf16 v[74:77], v[172:175], v[196:199], v[74:77]
	v_mfma_f32_16x16x32_bf16 v[70:73], v[164:167], v[204:207], v[70:73]
	v_mfma_f32_16x16x32_bf16 v[66:69], v[172:175], v[204:207], v[66:69]
	v_mfma_f32_16x16x32_bf16 v[114:117], v[168:171], v[184:187], v[114:117]
	v_mfma_f32_16x16x32_bf16 v[106:109], v[176:179], v[184:187], v[106:109]
	v_mfma_f32_16x16x32_bf16 v[98:101], v[168:171], v[192:195], v[98:101]
	v_mfma_f32_16x16x32_bf16 v[90:93], v[176:179], v[192:195], v[90:93]
	v_mfma_f32_16x16x32_bf16 v[82:85], v[168:171], v[200:203], v[82:85]
	v_mfma_f32_16x16x32_bf16 v[74:77], v[176:179], v[200:203], v[74:77]
	v_mfma_f32_16x16x32_bf16 v[70:73], v[168:171], v[218:221], v[70:73]
	v_mfma_f32_16x16x32_bf16 v[66:69], v[176:179], v[218:221], v[66:69]
	s_setprio 0
	s_barrier
	s_add_i32 s36, s74, s22
	v_lshl_add_u64 v[208:209], v[208:209], 0, s[50:51]
	s_mov_b32 m0, s36
	ds_read_b128 v[180:183], v146 offset:49152
	ds_read_b128 v[184:187], v146 offset:50176
	ds_read_b128 v[188:191], v146 offset:51200
	ds_read_b128 v[192:195], v146 offset:52224
	ds_read_b128 v[196:199], v146 offset:53248
	ds_read_b128 v[200:203], v146 offset:54272
	ds_read_b128 v[204:207], v146 offset:55296
	ds_read_b128 v[218:221], v146 offset:56320
	global_load_lds_dwordx4 v[208:209], off
	s_add_i32 m0, s36, 0x2000
	s_add_u32 s4, s4, 0x40080
	v_lshl_add_u64 v[208:209], v[214:215], 0, s[50:51]
	s_addc_u32 s5, s5, 0
	s_add_i32 s36, s75, s22
	global_load_lds_dwordx4 v[208:209], off
	v_lshl_add_u64 v[208:209], s[4:5], 0, v[0:1]
	s_mov_b32 m0, s36
	s_nop 0
	global_load_lds_dwordx4 v[208:209], off
	v_lshl_add_u64 v[208:209], s[4:5], 0, v[132:133]
	s_add_i32 m0, s36, 0x2000
	s_nop 0
	global_load_lds_dwordx4 v[208:209], off
	v_lshl_add_u64 v[208:209], v[230:231], 0, s[50:51]
	s_mov_b32 m0, s15
	s_nop 0
	global_load_lds_dwordx4 v[208:209], off
	v_lshl_add_u64 v[208:209], v[232:233], 0, s[50:51]
	s_mov_b32 m0, s71
	s_nop 0
	global_load_lds_dwordx4 v[208:209], off
	s_waitcnt vmcnt(8)
	s_waitcnt lgkmcnt(0)
	s_barrier
	s_setprio 1
	s_waitcnt lgkmcnt(0)
	v_mfma_f32_16x16x32_bf16 v[62:65], v[148:151], v[180:183], v[62:65]
	v_mfma_f32_16x16x32_bf16 v[58:61], v[156:159], v[180:183], v[58:61]
	v_mfma_f32_16x16x32_bf16 v[46:49], v[148:151], v[188:191], v[46:49]
	v_mfma_f32_16x16x32_bf16 v[42:45], v[156:159], v[188:191], v[42:45]
	v_mfma_f32_16x16x32_bf16 v[30:33], v[148:151], v[196:199], v[30:33]
	v_mfma_f32_16x16x32_bf16 v[26:29], v[156:159], v[196:199], v[26:29]
	v_mfma_f32_16x16x32_bf16 v[14:17], v[148:151], v[204:207], v[14:17]
	v_mfma_f32_16x16x32_bf16 v[10:13], v[156:159], v[204:207], v[10:13]
	v_mfma_f32_16x16x32_bf16 v[62:65], v[152:155], v[184:187], v[62:65]
	v_mfma_f32_16x16x32_bf16 v[58:61], v[160:163], v[184:187], v[58:61]
	v_mfma_f32_16x16x32_bf16 v[46:49], v[152:155], v[192:195], v[46:49]
	v_mfma_f32_16x16x32_bf16 v[42:45], v[160:163], v[192:195], v[42:45]
	v_mfma_f32_16x16x32_bf16 v[30:33], v[152:155], v[200:203], v[30:33]
	v_mfma_f32_16x16x32_bf16 v[26:29], v[160:163], v[200:203], v[26:29]
	v_mfma_f32_16x16x32_bf16 v[14:17], v[152:155], v[218:221], v[14:17]
	v_mfma_f32_16x16x32_bf16 v[10:13], v[160:163], v[218:221], v[10:13]
	v_mfma_f32_16x16x32_bf16 v[54:57], v[164:167], v[180:183], v[54:57]
	v_mfma_f32_16x16x32_bf16 v[50:53], v[172:175], v[180:183], v[50:53]
	v_mfma_f32_16x16x32_bf16 v[38:41], v[164:167], v[188:191], v[38:41]
	v_mfma_f32_16x16x32_bf16 v[34:37], v[172:175], v[188:191], v[34:37]
	v_mfma_f32_16x16x32_bf16 v[22:25], v[164:167], v[196:199], v[22:25]
	v_mfma_f32_16x16x32_bf16 v[18:21], v[172:175], v[196:199], v[18:21]
	v_mfma_f32_16x16x32_bf16 v[6:9], v[164:167], v[204:207], v[6:9]
	v_mfma_f32_16x16x32_bf16 v[2:5], v[172:175], v[204:207], v[2:5]
	v_mfma_f32_16x16x32_bf16 v[54:57], v[168:171], v[184:187], v[54:57]
	v_mfma_f32_16x16x32_bf16 v[50:53], v[176:179], v[184:187], v[50:53]
	v_mfma_f32_16x16x32_bf16 v[38:41], v[168:171], v[192:195], v[38:41]
	v_mfma_f32_16x16x32_bf16 v[34:37], v[176:179], v[192:195], v[34:37]
	v_mfma_f32_16x16x32_bf16 v[22:25], v[168:171], v[200:203], v[22:25]
	v_mfma_f32_16x16x32_bf16 v[18:21], v[176:179], v[200:203], v[18:21]
	v_mfma_f32_16x16x32_bf16 v[6:9], v[168:171], v[218:221], v[6:9]
	v_mfma_f32_16x16x32_bf16 v[2:5], v[176:179], v[218:221], v[2:5]
	s_setprio 0
	s_barrier
	s_add_i32 s73, s73, 2
	s_add_u32 s34, s34, 0x100
	s_addc_u32 s35, s35, 0
	s_cmp_gt_u32 s73, 13
	s_cbranch_scc0 .LBB0_720
	s_add_u32 s4, s17, 0xffffff00
	s_addc_u32 s5, vcc_lo, -1
	s_andn2_b64 vcc, exec, s[8:9]
	s_cbranch_vccnz .LBB0_723
	v_mov_b32_e32 v2, 0
	s_mov_b32 s18, s24
	s_mov_b32 s20, s26
	s_mov_b64 s[10:11], s[30:31]
	s_mov_b32 s16, s21
	v_mov_b32_e32 v3, v2
	v_mov_b32_e32 v4, v2
	v_mov_b32_e32 v5, v2
	v_mov_b32_e32 v6, v2
	v_mov_b32_e32 v7, v2
	v_mov_b32_e32 v8, v2
	v_mov_b32_e32 v9, v2
	v_mov_b32_e32 v18, v2
	v_mov_b32_e32 v19, v2
	v_mov_b32_e32 v20, v2
	v_mov_b32_e32 v21, v2
	v_mov_b32_e32 v22, v2
	v_mov_b32_e32 v23, v2
	v_mov_b32_e32 v24, v2
	v_mov_b32_e32 v25, v2
	v_mov_b32_e32 v34, v2
	v_mov_b32_e32 v35, v2
	v_mov_b32_e32 v36, v2
	v_mov_b32_e32 v37, v2
	v_mov_b32_e32 v38, v2
	v_mov_b32_e32 v39, v2
	v_mov_b32_e32 v40, v2
	v_mov_b32_e32 v41, v2
	v_mov_b32_e32 v50, v2
	v_mov_b32_e32 v51, v2
	v_mov_b32_e32 v52, v2
	v_mov_b32_e32 v53, v2
	v_mov_b32_e32 v54, v2
	v_mov_b32_e32 v55, v2
	v_mov_b32_e32 v56, v2
	v_mov_b32_e32 v57, v2
	v_mov_b32_e32 v10, v2
	v_mov_b32_e32 v11, v2
	v_mov_b32_e32 v12, v2
	v_mov_b32_e32 v13, v2
	v_mov_b32_e32 v14, v2
	v_mov_b32_e32 v15, v2
	v_mov_b32_e32 v16, v2
	v_mov_b32_e32 v17, v2
	v_mov_b32_e32 v26, v2
	v_mov_b32_e32 v27, v2
	v_mov_b32_e32 v28, v2
	v_mov_b32_e32 v29, v2
	v_mov_b32_e32 v30, v2
	v_mov_b32_e32 v31, v2
	v_mov_b32_e32 v32, v2
	v_mov_b32_e32 v33, v2
	v_mov_b32_e32 v42, v2
	v_mov_b32_e32 v43, v2
	v_mov_b32_e32 v44, v2
	v_mov_b32_e32 v45, v2
	v_mov_b32_e32 v46, v2
	v_mov_b32_e32 v47, v2
	v_mov_b32_e32 v48, v2
	v_mov_b32_e32 v49, v2
	v_mov_b32_e32 v58, v2
	v_mov_b32_e32 v59, v2
	v_mov_b32_e32 v60, v2
	v_mov_b32_e32 v61, v2
	v_mov_b32_e32 v62, v2
	v_mov_b32_e32 v63, v2
	v_mov_b32_e32 v64, v2
	v_mov_b32_e32 v65, v2
	v_mov_b32_e32 v66, v2
	v_mov_b32_e32 v67, v2
	v_mov_b32_e32 v68, v2
	v_mov_b32_e32 v69, v2
	v_mov_b32_e32 v70, v2
	v_mov_b32_e32 v71, v2
	v_mov_b32_e32 v72, v2
	v_mov_b32_e32 v73, v2
	v_mov_b32_e32 v74, v2
	v_mov_b32_e32 v75, v2
	v_mov_b32_e32 v76, v2
	v_mov_b32_e32 v77, v2
	v_mov_b32_e32 v82, v2
	v_mov_b32_e32 v83, v2
	v_mov_b32_e32 v84, v2
	v_mov_b32_e32 v85, v2
	v_mov_b32_e32 v90, v2
	v_mov_b32_e32 v91, v2
	v_mov_b32_e32 v92, v2
	v_mov_b32_e32 v93, v2
	v_mov_b32_e32 v98, v2
	v_mov_b32_e32 v99, v2
	v_mov_b32_e32 v100, v2
	v_mov_b32_e32 v101, v2
	v_mov_b32_e32 v106, v2
	v_mov_b32_e32 v107, v2
	v_mov_b32_e32 v108, v2
	v_mov_b32_e32 v109, v2
	v_mov_b32_e32 v114, v2
	v_mov_b32_e32 v115, v2
	v_mov_b32_e32 v116, v2
	v_mov_b32_e32 v117, v2
	v_mov_b32_e32 v78, v2
	v_mov_b32_e32 v79, v2
	v_mov_b32_e32 v80, v2
	v_mov_b32_e32 v81, v2
	v_mov_b32_e32 v86, v2
	v_mov_b32_e32 v87, v2
	v_mov_b32_e32 v88, v2
	v_mov_b32_e32 v89, v2
	v_mov_b32_e32 v94, v2
	v_mov_b32_e32 v95, v2
	v_mov_b32_e32 v96, v2
	v_mov_b32_e32 v97, v2
	v_mov_b32_e32 v102, v2
	v_mov_b32_e32 v103, v2
	v_mov_b32_e32 v104, v2
	v_mov_b32_e32 v105, v2
	v_mov_b32_e32 v110, v2
	v_mov_b32_e32 v111, v2
	v_mov_b32_e32 v112, v2
	v_mov_b32_e32 v113, v2
	v_mov_b32_e32 v118, v2
	v_mov_b32_e32 v119, v2
	v_mov_b32_e32 v120, v2
	v_mov_b32_e32 v121, v2
	v_mov_b32_e32 v122, v2
	v_mov_b32_e32 v123, v2
	v_mov_b32_e32 v124, v2
	v_mov_b32_e32 v125, v2
	v_mov_b32_e32 v126, v2
	v_mov_b32_e32 v127, v2
	v_mov_b32_e32 v128, v2
	v_mov_b32_e32 v129, v2
	s_andn2_b64 vcc, exec, s[6:7]
	s_cbranch_vccnz .LBB0_724
	s_branch .LBB0_725

.LBB0_825:
	s_add_i32 s71, 0, 0x10000
	s_add_i32 s72, 0, 0x14000
	v_add_u32_e32 v214, s71, v133
	v_add_u32_e32 v215, s72, v133
	ds_read_b128 v[2:5], v214
	ds_read_b128 v[6:9], v214 offset:1024
	ds_read_b128 v[10:13], v214 offset:2048
	ds_read_b128 v[14:17], v214 offset:3072
	ds_read_b128 v[18:21], v215
	ds_read_b128 v[22:25], v215 offset:1024
	ds_read_b128 v[26:29], v215 offset:2048
	ds_read_b128 v[30:33], v215 offset:3072
	s_add_u32 s38, s26, 0x40080
	s_addc_u32 s39, s27, 0
	s_add_i32 s73, s7, 0xc000
	v_lshl_add_u64 v[66:67], s[38:39], 0, v[0:1]
	s_mov_b32 m0, s73
	s_add_i32 s15, s7, 0xe000
	ds_read_b128 v[34:37], v135
	ds_read_b128 v[38:41], v135 offset:1024
	ds_read_b128 v[42:45], v135 offset:2048
	ds_read_b128 v[46:49], v135 offset:3072
	ds_read_b128 v[50:53], v135 offset:4096
	ds_read_b128 v[54:57], v135 offset:5120
	ds_read_b128 v[58:61], v135 offset:6144
	ds_read_b128 v[62:65], v135 offset:7168
	global_load_lds_dwordx4 v[66:67], off
	v_lshl_add_u64 v[66:67], s[38:39], 0, v[130:131]
	s_mov_b32 m0, s15
	s_nop 0
	global_load_lds_dwordx4 v[66:67], off
	s_waitcnt vmcnt(8)
	s_waitcnt lgkmcnt(0)
	s_barrier
	s_setprio 1
	s_waitcnt lgkmcnt(0)
	v_mfma_f32_16x16x32_bf16 v[66:69], v[2:5], v[34:37], 0
	v_mfma_f32_16x16x32_bf16 v[70:73], v[10:13], v[34:37], 0
	v_mfma_f32_16x16x32_bf16 v[74:77], v[2:5], v[42:45], 0
	v_mfma_f32_16x16x32_bf16 v[78:81], v[10:13], v[42:45], 0
	v_mfma_f32_16x16x32_bf16 v[82:85], v[2:5], v[50:53], 0
	v_mfma_f32_16x16x32_bf16 v[86:89], v[10:13], v[50:53], 0
	v_mfma_f32_16x16x32_bf16 v[90:93], v[2:5], v[58:61], 0
	v_mfma_f32_16x16x32_bf16 v[94:97], v[10:13], v[58:61], 0
	v_mfma_f32_16x16x32_bf16 v[66:69], v[6:9], v[38:41], v[66:69]
	v_mfma_f32_16x16x32_bf16 v[70:73], v[14:17], v[38:41], v[70:73]
	v_mfma_f32_16x16x32_bf16 v[74:77], v[6:9], v[46:49], v[74:77]
	v_mfma_f32_16x16x32_bf16 v[78:81], v[14:17], v[46:49], v[78:81]
	v_mfma_f32_16x16x32_bf16 v[82:85], v[6:9], v[54:57], v[82:85]
	v_mfma_f32_16x16x32_bf16 v[86:89], v[14:17], v[54:57], v[86:89]
	v_mfma_f32_16x16x32_bf16 v[90:93], v[6:9], v[62:65], v[90:93]
	v_mfma_f32_16x16x32_bf16 v[94:97], v[14:17], v[62:65], v[94:97]
	v_mfma_f32_16x16x32_bf16 v[98:101], v[18:21], v[34:37], 0
	v_mfma_f32_16x16x32_bf16 v[34:37], v[26:29], v[34:37], 0
	v_mfma_f32_16x16x32_bf16 v[98:101], v[22:25], v[38:41], v[98:101]
	v_mfma_f32_16x16x32_bf16 v[34:37], v[30:33], v[38:41], v[34:37]
	v_mfma_f32_16x16x32_bf16 v[38:41], v[18:21], v[42:45], 0
	v_mfma_f32_16x16x32_bf16 v[42:45], v[26:29], v[42:45], 0
	v_mfma_f32_16x16x32_bf16 v[38:41], v[22:25], v[46:49], v[38:41]
	v_mfma_f32_16x16x32_bf16 v[42:45], v[30:33], v[46:49], v[42:45]
	v_mfma_f32_16x16x32_bf16 v[46:49], v[18:21], v[50:53], 0
	v_mfma_f32_16x16x32_bf16 v[50:53], v[26:29], v[50:53], 0
	v_mfma_f32_16x16x32_bf16 v[46:49], v[22:25], v[54:57], v[46:49]
	v_mfma_f32_16x16x32_bf16 v[50:53], v[30:33], v[54:57], v[50:53]
	v_mfma_f32_16x16x32_bf16 v[54:57], v[18:21], v[58:61], 0
	v_mfma_f32_16x16x32_bf16 v[58:61], v[26:29], v[58:61], 0
	v_mfma_f32_16x16x32_bf16 v[54:57], v[22:25], v[62:65], v[54:57]
	v_mfma_f32_16x16x32_bf16 v[58:61], v[30:33], v[62:65], v[58:61]
	s_setprio 0
	s_barrier
	s_add_i32 s71, s71, s6
	v_lshl_add_u64 v[200:201], s[24:25], 0, v[0:1]
	s_mov_b64 s[76:77], 0x100
	s_add_i32 s17, s71, 0x2000
	v_lshl_add_u64 v[136:137], v[200:201], 0, s[76:77]
	s_mov_b32 m0, s71
	v_lshl_add_u64 v[202:203], s[24:25], 0, v[130:131]
	s_add_u32 s74, s24, 0x40100
	ds_read_b128 v[62:65], v135 offset:16384
	ds_read_b128 v[102:105], v135 offset:17408
	ds_read_b128 v[106:109], v135 offset:18432
	ds_read_b128 v[110:113], v135 offset:19456
	ds_read_b128 v[114:117], v135 offset:20480
	ds_read_b128 v[118:121], v135 offset:21504
	ds_read_b128 v[122:125], v135 offset:22528
	ds_read_b128 v[126:129], v135 offset:23552
	global_load_lds_dwordx4 v[136:137], off
	v_lshl_add_u64 v[136:137], v[202:203], 0, s[76:77]
	s_mov_b32 m0, s17
	s_addc_u32 s75, s25, 0
	s_add_i32 s38, s72, s6
	global_load_lds_dwordx4 v[136:137], off
	v_lshl_add_u64 v[136:137], s[74:75], 0, v[0:1]
	s_mov_b32 m0, s38
	s_add_i32 s39, s38, 0x2000
	global_load_lds_dwordx4 v[136:137], off
	v_lshl_add_u64 v[136:137], s[74:75], 0, v[130:131]
	s_mov_b32 m0, s39
	v_lshl_add_u64 v[204:205], s[26:27], 0, v[0:1]
	global_load_lds_dwordx4 v[136:137], off
	v_lshl_add_u64 v[136:137], v[204:205], 0, s[76:77]
	s_mov_b32 m0, s7
	v_lshl_add_u64 v[206:207], s[26:27], 0, v[130:131]
	global_load_lds_dwordx4 v[136:137], off
	v_lshl_add_u64 v[136:137], v[206:207], 0, s[76:77]
	s_mov_b32 m0, s12
	s_nop 0
	global_load_lds_dwordx4 v[136:137], off
	s_waitcnt vmcnt(8)
	s_waitcnt lgkmcnt(0)
	s_barrier
	s_setprio 1
	s_waitcnt lgkmcnt(0)
	v_mfma_f32_16x16x32_bf16 v[136:139], v[2:5], v[62:65], 0
	v_mfma_f32_16x16x32_bf16 v[144:147], v[2:5], v[106:109], 0
	v_mfma_f32_16x16x32_bf16 v[152:155], v[2:5], v[114:117], 0
	v_mfma_f32_16x16x32_bf16 v[2:5], v[2:5], v[122:125], 0
	v_mfma_f32_16x16x32_bf16 v[136:139], v[6:9], v[102:105], v[136:139]
	v_mfma_f32_16x16x32_bf16 v[144:147], v[6:9], v[110:113], v[144:147]
	v_mfma_f32_16x16x32_bf16 v[152:155], v[6:9], v[118:121], v[152:155]
	v_mfma_f32_16x16x32_bf16 v[2:5], v[6:9], v[126:129], v[2:5]
	v_mfma_f32_16x16x32_bf16 v[6:9], v[10:13], v[122:125], 0
	v_mfma_f32_16x16x32_bf16 v[140:143], v[10:13], v[62:65], 0
	v_mfma_f32_16x16x32_bf16 v[148:151], v[10:13], v[106:109], 0
	v_mfma_f32_16x16x32_bf16 v[156:159], v[10:13], v[114:117], 0
	v_mfma_f32_16x16x32_bf16 v[6:9], v[14:17], v[126:129], v[6:9]
	v_mfma_f32_16x16x32_bf16 v[140:143], v[14:17], v[102:105], v[140:143]
	v_mfma_f32_16x16x32_bf16 v[148:151], v[14:17], v[110:113], v[148:151]
	v_mfma_f32_16x16x32_bf16 v[156:159], v[14:17], v[118:121], v[156:159]
	v_mfma_f32_16x16x32_bf16 v[10:13], v[18:21], v[62:65], 0
	v_mfma_f32_16x16x32_bf16 v[14:17], v[26:29], v[62:65], 0
	v_mfma_f32_16x16x32_bf16 v[10:13], v[22:25], v[102:105], v[10:13]
	v_mfma_f32_16x16x32_bf16 v[14:17], v[30:33], v[102:105], v[14:17]
	v_mfma_f32_16x16x32_bf16 v[62:65], v[18:21], v[106:109], 0
	v_mfma_f32_16x16x32_bf16 v[102:105], v[26:29], v[106:109], 0
	v_mfma_f32_16x16x32_bf16 v[106:109], v[18:21], v[114:117], 0
	v_mfma_f32_16x16x32_bf16 v[18:21], v[18:21], v[122:125], 0
	v_mfma_f32_16x16x32_bf16 v[62:65], v[22:25], v[110:113], v[62:65]
	v_mfma_f32_16x16x32_bf16 v[102:105], v[30:33], v[110:113], v[102:105]
	v_mfma_f32_16x16x32_bf16 v[106:109], v[22:25], v[118:121], v[106:109]
	v_mfma_f32_16x16x32_bf16 v[110:113], v[26:29], v[114:117], 0
	v_mfma_f32_16x16x32_bf16 v[18:21], v[22:25], v[126:129], v[18:21]
	v_mfma_f32_16x16x32_bf16 v[22:25], v[26:29], v[122:125], 0
	v_mfma_f32_16x16x32_bf16 v[110:113], v[30:33], v[118:121], v[110:113]
	v_mfma_f32_16x16x32_bf16 v[22:25], v[30:33], v[126:129], v[22:25]
	s_setprio 0
	s_barrier
	s_add_i32 s72, 0, 0x18000
	s_add_i32 s76, 0, 0x1c000
	v_add_u32_e32 v218, s72, v133
	v_add_u32_e32 v230, s76, v133
	ds_read_b128 v[26:29], v218
	ds_read_b128 v[30:33], v218 offset:1024
	ds_read_b128 v[114:117], v218 offset:2048
	ds_read_b128 v[118:121], v218 offset:3072
	ds_read_b128 v[122:125], v230
	ds_read_b128 v[126:129], v230 offset:1024
	ds_read_b128 v[160:163], v230 offset:2048
	ds_read_b128 v[164:167], v230 offset:3072
	s_add_u32 s74, s26, 0x40100
	s_addc_u32 s75, s27, 0
	s_mov_b32 m0, s28
	v_lshl_add_u64 v[208:209], s[74:75], 0, v[0:1]
	ds_read_b128 v[168:171], v135 offset:32768
	ds_read_b128 v[172:175], v135 offset:33792
	ds_read_b128 v[176:179], v135 offset:34816
	ds_read_b128 v[180:183], v135 offset:35840
	ds_read_b128 v[184:187], v135 offset:36864
	ds_read_b128 v[188:191], v135 offset:37888
	ds_read_b128 v[192:195], v135 offset:38912
	ds_read_b128 v[196:199], v135 offset:39936
	global_load_lds_dwordx4 v[208:209], off
	v_lshl_add_u64 v[208:209], s[74:75], 0, v[130:131]
	s_mov_b32 m0, s29
	s_nop 0
	global_load_lds_dwordx4 v[208:209], off
	s_waitcnt vmcnt(8)
	s_waitcnt lgkmcnt(0)
	s_barrier
	s_setprio 1
	s_waitcnt lgkmcnt(0)
	v_mfma_f32_16x16x32_bf16 v[66:69], v[26:29], v[168:171], v[66:69]
	v_mfma_f32_16x16x32_bf16 v[70:73], v[114:117], v[168:171], v[70:73]
	v_mfma_f32_16x16x32_bf16 v[74:77], v[26:29], v[176:179], v[74:77]
	v_mfma_f32_16x16x32_bf16 v[78:81], v[114:117], v[176:179], v[78:81]
	v_mfma_f32_16x16x32_bf16 v[82:85], v[26:29], v[184:187], v[82:85]
	v_mfma_f32_16x16x32_bf16 v[86:89], v[114:117], v[184:187], v[86:89]
	v_mfma_f32_16x16x32_bf16 v[90:93], v[26:29], v[192:195], v[90:93]
	v_mfma_f32_16x16x32_bf16 v[94:97], v[114:117], v[192:195], v[94:97]
	v_mfma_f32_16x16x32_bf16 v[66:69], v[30:33], v[172:175], v[66:69]
	v_mfma_f32_16x16x32_bf16 v[70:73], v[118:121], v[172:175], v[70:73]
	v_mfma_f32_16x16x32_bf16 v[74:77], v[30:33], v[180:183], v[74:77]
	v_mfma_f32_16x16x32_bf16 v[78:81], v[118:121], v[180:183], v[78:81]
	v_mfma_f32_16x16x32_bf16 v[82:85], v[30:33], v[188:191], v[82:85]
	v_mfma_f32_16x16x32_bf16 v[86:89], v[118:121], v[188:191], v[86:89]
	v_mfma_f32_16x16x32_bf16 v[90:93], v[30:33], v[196:199], v[90:93]
	v_mfma_f32_16x16x32_bf16 v[94:97], v[118:121], v[196:199], v[94:97]
	v_mfma_f32_16x16x32_bf16 v[98:101], v[122:125], v[168:171], v[98:101]
	v_mfma_f32_16x16x32_bf16 v[34:37], v[160:163], v[168:171], v[34:37]
	v_mfma_f32_16x16x32_bf16 v[38:41], v[122:125], v[176:179], v[38:41]
	v_mfma_f32_16x16x32_bf16 v[42:45], v[160:163], v[176:179], v[42:45]
	v_mfma_f32_16x16x32_bf16 v[46:49], v[122:125], v[184:187], v[46:49]
	v_mfma_f32_16x16x32_bf16 v[50:53], v[160:163], v[184:187], v[50:53]
	v_mfma_f32_16x16x32_bf16 v[54:57], v[122:125], v[192:195], v[54:57]
	v_mfma_f32_16x16x32_bf16 v[58:61], v[160:163], v[192:195], v[58:61]
	v_mfma_f32_16x16x32_bf16 v[98:101], v[126:129], v[172:175], v[98:101]
	v_mfma_f32_16x16x32_bf16 v[34:37], v[164:167], v[172:175], v[34:37]
	v_mfma_f32_16x16x32_bf16 v[38:41], v[126:129], v[180:183], v[38:41]
	v_mfma_f32_16x16x32_bf16 v[42:45], v[164:167], v[180:183], v[42:45]
	v_mfma_f32_16x16x32_bf16 v[46:49], v[126:129], v[188:191], v[46:49]
	v_mfma_f32_16x16x32_bf16 v[50:53], v[164:167], v[188:191], v[50:53]
	v_mfma_f32_16x16x32_bf16 v[54:57], v[126:129], v[196:199], v[54:57]
	v_mfma_f32_16x16x32_bf16 v[58:61], v[164:167], v[196:199], v[58:61]
	s_setprio 0
	s_barrier
	s_add_i32 s74, s72, s6
	s_mov_b64 s[80:81], 0x180
	s_add_i32 s72, s74, 0x2000
	v_lshl_add_u64 v[200:201], v[200:201], 0, s[80:81]
	s_mov_b32 m0, s74
	s_add_u32 vcc_lo, s24, 0x40180
	ds_read_b128 v[168:171], v135 offset:49152
	ds_read_b128 v[172:175], v135 offset:50176
	ds_read_b128 v[176:179], v135 offset:51200
	ds_read_b128 v[180:183], v135 offset:52224
	ds_read_b128 v[184:187], v135 offset:53248
	ds_read_b128 v[188:191], v135 offset:54272
	ds_read_b128 v[192:195], v135 offset:55296
	ds_read_b128 v[196:199], v135 offset:56320
	global_load_lds_dwordx4 v[200:201], off
	v_lshl_add_u64 v[200:201], v[202:203], 0, s[80:81]
	s_mov_b32 m0, s72
	s_addc_u32 vcc_hi, s25, 0
	s_add_i32 s24, s76, s6
	global_load_lds_dwordx4 v[200:201], off
	v_lshl_add_u64 v[200:201], vcc, 0, v[0:1]
	s_mov_b32 m0, s24
	s_add_i32 s25, s24, 0x2000
	global_load_lds_dwordx4 v[200:201], off
	v_lshl_add_u64 v[200:201], vcc, 0, v[130:131]
	s_mov_b32 m0, s25
	s_nop 0
	global_load_lds_dwordx4 v[200:201], off
	v_lshl_add_u64 v[200:201], v[204:205], 0, s[80:81]
	s_mov_b32 m0, s30
	s_nop 0
	global_load_lds_dwordx4 v[200:201], off
	v_lshl_add_u64 v[200:201], v[206:207], 0, s[80:81]
	s_mov_b32 m0, s31
	s_nop 0
	global_load_lds_dwordx4 v[200:201], off
	s_waitcnt vmcnt(8)
	s_waitcnt lgkmcnt(0)
	s_barrier
	s_setprio 1
	s_waitcnt lgkmcnt(0)
	v_mfma_f32_16x16x32_bf16 v[2:5], v[26:29], v[192:195], v[2:5]
	v_mfma_f32_16x16x32_bf16 v[6:9], v[114:117], v[192:195], v[6:9]
	v_mfma_f32_16x16x32_bf16 v[136:139], v[26:29], v[168:171], v[136:139]
	v_mfma_f32_16x16x32_bf16 v[140:143], v[114:117], v[168:171], v[140:143]
	v_mfma_f32_16x16x32_bf16 v[144:147], v[26:29], v[176:179], v[144:147]
	v_mfma_f32_16x16x32_bf16 v[148:151], v[114:117], v[176:179], v[148:151]
	v_mfma_f32_16x16x32_bf16 v[152:155], v[26:29], v[184:187], v[152:155]
	v_mfma_f32_16x16x32_bf16 v[156:159], v[114:117], v[184:187], v[156:159]
	v_mfma_f32_16x16x32_bf16 v[2:5], v[30:33], v[196:199], v[2:5]
	v_mfma_f32_16x16x32_bf16 v[6:9], v[118:121], v[196:199], v[6:9]
	v_mfma_f32_16x16x32_bf16 v[136:139], v[30:33], v[172:175], v[136:139]
	v_mfma_f32_16x16x32_bf16 v[140:143], v[118:121], v[172:175], v[140:143]
	v_mfma_f32_16x16x32_bf16 v[144:147], v[30:33], v[180:183], v[144:147]
	v_mfma_f32_16x16x32_bf16 v[148:151], v[118:121], v[180:183], v[148:151]
	v_mfma_f32_16x16x32_bf16 v[152:155], v[30:33], v[188:191], v[152:155]
	v_mfma_f32_16x16x32_bf16 v[156:159], v[118:121], v[188:191], v[156:159]
	v_mfma_f32_16x16x32_bf16 v[10:13], v[122:125], v[168:171], v[10:13]
	v_mfma_f32_16x16x32_bf16 v[14:17], v[160:163], v[168:171], v[14:17]
	v_mfma_f32_16x16x32_bf16 v[26:29], v[122:125], v[176:179], v[62:65]
	v_mfma_f32_16x16x32_bf16 v[30:33], v[160:163], v[176:179], v[102:105]
	v_mfma_f32_16x16x32_bf16 v[62:65], v[122:125], v[184:187], v[106:109]
	v_mfma_f32_16x16x32_bf16 v[102:105], v[160:163], v[184:187], v[110:113]
	v_mfma_f32_16x16x32_bf16 v[18:21], v[122:125], v[192:195], v[18:21]
	v_mfma_f32_16x16x32_bf16 v[22:25], v[160:163], v[192:195], v[22:25]
	v_mfma_f32_16x16x32_bf16 v[10:13], v[126:129], v[172:175], v[10:13]
	v_mfma_f32_16x16x32_bf16 v[14:17], v[164:167], v[172:175], v[14:17]
	v_mfma_f32_16x16x32_bf16 v[26:29], v[126:129], v[180:183], v[26:29]
	v_mfma_f32_16x16x32_bf16 v[30:33], v[164:167], v[180:183], v[30:33]
	v_mfma_f32_16x16x32_bf16 v[62:65], v[126:129], v[188:191], v[62:65]
	v_mfma_f32_16x16x32_bf16 v[102:105], v[164:167], v[188:191], v[102:105]
	v_mfma_f32_16x16x32_bf16 v[18:21], v[126:129], v[196:199], v[18:21]
	v_mfma_f32_16x16x32_bf16 v[22:25], v[164:167], v[196:199], v[22:25]
	s_setprio 0
	s_barrier
	ds_read_b128 v[106:109], v214
	ds_read_b128 v[110:113], v214 offset:1024
	ds_read_b128 v[114:117], v214 offset:2048
	ds_read_b128 v[118:121], v214 offset:3072
	ds_read_b128 v[122:125], v215
	ds_read_b128 v[126:129], v215 offset:1024
	ds_read_b128 v[160:163], v215 offset:2048
	ds_read_b128 v[164:167], v215 offset:3072
	s_add_u32 s26, s26, 0x40180
	s_addc_u32 s27, s27, 0
	s_mov_b32 m0, s73
	v_lshl_add_u64 v[200:201], s[26:27], 0, v[0:1]
	ds_read_b128 v[168:171], v135
	ds_read_b128 v[172:175], v135 offset:1024
	ds_read_b128 v[176:179], v135 offset:2048
	ds_read_b128 v[180:183], v135 offset:3072
	ds_read_b128 v[184:187], v135 offset:4096
	ds_read_b128 v[188:191], v135 offset:5120
	ds_read_b128 v[192:195], v135 offset:6144
	ds_read_b128 v[196:199], v135 offset:7168
	global_load_lds_dwordx4 v[200:201], off
	v_lshl_add_u64 v[200:201], s[26:27], 0, v[130:131]
	s_mov_b32 m0, s15
	s_nop 0
	global_load_lds_dwordx4 v[200:201], off
	s_waitcnt vmcnt(8)
	s_waitcnt lgkmcnt(0)
	s_barrier
	s_setprio 1
	s_waitcnt lgkmcnt(0)
	v_mfma_f32_16x16x32_bf16 v[66:69], v[106:109], v[168:171], v[66:69]
	v_mfma_f32_16x16x32_bf16 v[70:73], v[114:117], v[168:171], v[70:73]
	v_mfma_f32_16x16x32_bf16 v[74:77], v[106:109], v[176:179], v[74:77]
	v_mfma_f32_16x16x32_bf16 v[78:81], v[114:117], v[176:179], v[78:81]
	v_mfma_f32_16x16x32_bf16 v[82:85], v[106:109], v[184:187], v[82:85]
	v_mfma_f32_16x16x32_bf16 v[86:89], v[114:117], v[184:187], v[86:89]
	v_mfma_f32_16x16x32_bf16 v[90:93], v[106:109], v[192:195], v[90:93]
	v_mfma_f32_16x16x32_bf16 v[94:97], v[114:117], v[192:195], v[94:97]
	v_mfma_f32_16x16x32_bf16 v[66:69], v[110:113], v[172:175], v[66:69]
	v_mfma_f32_16x16x32_bf16 v[70:73], v[118:121], v[172:175], v[70:73]
	v_mfma_f32_16x16x32_bf16 v[74:77], v[110:113], v[180:183], v[74:77]
	v_mfma_f32_16x16x32_bf16 v[78:81], v[118:121], v[180:183], v[78:81]
	v_mfma_f32_16x16x32_bf16 v[82:85], v[110:113], v[188:191], v[82:85]
	v_mfma_f32_16x16x32_bf16 v[86:89], v[118:121], v[188:191], v[86:89]
	v_mfma_f32_16x16x32_bf16 v[90:93], v[110:113], v[196:199], v[90:93]
	v_mfma_f32_16x16x32_bf16 v[94:97], v[118:121], v[196:199], v[94:97]
	v_mfma_f32_16x16x32_bf16 v[34:37], v[160:163], v[168:171], v[34:37]
	v_mfma_f32_16x16x32_bf16 v[98:101], v[122:125], v[168:171], v[98:101]
	v_mfma_f32_16x16x32_bf16 v[168:171], v[164:167], v[172:175], v[34:37]
	v_mfma_f32_16x16x32_bf16 v[34:37], v[122:125], v[176:179], v[38:41]
	v_mfma_f32_16x16x32_bf16 v[98:101], v[126:129], v[172:175], v[98:101]
	v_mfma_f32_16x16x32_bf16 v[172:175], v[126:129], v[180:183], v[34:37]
	v_mfma_f32_16x16x32_bf16 v[34:37], v[160:163], v[176:179], v[42:45]
	v_mfma_f32_16x16x32_bf16 v[42:45], v[164:167], v[180:183], v[34:37]
	v_mfma_f32_16x16x32_bf16 v[34:37], v[122:125], v[184:187], v[46:49]
	v_mfma_f32_16x16x32_bf16 v[46:49], v[126:129], v[188:191], v[34:37]
	v_mfma_f32_16x16x32_bf16 v[34:37], v[160:163], v[184:187], v[50:53]
	v_mfma_f32_16x16x32_bf16 v[50:53], v[164:167], v[188:191], v[34:37]
	v_mfma_f32_16x16x32_bf16 v[34:37], v[122:125], v[192:195], v[54:57]
	v_mfma_f32_16x16x32_bf16 v[54:57], v[126:129], v[196:199], v[34:37]
	v_mfma_f32_16x16x32_bf16 v[34:37], v[160:163], v[192:195], v[58:61]
	v_mfma_f32_16x16x32_bf16 v[176:179], v[164:167], v[196:199], v[34:37]
	s_setprio 0
	s_barrier
	s_mov_b32 m0, s71
	v_lshl_add_u64 v[208:209], s[20:21], 0, v[0:1]
	s_add_u32 s26, s20, 0x40000
	s_nop 1
	ds_read_b128 v[34:37], v135 offset:16384
	ds_read_b128 v[38:41], v135 offset:17408
	ds_read_b128 v[58:61], v135 offset:18432
	ds_read_b128 v[180:183], v135 offset:19456
	ds_read_b128 v[184:187], v135 offset:20480
	ds_read_b128 v[188:191], v135 offset:21504
	ds_read_b128 v[192:195], v135 offset:22528
	ds_read_b128 v[196:199], v135 offset:23552
	global_load_lds_dwordx4 v[208:209], off
	v_lshl_add_u64 v[246:247], s[20:21], 0, v[130:131]
	s_mov_b32 m0, s17
	s_addc_u32 s27, s21, 0
	global_load_lds_dwordx4 v[246:247], off
	v_lshl_add_u64 v[200:201], s[26:27], 0, v[0:1]
	s_mov_b32 m0, s38
	v_lshl_add_u64 v[228:229], s[18:19], 0, v[0:1]
	global_load_lds_dwordx4 v[200:201], off
	v_lshl_add_u64 v[200:201], s[26:27], 0, v[130:131]
	s_mov_b32 m0, s39
	v_lshl_add_u64 v[226:227], s[18:19], 0, v[130:131]
	global_load_lds_dwordx4 v[200:201], off
	s_mov_b32 m0, s7
	s_nop 0
	global_load_lds_dwordx4 v[228:229], off
	s_mov_b32 m0, s12
	s_nop 0
	global_load_lds_dwordx4 v[226:227], off
	s_waitcnt vmcnt(8)
	s_waitcnt lgkmcnt(0)
	s_barrier
	s_setprio 1
	s_waitcnt lgkmcnt(0)
	v_mfma_f32_16x16x32_bf16 v[136:139], v[106:109], v[34:37], v[136:139]
	v_mfma_f32_16x16x32_bf16 v[144:147], v[106:109], v[58:61], v[144:147]
	v_mfma_f32_16x16x32_bf16 v[152:155], v[106:109], v[184:187], v[152:155]
	v_mfma_f32_16x16x32_bf16 v[2:5], v[106:109], v[192:195], v[2:5]
	v_mfma_f32_16x16x32_bf16 v[136:139], v[110:113], v[38:41], v[136:139]
	v_mfma_f32_16x16x32_bf16 v[144:147], v[110:113], v[180:183], v[144:147]
	v_mfma_f32_16x16x32_bf16 v[152:155], v[110:113], v[188:191], v[152:155]
	v_mfma_f32_16x16x32_bf16 v[110:113], v[110:113], v[196:199], v[2:5]
	v_mfma_f32_16x16x32_bf16 v[2:5], v[114:117], v[192:195], v[6:9]
	v_mfma_f32_16x16x32_bf16 v[140:143], v[114:117], v[34:37], v[140:143]
	v_mfma_f32_16x16x32_bf16 v[148:151], v[114:117], v[58:61], v[148:151]
	v_mfma_f32_16x16x32_bf16 v[156:159], v[114:117], v[184:187], v[156:159]
	v_mfma_f32_16x16x32_bf16 v[114:117], v[118:121], v[196:199], v[2:5]
	v_mfma_f32_16x16x32_bf16 v[140:143], v[118:121], v[38:41], v[140:143]
	v_mfma_f32_16x16x32_bf16 v[148:151], v[118:121], v[180:183], v[148:151]
	v_mfma_f32_16x16x32_bf16 v[156:159], v[118:121], v[188:191], v[156:159]
	v_mfma_f32_16x16x32_bf16 v[2:5], v[122:125], v[34:37], v[10:13]
	v_mfma_f32_16x16x32_bf16 v[118:121], v[126:129], v[38:41], v[2:5]
	v_mfma_f32_16x16x32_bf16 v[2:5], v[160:163], v[34:37], v[14:17]
	v_mfma_f32_16x16x32_bf16 v[200:203], v[164:167], v[38:41], v[2:5]
	v_mfma_f32_16x16x32_bf16 v[2:5], v[122:125], v[58:61], v[26:29]
	v_mfma_f32_16x16x32_bf16 v[204:207], v[126:129], v[180:183], v[2:5]
	v_mfma_f32_16x16x32_bf16 v[2:5], v[160:163], v[58:61], v[30:33]
	v_mfma_f32_16x16x32_bf16 v[180:183], v[164:167], v[180:183], v[2:5]
	v_mfma_f32_16x16x32_bf16 v[2:5], v[122:125], v[184:187], v[62:65]
	v_mfma_f32_16x16x32_bf16 v[214:217], v[126:129], v[188:191], v[2:5]
	v_mfma_f32_16x16x32_bf16 v[2:5], v[160:163], v[184:187], v[102:105]
	v_mfma_f32_16x16x32_bf16 v[184:187], v[164:167], v[188:191], v[2:5]
	v_mfma_f32_16x16x32_bf16 v[2:5], v[122:125], v[192:195], v[18:21]
	v_mfma_f32_16x16x32_bf16 v[188:191], v[126:129], v[196:199], v[2:5]
	v_mfma_f32_16x16x32_bf16 v[2:5], v[160:163], v[192:195], v[22:25]
	v_mfma_f32_16x16x32_bf16 v[160:163], v[164:167], v[196:199], v[2:5]
	s_setprio 0
	s_barrier
	ds_read_b128 v[102:105], v218
	ds_read_b128 v[122:125], v218 offset:1024
	ds_read_b128 v[126:129], v218 offset:2048
	ds_read_b128 v[164:167], v218 offset:3072
	ds_read_b128 v[192:195], v230
	ds_read_b128 v[196:199], v230 offset:1024
	ds_read_b128 v[218:221], v230 offset:2048
	ds_read_b128 v[248:251], v230 offset:3072
	s_add_u32 s26, s18, 0x40000
	s_addc_u32 s27, s19, 0
	s_mov_b32 m0, s28
	v_lshl_add_u64 v[2:3], s[26:27], 0, v[0:1]
	ds_read_b128 v[26:29], v135 offset:32768
	ds_read_b128 v[30:33], v135 offset:33792
	ds_read_b128 v[62:65], v135 offset:34816
	ds_read_b128 v[106:109], v135 offset:35840
	ds_read_b128 v[230:233], v135 offset:36864
	ds_read_b128 v[234:237], v135 offset:37888
	ds_read_b128 v[238:241], v135 offset:38912
	ds_read_b128 v[242:245], v135 offset:39936
	global_load_lds_dwordx4 v[2:3], off
	v_lshl_add_u64 v[2:3], s[26:27], 0, v[130:131]
	s_mov_b32 m0, s29
	s_nop 0
	global_load_lds_dwordx4 v[2:3], off
	s_waitcnt vmcnt(8)
	s_waitcnt lgkmcnt(0)
	s_barrier
	s_setprio 1
	s_waitcnt lgkmcnt(0)
	v_mfma_f32_16x16x32_bf16 v[2:5], v[102:105], v[26:29], v[66:69]
	v_mfma_f32_16x16x32_bf16 v[34:37], v[122:125], v[30:33], v[2:5]
	v_mfma_f32_16x16x32_bf16 v[2:5], v[126:129], v[26:29], v[70:73]
	v_mfma_f32_16x16x32_bf16 v[38:41], v[164:167], v[30:33], v[2:5]
	v_mfma_f32_16x16x32_bf16 v[2:5], v[102:105], v[62:65], v[74:77]
	v_mfma_f32_16x16x32_bf16 v[18:21], v[122:125], v[106:109], v[2:5]
	v_mfma_f32_16x16x32_bf16 v[2:5], v[126:129], v[62:65], v[78:81]
	v_mfma_f32_16x16x32_bf16 v[22:25], v[164:167], v[106:109], v[2:5]
	v_mfma_f32_16x16x32_bf16 v[2:5], v[102:105], v[230:233], v[82:85]
	v_mfma_f32_16x16x32_bf16 v[10:13], v[122:125], v[234:237], v[2:5]
	v_mfma_f32_16x16x32_bf16 v[2:5], v[126:129], v[230:233], v[86:89]
	v_mfma_f32_16x16x32_bf16 v[14:17], v[164:167], v[234:237], v[2:5]
	v_mfma_f32_16x16x32_bf16 v[2:5], v[102:105], v[238:241], v[90:93]
	v_mfma_f32_16x16x32_bf16 v[6:9], v[126:129], v[238:241], v[94:97]
	v_mfma_f32_16x16x32_bf16 v[2:5], v[122:125], v[242:245], v[2:5]
	v_mfma_f32_16x16x32_bf16 v[6:9], v[164:167], v[242:245], v[6:9]
	v_mfma_f32_16x16x32_bf16 v[58:61], v[192:195], v[26:29], v[98:101]
	v_mfma_f32_16x16x32_bf16 v[26:29], v[218:221], v[26:29], v[168:171]
	v_mfma_f32_16x16x32_bf16 v[78:81], v[248:251], v[30:33], v[26:29]
	v_mfma_f32_16x16x32_bf16 v[26:29], v[192:195], v[62:65], v[172:175]
	v_mfma_f32_16x16x32_bf16 v[70:73], v[196:199], v[30:33], v[58:61]
	v_mfma_f32_16x16x32_bf16 v[58:61], v[196:199], v[106:109], v[26:29]
	v_mfma_f32_16x16x32_bf16 v[26:29], v[218:221], v[62:65], v[42:45]
	v_mfma_f32_16x16x32_bf16 v[62:65], v[248:251], v[106:109], v[26:29]
	v_mfma_f32_16x16x32_bf16 v[26:29], v[192:195], v[230:233], v[46:49]
	v_mfma_f32_16x16x32_bf16 v[42:45], v[196:199], v[234:237], v[26:29]
	v_mfma_f32_16x16x32_bf16 v[26:29], v[218:221], v[230:233], v[50:53]
	v_mfma_f32_16x16x32_bf16 v[46:49], v[248:251], v[234:237], v[26:29]
	v_mfma_f32_16x16x32_bf16 v[26:29], v[192:195], v[238:241], v[54:57]
	v_mfma_f32_16x16x32_bf16 v[30:33], v[218:221], v[238:241], v[176:179]
	v_mfma_f32_16x16x32_bf16 v[26:29], v[196:199], v[242:245], v[26:29]
	v_mfma_f32_16x16x32_bf16 v[30:33], v[248:251], v[242:245], v[30:33]
	s_setprio 0
	s_barrier
	s_mov_b32 m0, s74
	v_lshl_add_u64 v[50:51], v[208:209], 0, s[50:51]
	s_add_u32 s26, s20, 0x40080
	ds_read_b128 v[82:85], v135 offset:49152
	ds_read_b128 v[90:93], v135 offset:50176
	ds_read_b128 v[168:171], v135 offset:51200
	ds_read_b128 v[172:175], v135 offset:52224
	ds_read_b128 v[176:179], v135 offset:53248
	ds_read_b128 v[230:233], v135 offset:54272
	ds_read_b128 v[234:237], v135 offset:55296
	ds_read_b128 v[238:241], v135 offset:56320
	global_load_lds_dwordx4 v[50:51], off
	v_lshl_add_u64 v[50:51], v[246:247], 0, s[50:51]
	s_mov_b32 m0, s72
	s_addc_u32 s27, s21, 0
	global_load_lds_dwordx4 v[50:51], off
	v_lshl_add_u64 v[50:51], s[26:27], 0, v[0:1]
	s_mov_b32 m0, s24
	s_nop 0
	global_load_lds_dwordx4 v[50:51], off
	v_lshl_add_u64 v[50:51], s[26:27], 0, v[130:131]
	s_mov_b32 m0, s25
	s_nop 0
	global_load_lds_dwordx4 v[50:51], off
	v_lshl_add_u64 v[50:51], v[228:229], 0, s[50:51]
	s_mov_b32 m0, s30
	s_nop 0
	global_load_lds_dwordx4 v[50:51], off
	v_lshl_add_u64 v[50:51], v[226:227], 0, s[50:51]
	s_mov_b32 m0, s31
	s_nop 0
	global_load_lds_dwordx4 v[50:51], off
	s_waitcnt vmcnt(8)
	s_waitcnt lgkmcnt(0)
	s_barrier
	s_setprio 1
	s_waitcnt lgkmcnt(0)
	v_mfma_f32_16x16x32_bf16 v[50:53], v[102:105], v[82:85], v[136:139]
	v_mfma_f32_16x16x32_bf16 v[98:101], v[122:125], v[90:93], v[50:53]
	v_mfma_f32_16x16x32_bf16 v[50:53], v[126:129], v[82:85], v[140:143]
	v_mfma_f32_16x16x32_bf16 v[106:109], v[164:167], v[90:93], v[50:53]
	v_mfma_f32_16x16x32_bf16 v[50:53], v[102:105], v[168:171], v[144:147]
	v_mfma_f32_16x16x32_bf16 v[86:89], v[122:125], v[172:175], v[50:53]
	v_mfma_f32_16x16x32_bf16 v[50:53], v[126:129], v[168:171], v[148:151]
	v_mfma_f32_16x16x32_bf16 v[94:97], v[164:167], v[172:175], v[50:53]
	v_mfma_f32_16x16x32_bf16 v[50:53], v[102:105], v[176:179], v[152:155]
	v_mfma_f32_16x16x32_bf16 v[66:69], v[122:125], v[230:233], v[50:53]
	v_mfma_f32_16x16x32_bf16 v[50:53], v[126:129], v[176:179], v[156:159]
	v_mfma_f32_16x16x32_bf16 v[74:77], v[164:167], v[230:233], v[50:53]
	v_mfma_f32_16x16x32_bf16 v[50:53], v[102:105], v[234:237], v[110:113]
	v_mfma_f32_16x16x32_bf16 v[54:57], v[126:129], v[234:237], v[114:117]
	v_mfma_f32_16x16x32_bf16 v[50:53], v[122:125], v[238:241], v[50:53]
	v_mfma_f32_16x16x32_bf16 v[54:57], v[164:167], v[238:241], v[54:57]
	v_mfma_f32_16x16x32_bf16 v[102:105], v[192:195], v[82:85], v[118:121]
	v_mfma_f32_16x16x32_bf16 v[82:85], v[218:221], v[82:85], v[200:203]
	v_mfma_f32_16x16x32_bf16 v[126:129], v[248:251], v[90:93], v[82:85]
	v_mfma_f32_16x16x32_bf16 v[82:85], v[192:195], v[168:171], v[204:207]
	v_mfma_f32_16x16x32_bf16 v[114:117], v[196:199], v[172:175], v[82:85]
	v_mfma_f32_16x16x32_bf16 v[82:85], v[218:221], v[168:171], v[180:183]
	v_mfma_f32_16x16x32_bf16 v[118:121], v[248:251], v[172:175], v[82:85]
	v_mfma_f32_16x16x32_bf16 v[82:85], v[192:195], v[176:179], v[214:217]
	v_mfma_f32_16x16x32_bf16 v[122:125], v[196:199], v[90:93], v[102:105]
	v_mfma_f32_16x16x32_bf16 v[102:105], v[196:199], v[230:233], v[82:85]
	v_mfma_f32_16x16x32_bf16 v[82:85], v[218:221], v[176:179], v[184:187]
	v_mfma_f32_16x16x32_bf16 v[110:113], v[248:251], v[230:233], v[82:85]
	v_mfma_f32_16x16x32_bf16 v[82:85], v[192:195], v[234:237], v[188:191]
	v_mfma_f32_16x16x32_bf16 v[90:93], v[218:221], v[234:237], v[160:163]
	v_mfma_f32_16x16x32_bf16 v[82:85], v[196:199], v[238:241], v[82:85]
	v_mfma_f32_16x16x32_bf16 v[90:93], v[248:251], v[238:241], v[90:93]
	s_setprio 0
	s_barrier
	s_andn2_b64 vcc, exec, s[4:5]
	s_cbranch_vccnz .LBB0_827
	s_barrier

.LBB0_935:
	s_add_u32 s4, s28, 0xfffc0080
	s_addc_u32 s5, s29, -1
	s_add_i32 s75, 0, 0x10000
	s_cmp_eq_u32 s74, 12
	s_cselect_b32 s31, s19, s5
	s_cselect_b32 s30, vcc_lo, s4
	s_cselect_b32 s5, s17, s73
	s_cselect_b32 s4, vcc_hi, s72
	s_add_i32 s78, 0, 0x14000
	v_add_u32_e32 v156, s75, v145
	v_add_u32_e32 v172, s78, v145
	ds_read_b128 v[140:143], v156
	ds_read_b128 v[148:151], v156 offset:1024
	ds_read_b128 v[152:155], v156 offset:2048
	ds_read_b128 v[156:159], v156 offset:3072
	ds_read_b128 v[160:163], v172
	ds_read_b128 v[164:167], v172 offset:1024
	ds_read_b128 v[168:171], v172 offset:2048
	ds_read_b128 v[172:175], v172 offset:3072
	v_lshl_add_u64 v[208:209], s[28:29], 0, v[138:139]
	s_add_i32 m0, s25, 0xc000
	ds_read_b128 v[176:179], v147
	ds_read_b128 v[180:183], v147 offset:1024
	ds_read_b128 v[184:187], v147 offset:2048
	ds_read_b128 v[188:191], v147 offset:3072
	ds_read_b128 v[192:195], v147 offset:4096
	ds_read_b128 v[196:199], v147 offset:5120
	ds_read_b128 v[200:203], v147 offset:6144
	ds_read_b128 v[204:207], v147 offset:7168
	global_load_lds_dwordx4 v[208:209], off
	v_lshl_add_u64 v[208:209], s[28:29], 0, v[136:137]
	s_add_i32 m0, s25, 0xe000
	s_nop 0
	global_load_lds_dwordx4 v[208:209], off
	s_waitcnt vmcnt(8)
	s_waitcnt lgkmcnt(0)
	s_barrier
	s_setprio 1
	s_waitcnt lgkmcnt(0)
	v_mfma_f32_16x16x32_bf16 v[126:129], v[140:143], v[176:179], v[126:129]
	v_mfma_f32_16x16x32_bf16 v[118:121], v[152:155], v[176:179], v[118:121]
	v_mfma_f32_16x16x32_bf16 v[110:113], v[140:143], v[184:187], v[110:113]
	v_mfma_f32_16x16x32_bf16 v[102:105], v[152:155], v[184:187], v[102:105]
	v_mfma_f32_16x16x32_bf16 v[94:97], v[140:143], v[192:195], v[94:97]
	v_mfma_f32_16x16x32_bf16 v[86:89], v[152:155], v[192:195], v[86:89]
	v_mfma_f32_16x16x32_bf16 v[78:81], v[140:143], v[200:203], v[78:81]
	v_mfma_f32_16x16x32_bf16 v[70:73], v[152:155], v[200:203], v[70:73]
	v_mfma_f32_16x16x32_bf16 v[126:129], v[148:151], v[180:183], v[126:129]
	v_mfma_f32_16x16x32_bf16 v[118:121], v[156:159], v[180:183], v[118:121]
	v_mfma_f32_16x16x32_bf16 v[110:113], v[148:151], v[188:191], v[110:113]
	v_mfma_f32_16x16x32_bf16 v[102:105], v[156:159], v[188:191], v[102:105]
	v_mfma_f32_16x16x32_bf16 v[94:97], v[148:151], v[196:199], v[94:97]
	v_mfma_f32_16x16x32_bf16 v[86:89], v[156:159], v[196:199], v[86:89]
	v_mfma_f32_16x16x32_bf16 v[78:81], v[148:151], v[204:207], v[78:81]
	v_mfma_f32_16x16x32_bf16 v[70:73], v[156:159], v[204:207], v[70:73]
	v_mfma_f32_16x16x32_bf16 v[122:125], v[160:163], v[176:179], v[122:125]
	v_mfma_f32_16x16x32_bf16 v[114:117], v[168:171], v[176:179], v[114:117]
	v_mfma_f32_16x16x32_bf16 v[106:109], v[160:163], v[184:187], v[106:109]
	v_mfma_f32_16x16x32_bf16 v[98:101], v[168:171], v[184:187], v[98:101]
	v_mfma_f32_16x16x32_bf16 v[90:93], v[160:163], v[192:195], v[90:93]
	v_mfma_f32_16x16x32_bf16 v[82:85], v[168:171], v[192:195], v[82:85]
	v_mfma_f32_16x16x32_bf16 v[74:77], v[160:163], v[200:203], v[74:77]
	v_mfma_f32_16x16x32_bf16 v[66:69], v[168:171], v[200:203], v[66:69]
	v_mfma_f32_16x16x32_bf16 v[122:125], v[164:167], v[180:183], v[122:125]
	v_mfma_f32_16x16x32_bf16 v[114:117], v[172:175], v[180:183], v[114:117]
	v_mfma_f32_16x16x32_bf16 v[106:109], v[164:167], v[188:191], v[106:109]
	v_mfma_f32_16x16x32_bf16 v[98:101], v[172:175], v[188:191], v[98:101]
	v_mfma_f32_16x16x32_bf16 v[90:93], v[164:167], v[196:199], v[90:93]
	v_mfma_f32_16x16x32_bf16 v[82:85], v[172:175], v[196:199], v[82:85]
	v_mfma_f32_16x16x32_bf16 v[74:77], v[164:167], v[204:207], v[74:77]
	v_mfma_f32_16x16x32_bf16 v[66:69], v[172:175], v[204:207], v[66:69]
	s_setprio 0
	s_barrier
	s_add_i32 s75, s75, s37
	v_lshl_add_u64 v[208:209], s[4:5], 0, v[0:1]
	s_mov_b32 m0, s75
	ds_read_b128 v[176:179], v147 offset:16384
	ds_read_b128 v[180:183], v147 offset:17408
	ds_read_b128 v[184:187], v147 offset:18432
	ds_read_b128 v[188:191], v147 offset:19456
	ds_read_b128 v[192:195], v147 offset:20480
	ds_read_b128 v[196:199], v147 offset:21504
	ds_read_b128 v[200:203], v147 offset:22528
	ds_read_b128 v[204:207], v147 offset:23552
	global_load_lds_dwordx4 v[208:209], off
	s_add_i32 m0, s75, 0x2000
	s_add_u32 s76, s4, 0x40000
	v_lshl_add_u64 v[214:215], s[4:5], 0, v[130:131]
	s_addc_u32 s77, s5, 0
	s_add_i32 s75, s78, s37
	global_load_lds_dwordx4 v[214:215], off
	v_lshl_add_u64 v[216:217], s[76:77], 0, v[0:1]
	s_mov_b32 m0, s75
	v_lshl_add_u64 v[218:219], s[30:31], 0, v[132:133]
	global_load_lds_dwordx4 v[216:217], off
	v_lshl_add_u64 v[216:217], s[76:77], 0, v[130:131]
	s_add_i32 m0, s75, 0x2000
	s_nop 0
	global_load_lds_dwordx4 v[216:217], off
	v_lshl_add_u64 v[216:217], s[30:31], 0, v[134:135]
	s_mov_b32 m0, s25
	s_nop 0
	global_load_lds_dwordx4 v[216:217], off
	s_mov_b32 m0, s27
	s_nop 0
	global_load_lds_dwordx4 v[218:219], off
	s_waitcnt vmcnt(8)
	s_waitcnt lgkmcnt(0)
	s_barrier
	s_setprio 1
	s_waitcnt lgkmcnt(0)
	v_mfma_f32_16x16x32_bf16 v[62:65], v[140:143], v[176:179], v[62:65]
	v_mfma_f32_16x16x32_bf16 v[54:57], v[152:155], v[176:179], v[54:57]
	v_mfma_f32_16x16x32_bf16 v[46:49], v[140:143], v[184:187], v[46:49]
	v_mfma_f32_16x16x32_bf16 v[38:41], v[152:155], v[184:187], v[38:41]
	v_mfma_f32_16x16x32_bf16 v[30:33], v[140:143], v[192:195], v[30:33]
	v_mfma_f32_16x16x32_bf16 v[22:25], v[152:155], v[192:195], v[22:25]
	v_mfma_f32_16x16x32_bf16 v[14:17], v[140:143], v[200:203], v[14:17]
	v_mfma_f32_16x16x32_bf16 v[6:9], v[152:155], v[200:203], v[6:9]
	v_mfma_f32_16x16x32_bf16 v[62:65], v[148:151], v[180:183], v[62:65]
	v_mfma_f32_16x16x32_bf16 v[54:57], v[156:159], v[180:183], v[54:57]
	v_mfma_f32_16x16x32_bf16 v[46:49], v[148:151], v[188:191], v[46:49]
	v_mfma_f32_16x16x32_bf16 v[38:41], v[156:159], v[188:191], v[38:41]
	v_mfma_f32_16x16x32_bf16 v[30:33], v[148:151], v[196:199], v[30:33]
	v_mfma_f32_16x16x32_bf16 v[22:25], v[156:159], v[196:199], v[22:25]
	v_mfma_f32_16x16x32_bf16 v[14:17], v[148:151], v[204:207], v[14:17]
	v_mfma_f32_16x16x32_bf16 v[6:9], v[156:159], v[204:207], v[6:9]
	v_mfma_f32_16x16x32_bf16 v[58:61], v[160:163], v[176:179], v[58:61]
	v_mfma_f32_16x16x32_bf16 v[50:53], v[168:171], v[176:179], v[50:53]
	v_mfma_f32_16x16x32_bf16 v[42:45], v[160:163], v[184:187], v[42:45]
	v_mfma_f32_16x16x32_bf16 v[34:37], v[168:171], v[184:187], v[34:37]
	v_mfma_f32_16x16x32_bf16 v[26:29], v[160:163], v[192:195], v[26:29]
	v_mfma_f32_16x16x32_bf16 v[18:21], v[168:171], v[192:195], v[18:21]
	v_mfma_f32_16x16x32_bf16 v[10:13], v[160:163], v[200:203], v[10:13]
	v_mfma_f32_16x16x32_bf16 v[2:5], v[168:171], v[200:203], v[2:5]
	v_mfma_f32_16x16x32_bf16 v[58:61], v[164:167], v[180:183], v[58:61]
	v_mfma_f32_16x16x32_bf16 v[50:53], v[172:175], v[180:183], v[50:53]
	v_mfma_f32_16x16x32_bf16 v[42:45], v[164:167], v[188:191], v[42:45]
	v_mfma_f32_16x16x32_bf16 v[34:37], v[172:175], v[188:191], v[34:37]
	v_mfma_f32_16x16x32_bf16 v[26:29], v[164:167], v[196:199], v[26:29]
	v_mfma_f32_16x16x32_bf16 v[18:21], v[172:175], v[196:199], v[18:21]
	v_mfma_f32_16x16x32_bf16 v[10:13], v[164:167], v[204:207], v[10:13]
	v_mfma_f32_16x16x32_bf16 v[2:5], v[172:175], v[204:207], v[2:5]
	s_setprio 0
	s_barrier
	s_add_i32 s75, 0, 0x18000
	s_add_i32 s76, 0, 0x1c000
	v_add_u32_e32 v156, s75, v145
	v_add_u32_e32 v172, s76, v145
	ds_read_b128 v[140:143], v156
	ds_read_b128 v[148:151], v156 offset:1024
	ds_read_b128 v[152:155], v156 offset:2048
	ds_read_b128 v[156:159], v156 offset:3072
	ds_read_b128 v[160:163], v172
	ds_read_b128 v[164:167], v172 offset:1024
	ds_read_b128 v[168:171], v172 offset:2048
	ds_read_b128 v[172:175], v172 offset:3072
	s_add_u32 s30, s30, 0x40000
	s_addc_u32 s31, s31, 0
	s_mov_b32 m0, s40
	v_lshl_add_u64 v[220:221], s[30:31], 0, v[134:135]
	ds_read_b128 v[176:179], v147 offset:32768
	ds_read_b128 v[180:183], v147 offset:33792
	ds_read_b128 v[184:187], v147 offset:34816
	ds_read_b128 v[188:191], v147 offset:35840
	ds_read_b128 v[192:195], v147 offset:36864
	ds_read_b128 v[196:199], v147 offset:37888
	ds_read_b128 v[200:203], v147 offset:38912
	ds_read_b128 v[204:207], v147 offset:39936
	global_load_lds_dwordx4 v[220:221], off
	v_lshl_add_u64 v[220:221], s[30:31], 0, v[132:133]
	s_mov_b32 m0, s41
	s_nop 0
	global_load_lds_dwordx4 v[220:221], off
	s_waitcnt vmcnt(8)
	s_waitcnt lgkmcnt(0)
	s_barrier
	s_setprio 1
	s_waitcnt lgkmcnt(0)
	v_mfma_f32_16x16x32_bf16 v[126:129], v[140:143], v[176:179], v[126:129]
	v_mfma_f32_16x16x32_bf16 v[118:121], v[152:155], v[176:179], v[118:121]
	v_mfma_f32_16x16x32_bf16 v[110:113], v[140:143], v[184:187], v[110:113]
	v_mfma_f32_16x16x32_bf16 v[102:105], v[152:155], v[184:187], v[102:105]
	v_mfma_f32_16x16x32_bf16 v[94:97], v[140:143], v[192:195], v[94:97]
	v_mfma_f32_16x16x32_bf16 v[86:89], v[152:155], v[192:195], v[86:89]
	v_mfma_f32_16x16x32_bf16 v[78:81], v[140:143], v[200:203], v[78:81]
	v_mfma_f32_16x16x32_bf16 v[70:73], v[152:155], v[200:203], v[70:73]
	v_mfma_f32_16x16x32_bf16 v[126:129], v[148:151], v[180:183], v[126:129]
	v_mfma_f32_16x16x32_bf16 v[118:121], v[156:159], v[180:183], v[118:121]
	v_mfma_f32_16x16x32_bf16 v[110:113], v[148:151], v[188:191], v[110:113]
	v_mfma_f32_16x16x32_bf16 v[102:105], v[156:159], v[188:191], v[102:105]
	v_mfma_f32_16x16x32_bf16 v[94:97], v[148:151], v[196:199], v[94:97]
	v_mfma_f32_16x16x32_bf16 v[86:89], v[156:159], v[196:199], v[86:89]
	v_mfma_f32_16x16x32_bf16 v[78:81], v[148:151], v[204:207], v[78:81]
	v_mfma_f32_16x16x32_bf16 v[70:73], v[156:159], v[204:207], v[70:73]
	v_mfma_f32_16x16x32_bf16 v[122:125], v[160:163], v[176:179], v[122:125]
	v_mfma_f32_16x16x32_bf16 v[114:117], v[168:171], v[176:179], v[114:117]
	v_mfma_f32_16x16x32_bf16 v[106:109], v[160:163], v[184:187], v[106:109]
	v_mfma_f32_16x16x32_bf16 v[98:101], v[168:171], v[184:187], v[98:101]
	v_mfma_f32_16x16x32_bf16 v[90:93], v[160:163], v[192:195], v[90:93]
	v_mfma_f32_16x16x32_bf16 v[82:85], v[168:171], v[192:195], v[82:85]
	v_mfma_f32_16x16x32_bf16 v[74:77], v[160:163], v[200:203], v[74:77]
	v_mfma_f32_16x16x32_bf16 v[66:69], v[168:171], v[200:203], v[66:69]
	v_mfma_f32_16x16x32_bf16 v[122:125], v[164:167], v[180:183], v[122:125]
	v_mfma_f32_16x16x32_bf16 v[114:117], v[172:175], v[180:183], v[114:117]
	v_mfma_f32_16x16x32_bf16 v[106:109], v[164:167], v[188:191], v[106:109]
	v_mfma_f32_16x16x32_bf16 v[98:101], v[172:175], v[188:191], v[98:101]
	v_mfma_f32_16x16x32_bf16 v[90:93], v[164:167], v[196:199], v[90:93]
	v_mfma_f32_16x16x32_bf16 v[82:85], v[172:175], v[196:199], v[82:85]
	v_mfma_f32_16x16x32_bf16 v[74:77], v[164:167], v[204:207], v[74:77]
	v_mfma_f32_16x16x32_bf16 v[66:69], v[172:175], v[204:207], v[66:69]
	s_setprio 0
	s_barrier
	s_add_i32 s30, s75, s37
	v_lshl_add_u64 v[208:209], v[208:209], 0, s[50:51]
	s_mov_b32 m0, s30
	ds_read_b128 v[176:179], v147 offset:49152
	ds_read_b128 v[180:183], v147 offset:50176
	ds_read_b128 v[184:187], v147 offset:51200
	ds_read_b128 v[188:191], v147 offset:52224
	ds_read_b128 v[192:195], v147 offset:53248
	ds_read_b128 v[196:199], v147 offset:54272
	ds_read_b128 v[200:203], v147 offset:55296
	ds_read_b128 v[204:207], v147 offset:56320
	global_load_lds_dwordx4 v[208:209], off
	s_add_i32 m0, s30, 0x2000
	s_add_u32 s4, s4, 0x40080
	v_lshl_add_u64 v[208:209], v[214:215], 0, s[50:51]
	s_addc_u32 s5, s5, 0
	s_add_i32 s30, s76, s37
	global_load_lds_dwordx4 v[208:209], off
	v_lshl_add_u64 v[208:209], s[4:5], 0, v[0:1]
	s_mov_b32 m0, s30
	s_nop 0
	global_load_lds_dwordx4 v[208:209], off
	v_lshl_add_u64 v[208:209], s[4:5], 0, v[130:131]
	s_add_i32 m0, s30, 0x2000
	s_nop 0
	global_load_lds_dwordx4 v[208:209], off
	v_lshl_add_u64 v[208:209], v[216:217], 0, s[50:51]
	s_mov_b32 m0, s71
	s_nop 0
	global_load_lds_dwordx4 v[208:209], off
	v_lshl_add_u64 v[208:209], v[218:219], 0, s[50:51]
	s_mov_b32 m0, s6
	s_nop 0
	global_load_lds_dwordx4 v[208:209], off
	s_waitcnt vmcnt(8)
	s_waitcnt lgkmcnt(0)
	s_barrier
	s_setprio 1
	s_waitcnt lgkmcnt(0)
	v_mfma_f32_16x16x32_bf16 v[62:65], v[140:143], v[176:179], v[62:65]
	v_mfma_f32_16x16x32_bf16 v[54:57], v[152:155], v[176:179], v[54:57]
	v_mfma_f32_16x16x32_bf16 v[46:49], v[140:143], v[184:187], v[46:49]
	v_mfma_f32_16x16x32_bf16 v[38:41], v[152:155], v[184:187], v[38:41]
	v_mfma_f32_16x16x32_bf16 v[30:33], v[140:143], v[192:195], v[30:33]
	v_mfma_f32_16x16x32_bf16 v[22:25], v[152:155], v[192:195], v[22:25]
	v_mfma_f32_16x16x32_bf16 v[14:17], v[140:143], v[200:203], v[14:17]
	v_mfma_f32_16x16x32_bf16 v[6:9], v[152:155], v[200:203], v[6:9]
	v_mfma_f32_16x16x32_bf16 v[62:65], v[148:151], v[180:183], v[62:65]
	v_mfma_f32_16x16x32_bf16 v[54:57], v[156:159], v[180:183], v[54:57]
	v_mfma_f32_16x16x32_bf16 v[46:49], v[148:151], v[188:191], v[46:49]
	v_mfma_f32_16x16x32_bf16 v[38:41], v[156:159], v[188:191], v[38:41]
	v_mfma_f32_16x16x32_bf16 v[30:33], v[148:151], v[196:199], v[30:33]
	v_mfma_f32_16x16x32_bf16 v[22:25], v[156:159], v[196:199], v[22:25]
	v_mfma_f32_16x16x32_bf16 v[14:17], v[148:151], v[204:207], v[14:17]
	v_mfma_f32_16x16x32_bf16 v[6:9], v[156:159], v[204:207], v[6:9]
	v_mfma_f32_16x16x32_bf16 v[58:61], v[160:163], v[176:179], v[58:61]
	v_mfma_f32_16x16x32_bf16 v[50:53], v[168:171], v[176:179], v[50:53]
	v_mfma_f32_16x16x32_bf16 v[42:45], v[160:163], v[184:187], v[42:45]
	v_mfma_f32_16x16x32_bf16 v[34:37], v[168:171], v[184:187], v[34:37]
	v_mfma_f32_16x16x32_bf16 v[26:29], v[160:163], v[192:195], v[26:29]
	v_mfma_f32_16x16x32_bf16 v[18:21], v[168:171], v[192:195], v[18:21]
	v_mfma_f32_16x16x32_bf16 v[10:13], v[160:163], v[200:203], v[10:13]
	v_mfma_f32_16x16x32_bf16 v[2:5], v[168:171], v[200:203], v[2:5]
	v_mfma_f32_16x16x32_bf16 v[58:61], v[164:167], v[180:183], v[58:61]
	v_mfma_f32_16x16x32_bf16 v[50:53], v[172:175], v[180:183], v[50:53]
	v_mfma_f32_16x16x32_bf16 v[42:45], v[164:167], v[188:191], v[42:45]
	v_mfma_f32_16x16x32_bf16 v[34:37], v[172:175], v[188:191], v[34:37]
	v_mfma_f32_16x16x32_bf16 v[26:29], v[164:167], v[196:199], v[26:29]
	v_mfma_f32_16x16x32_bf16 v[18:21], v[172:175], v[196:199], v[18:21]
	v_mfma_f32_16x16x32_bf16 v[10:13], v[164:167], v[204:207], v[10:13]
	v_mfma_f32_16x16x32_bf16 v[2:5], v[172:175], v[204:207], v[2:5]
	s_setprio 0
	s_barrier
	s_add_i32 s74, s74, 2
	s_add_u32 s72, s72, 0x100
	s_addc_u32 s73, s73, 0
	s_add_u32 s28, s28, 0x100
	s_addc_u32 s29, s29, 0
	s_cmp_gt_u32 s74, 13
	s_cbranch_scc0 .LBB0_935
	s_and_b64 vcc, exec, s[14:15]
	s_cbranch_vccz .LBB0_938
	s_barrier

.LBB0_1004:
	s_add_u32 s4, s18, s22
	s_addc_u32 s5, s19, s23
	s_add_u32 s4, s4, 0x100
	s_addc_u32 s5, s5, 0
	s_add_u32 s75, s72, s22
	s_addc_u32 s76, s73, s23
	s_add_i32 s77, 0, 0x10000
	s_cmpk_eq_i32 s22, 0x1500
	s_cselect_b32 s25, s21, s5
	s_cselect_b32 s24, s20, s4
	v_add_u32_e32 v147, s77, v131
	s_cselect_b32 s5, s11, s76
	s_cselect_b32 s4, s10, s75
	s_add_i32 s75, 0, 0x14000
	ds_read_b128 v[148:151], v147
	ds_read_b128 v[152:155], v147 offset:1024
	ds_read_b128 v[156:159], v147 offset:2048
	ds_read_b128 v[160:163], v147 offset:3072
	v_add_u32_e32 v147, s75, v131
	ds_read_b128 v[164:167], v147
	ds_read_b128 v[168:171], v147 offset:1024
	ds_read_b128 v[172:175], v147 offset:2048
	ds_read_b128 v[176:179], v147 offset:3072
	v_lshl_add_u64 v[208:209], v[144:145], 0, s[22:23]
	s_add_i32 m0, s26, 0xc000
	ds_read_b128 v[180:183], v146
	ds_read_b128 v[184:187], v146 offset:1024
	ds_read_b128 v[188:191], v146 offset:2048
	ds_read_b128 v[192:195], v146 offset:3072
	ds_read_b128 v[196:199], v146 offset:4096
	ds_read_b128 v[200:203], v146 offset:5120
	ds_read_b128 v[204:207], v146 offset:6144
	ds_read_b128 v[230:233], v146 offset:7168
	global_load_lds_dwordx4 v[208:209], off
	v_lshl_add_u64 v[208:209], v[142:143], 0, s[22:23]
	s_add_i32 m0, s26, 0xe000
	s_nop 0
	global_load_lds_dwordx4 v[208:209], off
	s_waitcnt vmcnt(8)
	s_waitcnt lgkmcnt(0)
	s_barrier
	s_setprio 1
	s_waitcnt lgkmcnt(0)
	v_mfma_f32_16x16x32_bf16 v[126:129], v[148:151], v[180:183], v[126:129]
	v_mfma_f32_16x16x32_bf16 v[122:125], v[156:159], v[180:183], v[122:125]
	v_mfma_f32_16x16x32_bf16 v[114:117], v[148:151], v[188:191], v[114:117]
	v_mfma_f32_16x16x32_bf16 v[106:109], v[156:159], v[188:191], v[106:109]
	v_mfma_f32_16x16x32_bf16 v[98:101], v[148:151], v[196:199], v[98:101]
	v_mfma_f32_16x16x32_bf16 v[90:93], v[156:159], v[196:199], v[90:93]
	v_mfma_f32_16x16x32_bf16 v[82:85], v[148:151], v[204:207], v[82:85]
	v_mfma_f32_16x16x32_bf16 v[74:77], v[156:159], v[204:207], v[74:77]
	v_mfma_f32_16x16x32_bf16 v[126:129], v[152:155], v[184:187], v[126:129]
	v_mfma_f32_16x16x32_bf16 v[122:125], v[160:163], v[184:187], v[122:125]
	v_mfma_f32_16x16x32_bf16 v[114:117], v[152:155], v[192:195], v[114:117]
	v_mfma_f32_16x16x32_bf16 v[106:109], v[160:163], v[192:195], v[106:109]
	v_mfma_f32_16x16x32_bf16 v[98:101], v[152:155], v[200:203], v[98:101]
	v_mfma_f32_16x16x32_bf16 v[90:93], v[160:163], v[200:203], v[90:93]
	v_mfma_f32_16x16x32_bf16 v[82:85], v[152:155], v[230:233], v[82:85]
	v_mfma_f32_16x16x32_bf16 v[74:77], v[160:163], v[230:233], v[74:77]
	v_mfma_f32_16x16x32_bf16 v[118:121], v[164:167], v[180:183], v[118:121]
	v_mfma_f32_16x16x32_bf16 v[110:113], v[172:175], v[180:183], v[110:113]
	v_mfma_f32_16x16x32_bf16 v[102:105], v[164:167], v[188:191], v[102:105]
	v_mfma_f32_16x16x32_bf16 v[94:97], v[172:175], v[188:191], v[94:97]
	v_mfma_f32_16x16x32_bf16 v[86:89], v[164:167], v[196:199], v[86:89]
	v_mfma_f32_16x16x32_bf16 v[78:81], v[172:175], v[196:199], v[78:81]
	v_mfma_f32_16x16x32_bf16 v[70:73], v[164:167], v[204:207], v[70:73]
	v_mfma_f32_16x16x32_bf16 v[66:69], v[172:175], v[204:207], v[66:69]
	v_mfma_f32_16x16x32_bf16 v[118:121], v[168:171], v[184:187], v[118:121]
	v_mfma_f32_16x16x32_bf16 v[110:113], v[176:179], v[184:187], v[110:113]
	v_mfma_f32_16x16x32_bf16 v[102:105], v[168:171], v[192:195], v[102:105]
	v_mfma_f32_16x16x32_bf16 v[94:97], v[176:179], v[192:195], v[94:97]
	v_mfma_f32_16x16x32_bf16 v[86:89], v[168:171], v[200:203], v[86:89]
	v_mfma_f32_16x16x32_bf16 v[78:81], v[176:179], v[200:203], v[78:81]
	v_mfma_f32_16x16x32_bf16 v[70:73], v[168:171], v[230:233], v[70:73]
	v_mfma_f32_16x16x32_bf16 v[66:69], v[176:179], v[230:233], v[66:69]
	s_setprio 0
	s_barrier
	s_add_i32 s76, s77, s15
	v_lshl_add_u64 v[208:209], s[4:5], 0, v[0:1]
	s_mov_b32 m0, s76
	ds_read_b128 v[180:183], v146 offset:16384
	ds_read_b128 v[184:187], v146 offset:17408
	ds_read_b128 v[188:191], v146 offset:18432
	ds_read_b128 v[192:195], v146 offset:19456
	ds_read_b128 v[196:199], v146 offset:20480
	ds_read_b128 v[200:203], v146 offset:21504
	ds_read_b128 v[204:207], v146 offset:22528
	ds_read_b128 v[230:233], v146 offset:23552
	global_load_lds_dwordx4 v[208:209], off
	s_add_i32 m0, s76, 0x2000
	s_add_u32 s76, s4, 0xb0000
	v_lshl_add_u64 v[214:215], s[4:5], 0, v[132:133]
	s_addc_u32 s77, s5, 0
	s_add_i32 s75, s75, s15
	global_load_lds_dwordx4 v[214:215], off
	v_lshl_add_u64 v[218:219], s[76:77], 0, v[0:1]
	s_mov_b32 m0, s75
	v_lshl_add_u64 v[226:227], s[24:25], 0, v[134:135]
	global_load_lds_dwordx4 v[218:219], off
	v_lshl_add_u64 v[218:219], s[76:77], 0, v[132:133]
	s_add_i32 m0, s75, 0x2000
	s_nop 0
	global_load_lds_dwordx4 v[218:219], off
	v_lshl_add_u64 v[218:219], s[24:25], 0, v[136:137]
	s_mov_b32 m0, s26
	s_nop 0
	global_load_lds_dwordx4 v[218:219], off
	s_mov_b32 m0, s27
	s_nop 0
	global_load_lds_dwordx4 v[226:227], off
	s_waitcnt vmcnt(8)
	s_waitcnt lgkmcnt(0)
	s_barrier
	s_setprio 1
	s_waitcnt lgkmcnt(0)
	v_mfma_f32_16x16x32_bf16 v[62:65], v[148:151], v[180:183], v[62:65]
	v_mfma_f32_16x16x32_bf16 v[58:61], v[156:159], v[180:183], v[58:61]
	v_mfma_f32_16x16x32_bf16 v[50:53], v[148:151], v[188:191], v[50:53]
	v_mfma_f32_16x16x32_bf16 v[42:45], v[156:159], v[188:191], v[42:45]
	v_mfma_f32_16x16x32_bf16 v[34:37], v[148:151], v[196:199], v[34:37]
	v_mfma_f32_16x16x32_bf16 v[26:29], v[156:159], v[196:199], v[26:29]
	v_mfma_f32_16x16x32_bf16 v[18:21], v[148:151], v[204:207], v[18:21]
	v_mfma_f32_16x16x32_bf16 v[10:13], v[156:159], v[204:207], v[10:13]
	v_mfma_f32_16x16x32_bf16 v[62:65], v[152:155], v[184:187], v[62:65]
	v_mfma_f32_16x16x32_bf16 v[58:61], v[160:163], v[184:187], v[58:61]
	v_mfma_f32_16x16x32_bf16 v[50:53], v[152:155], v[192:195], v[50:53]
	v_mfma_f32_16x16x32_bf16 v[42:45], v[160:163], v[192:195], v[42:45]
	v_mfma_f32_16x16x32_bf16 v[34:37], v[152:155], v[200:203], v[34:37]
	v_mfma_f32_16x16x32_bf16 v[26:29], v[160:163], v[200:203], v[26:29]
	v_mfma_f32_16x16x32_bf16 v[18:21], v[152:155], v[230:233], v[18:21]
	v_mfma_f32_16x16x32_bf16 v[10:13], v[160:163], v[230:233], v[10:13]
	v_mfma_f32_16x16x32_bf16 v[54:57], v[164:167], v[180:183], v[54:57]
	v_mfma_f32_16x16x32_bf16 v[46:49], v[172:175], v[180:183], v[46:49]
	v_mfma_f32_16x16x32_bf16 v[38:41], v[164:167], v[188:191], v[38:41]
	v_mfma_f32_16x16x32_bf16 v[30:33], v[172:175], v[188:191], v[30:33]
	v_mfma_f32_16x16x32_bf16 v[22:25], v[164:167], v[196:199], v[22:25]
	v_mfma_f32_16x16x32_bf16 v[14:17], v[172:175], v[196:199], v[14:17]
	v_mfma_f32_16x16x32_bf16 v[6:9], v[164:167], v[204:207], v[6:9]
	v_mfma_f32_16x16x32_bf16 v[2:5], v[172:175], v[204:207], v[2:5]
	v_mfma_f32_16x16x32_bf16 v[54:57], v[168:171], v[184:187], v[54:57]
	v_mfma_f32_16x16x32_bf16 v[46:49], v[176:179], v[184:187], v[46:49]
	v_mfma_f32_16x16x32_bf16 v[38:41], v[168:171], v[192:195], v[38:41]
	v_mfma_f32_16x16x32_bf16 v[30:33], v[176:179], v[192:195], v[30:33]
	v_mfma_f32_16x16x32_bf16 v[22:25], v[168:171], v[200:203], v[22:25]
	v_mfma_f32_16x16x32_bf16 v[14:17], v[176:179], v[200:203], v[14:17]
	v_mfma_f32_16x16x32_bf16 v[6:9], v[168:171], v[230:233], v[6:9]
	v_mfma_f32_16x16x32_bf16 v[2:5], v[176:179], v[230:233], v[2:5]
	s_setprio 0
	s_barrier
	s_add_i32 s75, 0, 0x18000
	v_add_u32_e32 v147, s75, v131
	s_add_i32 s76, 0, 0x1c000
	ds_read_b128 v[148:151], v147
	ds_read_b128 v[152:155], v147 offset:1024
	ds_read_b128 v[156:159], v147 offset:2048
	ds_read_b128 v[160:163], v147 offset:3072
	v_add_u32_e32 v147, s76, v131
	ds_read_b128 v[164:167], v147
	ds_read_b128 v[168:171], v147 offset:1024
	ds_read_b128 v[172:175], v147 offset:2048
	ds_read_b128 v[176:179], v147 offset:3072
	s_add_u32 s24, s24, 0xb0000
	s_addc_u32 s25, s25, 0
	s_mov_b32 m0, s28
	v_lshl_add_u64 v[228:229], s[24:25], 0, v[136:137]
	ds_read_b128 v[180:183], v146 offset:32768
	ds_read_b128 v[184:187], v146 offset:33792
	ds_read_b128 v[188:191], v146 offset:34816
	ds_read_b128 v[192:195], v146 offset:35840
	ds_read_b128 v[196:199], v146 offset:36864
	ds_read_b128 v[200:203], v146 offset:37888
	ds_read_b128 v[204:207], v146 offset:38912
	ds_read_b128 v[230:233], v146 offset:39936
	global_load_lds_dwordx4 v[228:229], off
	v_lshl_add_u64 v[228:229], s[24:25], 0, v[134:135]
	s_mov_b32 m0, s29
	s_nop 0
	global_load_lds_dwordx4 v[228:229], off
	s_waitcnt vmcnt(8)
	s_waitcnt lgkmcnt(0)
	s_barrier
	s_setprio 1
	s_waitcnt lgkmcnt(0)
	v_mfma_f32_16x16x32_bf16 v[126:129], v[148:151], v[180:183], v[126:129]
	v_mfma_f32_16x16x32_bf16 v[122:125], v[156:159], v[180:183], v[122:125]
	v_mfma_f32_16x16x32_bf16 v[114:117], v[148:151], v[188:191], v[114:117]
	v_mfma_f32_16x16x32_bf16 v[106:109], v[156:159], v[188:191], v[106:109]
	v_mfma_f32_16x16x32_bf16 v[98:101], v[148:151], v[196:199], v[98:101]
	v_mfma_f32_16x16x32_bf16 v[90:93], v[156:159], v[196:199], v[90:93]
	v_mfma_f32_16x16x32_bf16 v[82:85], v[148:151], v[204:207], v[82:85]
	v_mfma_f32_16x16x32_bf16 v[74:77], v[156:159], v[204:207], v[74:77]
	v_mfma_f32_16x16x32_bf16 v[126:129], v[152:155], v[184:187], v[126:129]
	v_mfma_f32_16x16x32_bf16 v[122:125], v[160:163], v[184:187], v[122:125]
	v_mfma_f32_16x16x32_bf16 v[114:117], v[152:155], v[192:195], v[114:117]
	v_mfma_f32_16x16x32_bf16 v[106:109], v[160:163], v[192:195], v[106:109]
	v_mfma_f32_16x16x32_bf16 v[98:101], v[152:155], v[200:203], v[98:101]
	v_mfma_f32_16x16x32_bf16 v[90:93], v[160:163], v[200:203], v[90:93]
	v_mfma_f32_16x16x32_bf16 v[82:85], v[152:155], v[230:233], v[82:85]
	v_mfma_f32_16x16x32_bf16 v[74:77], v[160:163], v[230:233], v[74:77]
	v_mfma_f32_16x16x32_bf16 v[118:121], v[164:167], v[180:183], v[118:121]
	v_mfma_f32_16x16x32_bf16 v[110:113], v[172:175], v[180:183], v[110:113]
	v_mfma_f32_16x16x32_bf16 v[102:105], v[164:167], v[188:191], v[102:105]
	v_mfma_f32_16x16x32_bf16 v[94:97], v[172:175], v[188:191], v[94:97]
	v_mfma_f32_16x16x32_bf16 v[86:89], v[164:167], v[196:199], v[86:89]
	v_mfma_f32_16x16x32_bf16 v[78:81], v[172:175], v[196:199], v[78:81]
	v_mfma_f32_16x16x32_bf16 v[70:73], v[164:167], v[204:207], v[70:73]
	v_mfma_f32_16x16x32_bf16 v[66:69], v[172:175], v[204:207], v[66:69]
	v_mfma_f32_16x16x32_bf16 v[118:121], v[168:171], v[184:187], v[118:121]
	v_mfma_f32_16x16x32_bf16 v[110:113], v[176:179], v[184:187], v[110:113]
	v_mfma_f32_16x16x32_bf16 v[102:105], v[168:171], v[192:195], v[102:105]
	v_mfma_f32_16x16x32_bf16 v[94:97], v[176:179], v[192:195], v[94:97]
	v_mfma_f32_16x16x32_bf16 v[86:89], v[168:171], v[200:203], v[86:89]
	v_mfma_f32_16x16x32_bf16 v[78:81], v[176:179], v[200:203], v[78:81]
	v_mfma_f32_16x16x32_bf16 v[70:73], v[168:171], v[230:233], v[70:73]
	v_mfma_f32_16x16x32_bf16 v[66:69], v[176:179], v[230:233], v[66:69]
	s_setprio 0
	s_barrier
	s_add_i32 s24, s75, s15
	v_lshl_add_u64 v[208:209], v[208:209], 0, s[50:51]
	s_mov_b32 m0, s24
	ds_read_b128 v[180:183], v146 offset:49152
	ds_read_b128 v[184:187], v146 offset:50176
	ds_read_b128 v[188:191], v146 offset:51200
	ds_read_b128 v[192:195], v146 offset:52224
	ds_read_b128 v[196:199], v146 offset:53248
	ds_read_b128 v[200:203], v146 offset:54272
	ds_read_b128 v[204:207], v146 offset:55296
	ds_read_b128 v[230:233], v146 offset:56320
	global_load_lds_dwordx4 v[208:209], off
	s_add_i32 m0, s24, 0x2000
	s_add_u32 s4, s4, 0xb0080
	v_lshl_add_u64 v[208:209], v[214:215], 0, s[50:51]
	s_addc_u32 s5, s5, 0
	s_add_i32 s24, s76, s15
	global_load_lds_dwordx4 v[208:209], off
	v_lshl_add_u64 v[208:209], s[4:5], 0, v[0:1]
	s_mov_b32 m0, s24
	s_nop 0
	global_load_lds_dwordx4 v[208:209], off
	v_lshl_add_u64 v[208:209], s[4:5], 0, v[132:133]
	s_add_i32 m0, s24, 0x2000
	s_nop 0
	global_load_lds_dwordx4 v[208:209], off
	v_lshl_add_u64 v[208:209], v[218:219], 0, s[50:51]
	s_mov_b32 m0, s35
	s_nop 0
	global_load_lds_dwordx4 v[208:209], off
	v_lshl_add_u64 v[208:209], v[226:227], 0, s[50:51]
	s_mov_b32 m0, s36
	s_nop 0
	global_load_lds_dwordx4 v[208:209], off
	s_waitcnt vmcnt(8)
	s_waitcnt lgkmcnt(0)
	s_barrier
	s_setprio 1
	s_waitcnt lgkmcnt(0)
	v_mfma_f32_16x16x32_bf16 v[62:65], v[148:151], v[180:183], v[62:65]
	v_mfma_f32_16x16x32_bf16 v[58:61], v[156:159], v[180:183], v[58:61]
	v_mfma_f32_16x16x32_bf16 v[50:53], v[148:151], v[188:191], v[50:53]
	v_mfma_f32_16x16x32_bf16 v[42:45], v[156:159], v[188:191], v[42:45]
	v_mfma_f32_16x16x32_bf16 v[34:37], v[148:151], v[196:199], v[34:37]
	v_mfma_f32_16x16x32_bf16 v[26:29], v[156:159], v[196:199], v[26:29]
	v_mfma_f32_16x16x32_bf16 v[18:21], v[148:151], v[204:207], v[18:21]
	v_mfma_f32_16x16x32_bf16 v[10:13], v[156:159], v[204:207], v[10:13]
	v_mfma_f32_16x16x32_bf16 v[62:65], v[152:155], v[184:187], v[62:65]
	v_mfma_f32_16x16x32_bf16 v[58:61], v[160:163], v[184:187], v[58:61]
	v_mfma_f32_16x16x32_bf16 v[50:53], v[152:155], v[192:195], v[50:53]
	v_mfma_f32_16x16x32_bf16 v[42:45], v[160:163], v[192:195], v[42:45]
	v_mfma_f32_16x16x32_bf16 v[34:37], v[152:155], v[200:203], v[34:37]
	v_mfma_f32_16x16x32_bf16 v[26:29], v[160:163], v[200:203], v[26:29]
	v_mfma_f32_16x16x32_bf16 v[18:21], v[152:155], v[230:233], v[18:21]
	v_mfma_f32_16x16x32_bf16 v[10:13], v[160:163], v[230:233], v[10:13]
	v_mfma_f32_16x16x32_bf16 v[54:57], v[164:167], v[180:183], v[54:57]
	v_mfma_f32_16x16x32_bf16 v[46:49], v[172:175], v[180:183], v[46:49]
	v_mfma_f32_16x16x32_bf16 v[38:41], v[164:167], v[188:191], v[38:41]
	v_mfma_f32_16x16x32_bf16 v[30:33], v[172:175], v[188:191], v[30:33]
	v_mfma_f32_16x16x32_bf16 v[22:25], v[164:167], v[196:199], v[22:25]
	v_mfma_f32_16x16x32_bf16 v[14:17], v[172:175], v[196:199], v[14:17]
	v_mfma_f32_16x16x32_bf16 v[6:9], v[164:167], v[204:207], v[6:9]
	v_mfma_f32_16x16x32_bf16 v[2:5], v[172:175], v[204:207], v[2:5]
	v_mfma_f32_16x16x32_bf16 v[54:57], v[168:171], v[184:187], v[54:57]
	v_mfma_f32_16x16x32_bf16 v[46:49], v[176:179], v[184:187], v[46:49]
	v_mfma_f32_16x16x32_bf16 v[38:41], v[168:171], v[192:195], v[38:41]
	v_mfma_f32_16x16x32_bf16 v[30:33], v[176:179], v[192:195], v[30:33]
	v_mfma_f32_16x16x32_bf16 v[22:25], v[168:171], v[200:203], v[22:25]
	v_mfma_f32_16x16x32_bf16 v[14:17], v[176:179], v[200:203], v[14:17]
	v_mfma_f32_16x16x32_bf16 v[6:9], v[168:171], v[230:233], v[6:9]
	v_mfma_f32_16x16x32_bf16 v[2:5], v[176:179], v[230:233], v[2:5]
	s_setprio 0
	s_barrier
	s_add_i32 s74, s74, 2
	s_add_u32 s22, s22, 0x100
	s_addc_u32 s23, s23, 0
	s_cmp_gt_u32 s74, 41
	s_cbranch_scc0 .LBB0_1004
	s_add_u32 s4, s72, 0xffffff00
	s_addc_u32 s5, s73, -1
	s_and_b64 vcc, exec, s[8:9]
	s_cbranch_vccnz .LBB0_1007
	v_mov_b32_e32 v2, 0
	s_mov_b32 s14, s38
	s_mov_b32 s16, s39
	s_mov_b64 s[18:19], s[20:21]
	s_mov_b32 s37, s71
	v_mov_b32_e32 v3, v2
	v_mov_b32_e32 v4, v2
	v_mov_b32_e32 v5, v2
	v_mov_b32_e32 v6, v2
	v_mov_b32_e32 v7, v2
	v_mov_b32_e32 v8, v2
	v_mov_b32_e32 v9, v2
	v_mov_b32_e32 v14, v2
	v_mov_b32_e32 v15, v2
	v_mov_b32_e32 v16, v2
	v_mov_b32_e32 v17, v2
	v_mov_b32_e32 v22, v2
	v_mov_b32_e32 v23, v2
	v_mov_b32_e32 v24, v2
	v_mov_b32_e32 v25, v2
	v_mov_b32_e32 v30, v2
	v_mov_b32_e32 v31, v2
	v_mov_b32_e32 v32, v2
	v_mov_b32_e32 v33, v2
	v_mov_b32_e32 v38, v2
	v_mov_b32_e32 v39, v2
	v_mov_b32_e32 v40, v2
	v_mov_b32_e32 v41, v2
	v_mov_b32_e32 v46, v2
	v_mov_b32_e32 v47, v2
	v_mov_b32_e32 v48, v2
	v_mov_b32_e32 v49, v2
	v_mov_b32_e32 v54, v2
	v_mov_b32_e32 v55, v2
	v_mov_b32_e32 v56, v2
	v_mov_b32_e32 v57, v2
	v_mov_b32_e32 v10, v2
	v_mov_b32_e32 v11, v2
	v_mov_b32_e32 v12, v2
	v_mov_b32_e32 v13, v2
	v_mov_b32_e32 v18, v2
	v_mov_b32_e32 v19, v2
	v_mov_b32_e32 v20, v2
	v_mov_b32_e32 v21, v2
	v_mov_b32_e32 v26, v2
	v_mov_b32_e32 v27, v2
	v_mov_b32_e32 v28, v2
	v_mov_b32_e32 v29, v2
	v_mov_b32_e32 v34, v2
	v_mov_b32_e32 v35, v2
	v_mov_b32_e32 v36, v2
	v_mov_b32_e32 v37, v2
	v_mov_b32_e32 v42, v2
	v_mov_b32_e32 v43, v2
	v_mov_b32_e32 v44, v2
	v_mov_b32_e32 v45, v2
	v_mov_b32_e32 v50, v2
	v_mov_b32_e32 v51, v2
	v_mov_b32_e32 v52, v2
	v_mov_b32_e32 v53, v2
	v_mov_b32_e32 v58, v2
	v_mov_b32_e32 v59, v2
	v_mov_b32_e32 v60, v2
	v_mov_b32_e32 v61, v2
	v_mov_b32_e32 v62, v2
	v_mov_b32_e32 v63, v2
	v_mov_b32_e32 v64, v2
	v_mov_b32_e32 v65, v2
	v_mov_b32_e32 v66, v2
	v_mov_b32_e32 v67, v2
	v_mov_b32_e32 v68, v2
	v_mov_b32_e32 v69, v2
	v_mov_b32_e32 v70, v2
	v_mov_b32_e32 v71, v2
	v_mov_b32_e32 v72, v2
	v_mov_b32_e32 v73, v2
	v_mov_b32_e32 v78, v2
	v_mov_b32_e32 v79, v2
	v_mov_b32_e32 v80, v2
	v_mov_b32_e32 v81, v2
	v_mov_b32_e32 v86, v2
	v_mov_b32_e32 v87, v2
	v_mov_b32_e32 v88, v2
	v_mov_b32_e32 v89, v2
	v_mov_b32_e32 v94, v2
	v_mov_b32_e32 v95, v2
	v_mov_b32_e32 v96, v2
	v_mov_b32_e32 v97, v2
	v_mov_b32_e32 v102, v2
	v_mov_b32_e32 v103, v2
	v_mov_b32_e32 v104, v2
	v_mov_b32_e32 v105, v2
	v_mov_b32_e32 v110, v2
	v_mov_b32_e32 v111, v2
	v_mov_b32_e32 v112, v2
	v_mov_b32_e32 v113, v2
	v_mov_b32_e32 v118, v2
	v_mov_b32_e32 v119, v2
	v_mov_b32_e32 v120, v2
	v_mov_b32_e32 v121, v2
	v_mov_b32_e32 v74, v2
	v_mov_b32_e32 v75, v2
	v_mov_b32_e32 v76, v2
	v_mov_b32_e32 v77, v2
	v_mov_b32_e32 v82, v2
	v_mov_b32_e32 v83, v2
	v_mov_b32_e32 v84, v2
	v_mov_b32_e32 v85, v2
	v_mov_b32_e32 v90, v2
	v_mov_b32_e32 v91, v2
	v_mov_b32_e32 v92, v2
	v_mov_b32_e32 v93, v2
	v_mov_b32_e32 v98, v2
	v_mov_b32_e32 v99, v2
	v_mov_b32_e32 v100, v2
	v_mov_b32_e32 v101, v2
	v_mov_b32_e32 v106, v2
	v_mov_b32_e32 v107, v2
	v_mov_b32_e32 v108, v2
	v_mov_b32_e32 v109, v2
	v_mov_b32_e32 v114, v2
	v_mov_b32_e32 v115, v2
	v_mov_b32_e32 v116, v2
	v_mov_b32_e32 v117, v2
	v_mov_b32_e32 v122, v2
	v_mov_b32_e32 v123, v2
	v_mov_b32_e32 v124, v2
	v_mov_b32_e32 v125, v2
	v_mov_b32_e32 v126, v2
	v_mov_b32_e32 v127, v2
	v_mov_b32_e32 v128, v2
	v_mov_b32_e32 v129, v2
	s_andn2_b64 vcc, exec, s[6:7]
	s_cbranch_vccnz .LBB0_1008
	s_branch .LBB0_1009

.LBB0_1108:
	s_add_i32 s71, 0, 0x10000
	s_add_i32 s38, 0, 0x14000
	v_add_u32_e32 v214, s71, v133
	v_add_u32_e32 v215, s38, v133
	ds_read_b128 v[2:5], v214
	ds_read_b128 v[6:9], v214 offset:1024
	ds_read_b128 v[10:13], v214 offset:2048
	ds_read_b128 v[14:17], v214 offset:3072
	ds_read_b128 v[18:21], v215
	ds_read_b128 v[22:25], v215 offset:1024
	ds_read_b128 v[26:29], v215 offset:2048
	ds_read_b128 v[30:33], v215 offset:3072
	s_add_u32 s36, s20, 0xb0080
	s_addc_u32 s37, s21, 0
	s_add_i32 s73, s22, 0xc000
	v_lshl_add_u64 v[66:67], s[36:37], 0, v[0:1]
	s_mov_b32 m0, s73
	ds_read_b128 v[34:37], v135
	ds_read_b128 v[38:41], v135 offset:1024
	ds_read_b128 v[42:45], v135 offset:2048
	ds_read_b128 v[46:49], v135 offset:3072
	ds_read_b128 v[50:53], v135 offset:4096
	ds_read_b128 v[54:57], v135 offset:5120
	ds_read_b128 v[58:61], v135 offset:6144
	ds_read_b128 v[62:65], v135 offset:7168
	global_load_lds_dwordx4 v[66:67], off
	v_lshl_add_u64 v[66:67], s[36:37], 0, v[130:131]
	s_add_i32 s36, s22, 0xe000
	s_mov_b32 m0, s36
	s_nop 0
	global_load_lds_dwordx4 v[66:67], off
	s_waitcnt vmcnt(8)
	s_waitcnt lgkmcnt(0)
	s_barrier
	s_setprio 1
	s_waitcnt lgkmcnt(0)
	v_mfma_f32_16x16x32_bf16 v[66:69], v[2:5], v[34:37], 0
	v_mfma_f32_16x16x32_bf16 v[70:73], v[10:13], v[34:37], 0
	v_mfma_f32_16x16x32_bf16 v[74:77], v[2:5], v[42:45], 0
	v_mfma_f32_16x16x32_bf16 v[78:81], v[10:13], v[42:45], 0
	v_mfma_f32_16x16x32_bf16 v[82:85], v[2:5], v[50:53], 0
	v_mfma_f32_16x16x32_bf16 v[86:89], v[10:13], v[50:53], 0
	v_mfma_f32_16x16x32_bf16 v[90:93], v[2:5], v[58:61], 0
	v_mfma_f32_16x16x32_bf16 v[94:97], v[10:13], v[58:61], 0
	v_mfma_f32_16x16x32_bf16 v[66:69], v[6:9], v[38:41], v[66:69]
	v_mfma_f32_16x16x32_bf16 v[70:73], v[14:17], v[38:41], v[70:73]
	v_mfma_f32_16x16x32_bf16 v[74:77], v[6:9], v[46:49], v[74:77]
	v_mfma_f32_16x16x32_bf16 v[78:81], v[14:17], v[46:49], v[78:81]
	v_mfma_f32_16x16x32_bf16 v[82:85], v[6:9], v[54:57], v[82:85]
	v_mfma_f32_16x16x32_bf16 v[86:89], v[14:17], v[54:57], v[86:89]
	v_mfma_f32_16x16x32_bf16 v[90:93], v[6:9], v[62:65], v[90:93]
	v_mfma_f32_16x16x32_bf16 v[94:97], v[14:17], v[62:65], v[94:97]
	v_mfma_f32_16x16x32_bf16 v[98:101], v[18:21], v[34:37], 0
	v_mfma_f32_16x16x32_bf16 v[34:37], v[26:29], v[34:37], 0
	v_mfma_f32_16x16x32_bf16 v[98:101], v[22:25], v[38:41], v[98:101]
	v_mfma_f32_16x16x32_bf16 v[34:37], v[30:33], v[38:41], v[34:37]
	v_mfma_f32_16x16x32_bf16 v[38:41], v[18:21], v[42:45], 0
	v_mfma_f32_16x16x32_bf16 v[42:45], v[26:29], v[42:45], 0
	v_mfma_f32_16x16x32_bf16 v[38:41], v[22:25], v[46:49], v[38:41]
	v_mfma_f32_16x16x32_bf16 v[42:45], v[30:33], v[46:49], v[42:45]
	v_mfma_f32_16x16x32_bf16 v[46:49], v[18:21], v[50:53], 0
	v_mfma_f32_16x16x32_bf16 v[50:53], v[26:29], v[50:53], 0
	v_mfma_f32_16x16x32_bf16 v[46:49], v[22:25], v[54:57], v[46:49]
	v_mfma_f32_16x16x32_bf16 v[50:53], v[30:33], v[54:57], v[50:53]
	v_mfma_f32_16x16x32_bf16 v[54:57], v[18:21], v[58:61], 0
	v_mfma_f32_16x16x32_bf16 v[58:61], v[26:29], v[58:61], 0
	v_mfma_f32_16x16x32_bf16 v[54:57], v[22:25], v[62:65], v[54:57]
	v_mfma_f32_16x16x32_bf16 v[58:61], v[30:33], v[62:65], v[58:61]
	s_setprio 0
	s_barrier
	s_add_i32 s71, s71, s12
	v_lshl_add_u64 v[200:201], s[18:19], 0, v[0:1]
	s_mov_b64 s[76:77], 0x100
	s_add_i32 s37, s71, 0x2000
	v_lshl_add_u64 v[136:137], v[200:201], 0, s[76:77]
	s_mov_b32 m0, s71
	v_lshl_add_u64 v[202:203], s[18:19], 0, v[130:131]
	s_add_u32 s74, s18, 0xb0100
	ds_read_b128 v[62:65], v135 offset:16384
	ds_read_b128 v[102:105], v135 offset:17408
	ds_read_b128 v[106:109], v135 offset:18432
	ds_read_b128 v[110:113], v135 offset:19456
	ds_read_b128 v[114:117], v135 offset:20480
	ds_read_b128 v[118:121], v135 offset:21504
	ds_read_b128 v[122:125], v135 offset:22528
	ds_read_b128 v[126:129], v135 offset:23552
	global_load_lds_dwordx4 v[136:137], off
	v_lshl_add_u64 v[136:137], v[202:203], 0, s[76:77]
	s_mov_b32 m0, s37
	s_addc_u32 s75, s19, 0
	s_add_i32 s38, s38, s12
	global_load_lds_dwordx4 v[136:137], off
	v_lshl_add_u64 v[136:137], s[74:75], 0, v[0:1]
	s_mov_b32 m0, s38
	s_add_i32 s39, s38, 0x2000
	global_load_lds_dwordx4 v[136:137], off
	v_lshl_add_u64 v[136:137], s[74:75], 0, v[130:131]
	s_mov_b32 m0, s39
	v_lshl_add_u64 v[204:205], s[20:21], 0, v[0:1]
	global_load_lds_dwordx4 v[136:137], off
	v_lshl_add_u64 v[136:137], v[204:205], 0, s[76:77]
	s_mov_b32 m0, s22
	v_lshl_add_u64 v[206:207], s[20:21], 0, v[130:131]
	global_load_lds_dwordx4 v[136:137], off
	v_lshl_add_u64 v[136:137], v[206:207], 0, s[76:77]
	s_mov_b32 m0, s23
	s_nop 0
	global_load_lds_dwordx4 v[136:137], off
	s_waitcnt vmcnt(8)
	s_waitcnt lgkmcnt(0)
	s_barrier
	s_setprio 1
	s_waitcnt lgkmcnt(0)
	v_mfma_f32_16x16x32_bf16 v[136:139], v[2:5], v[62:65], 0
	v_mfma_f32_16x16x32_bf16 v[144:147], v[2:5], v[106:109], 0
	v_mfma_f32_16x16x32_bf16 v[152:155], v[2:5], v[114:117], 0
	v_mfma_f32_16x16x32_bf16 v[2:5], v[2:5], v[122:125], 0
	v_mfma_f32_16x16x32_bf16 v[136:139], v[6:9], v[102:105], v[136:139]
	v_mfma_f32_16x16x32_bf16 v[144:147], v[6:9], v[110:113], v[144:147]
	v_mfma_f32_16x16x32_bf16 v[152:155], v[6:9], v[118:121], v[152:155]
	v_mfma_f32_16x16x32_bf16 v[2:5], v[6:9], v[126:129], v[2:5]
	v_mfma_f32_16x16x32_bf16 v[6:9], v[10:13], v[122:125], 0
	v_mfma_f32_16x16x32_bf16 v[140:143], v[10:13], v[62:65], 0
	v_mfma_f32_16x16x32_bf16 v[148:151], v[10:13], v[106:109], 0
	v_mfma_f32_16x16x32_bf16 v[156:159], v[10:13], v[114:117], 0
	v_mfma_f32_16x16x32_bf16 v[6:9], v[14:17], v[126:129], v[6:9]
	v_mfma_f32_16x16x32_bf16 v[140:143], v[14:17], v[102:105], v[140:143]
	v_mfma_f32_16x16x32_bf16 v[148:151], v[14:17], v[110:113], v[148:151]
	v_mfma_f32_16x16x32_bf16 v[156:159], v[14:17], v[118:121], v[156:159]
	v_mfma_f32_16x16x32_bf16 v[10:13], v[18:21], v[62:65], 0
	v_mfma_f32_16x16x32_bf16 v[14:17], v[26:29], v[62:65], 0
	v_mfma_f32_16x16x32_bf16 v[10:13], v[22:25], v[102:105], v[10:13]
	v_mfma_f32_16x16x32_bf16 v[14:17], v[30:33], v[102:105], v[14:17]
	v_mfma_f32_16x16x32_bf16 v[62:65], v[18:21], v[106:109], 0
	v_mfma_f32_16x16x32_bf16 v[102:105], v[26:29], v[106:109], 0
	v_mfma_f32_16x16x32_bf16 v[106:109], v[18:21], v[114:117], 0
	v_mfma_f32_16x16x32_bf16 v[18:21], v[18:21], v[122:125], 0
	v_mfma_f32_16x16x32_bf16 v[62:65], v[22:25], v[110:113], v[62:65]
	v_mfma_f32_16x16x32_bf16 v[102:105], v[30:33], v[110:113], v[102:105]
	v_mfma_f32_16x16x32_bf16 v[106:109], v[22:25], v[118:121], v[106:109]
	v_mfma_f32_16x16x32_bf16 v[110:113], v[26:29], v[114:117], 0
	v_mfma_f32_16x16x32_bf16 v[18:21], v[22:25], v[126:129], v[18:21]
	v_mfma_f32_16x16x32_bf16 v[22:25], v[26:29], v[122:125], 0
	v_mfma_f32_16x16x32_bf16 v[110:113], v[30:33], v[118:121], v[110:113]
	v_mfma_f32_16x16x32_bf16 v[22:25], v[30:33], v[126:129], v[22:25]
	s_setprio 0
	s_barrier
	s_add_i32 s72, 0, 0x18000
	s_add_i32 s78, 0, 0x1c000
	v_add_u32_e32 v218, s72, v133
	v_add_u32_e32 v230, s78, v133
	ds_read_b128 v[26:29], v218
	ds_read_b128 v[30:33], v218 offset:1024
	ds_read_b128 v[114:117], v218 offset:2048
	ds_read_b128 v[118:121], v218 offset:3072
	ds_read_b128 v[122:125], v230
	ds_read_b128 v[126:129], v230 offset:1024
	ds_read_b128 v[160:163], v230 offset:2048
	ds_read_b128 v[164:167], v230 offset:3072
	s_add_u32 s74, s20, 0xb0100
	s_addc_u32 s75, s21, 0
	s_mov_b32 m0, s24
	v_lshl_add_u64 v[208:209], s[74:75], 0, v[0:1]
	ds_read_b128 v[168:171], v135 offset:32768
	ds_read_b128 v[172:175], v135 offset:33792
	ds_read_b128 v[176:179], v135 offset:34816
	ds_read_b128 v[180:183], v135 offset:35840
	ds_read_b128 v[184:187], v135 offset:36864
	ds_read_b128 v[188:191], v135 offset:37888
	ds_read_b128 v[192:195], v135 offset:38912
	ds_read_b128 v[196:199], v135 offset:39936
	global_load_lds_dwordx4 v[208:209], off
	v_lshl_add_u64 v[208:209], s[74:75], 0, v[130:131]
	s_mov_b32 m0, s25
	s_nop 0
	global_load_lds_dwordx4 v[208:209], off
	s_waitcnt vmcnt(8)
	s_waitcnt lgkmcnt(0)
	s_barrier
	s_setprio 1
	s_waitcnt lgkmcnt(0)
	v_mfma_f32_16x16x32_bf16 v[66:69], v[26:29], v[168:171], v[66:69]
	v_mfma_f32_16x16x32_bf16 v[70:73], v[114:117], v[168:171], v[70:73]
	v_mfma_f32_16x16x32_bf16 v[74:77], v[26:29], v[176:179], v[74:77]
	v_mfma_f32_16x16x32_bf16 v[78:81], v[114:117], v[176:179], v[78:81]
	v_mfma_f32_16x16x32_bf16 v[82:85], v[26:29], v[184:187], v[82:85]
	v_mfma_f32_16x16x32_bf16 v[86:89], v[114:117], v[184:187], v[86:89]
	v_mfma_f32_16x16x32_bf16 v[90:93], v[26:29], v[192:195], v[90:93]
	v_mfma_f32_16x16x32_bf16 v[94:97], v[114:117], v[192:195], v[94:97]
	v_mfma_f32_16x16x32_bf16 v[66:69], v[30:33], v[172:175], v[66:69]
	v_mfma_f32_16x16x32_bf16 v[70:73], v[118:121], v[172:175], v[70:73]
	v_mfma_f32_16x16x32_bf16 v[74:77], v[30:33], v[180:183], v[74:77]
	v_mfma_f32_16x16x32_bf16 v[78:81], v[118:121], v[180:183], v[78:81]
	v_mfma_f32_16x16x32_bf16 v[82:85], v[30:33], v[188:191], v[82:85]
	v_mfma_f32_16x16x32_bf16 v[86:89], v[118:121], v[188:191], v[86:89]
	v_mfma_f32_16x16x32_bf16 v[90:93], v[30:33], v[196:199], v[90:93]
	v_mfma_f32_16x16x32_bf16 v[94:97], v[118:121], v[196:199], v[94:97]
	v_mfma_f32_16x16x32_bf16 v[98:101], v[122:125], v[168:171], v[98:101]
	v_mfma_f32_16x16x32_bf16 v[34:37], v[160:163], v[168:171], v[34:37]
	v_mfma_f32_16x16x32_bf16 v[38:41], v[122:125], v[176:179], v[38:41]
	v_mfma_f32_16x16x32_bf16 v[42:45], v[160:163], v[176:179], v[42:45]
	v_mfma_f32_16x16x32_bf16 v[46:49], v[122:125], v[184:187], v[46:49]
	v_mfma_f32_16x16x32_bf16 v[50:53], v[160:163], v[184:187], v[50:53]
	v_mfma_f32_16x16x32_bf16 v[54:57], v[122:125], v[192:195], v[54:57]
	v_mfma_f32_16x16x32_bf16 v[58:61], v[160:163], v[192:195], v[58:61]
	v_mfma_f32_16x16x32_bf16 v[98:101], v[126:129], v[172:175], v[98:101]
	v_mfma_f32_16x16x32_bf16 v[34:37], v[164:167], v[172:175], v[34:37]
	v_mfma_f32_16x16x32_bf16 v[38:41], v[126:129], v[180:183], v[38:41]
	v_mfma_f32_16x16x32_bf16 v[42:45], v[164:167], v[180:183], v[42:45]
	v_mfma_f32_16x16x32_bf16 v[46:49], v[126:129], v[188:191], v[46:49]
	v_mfma_f32_16x16x32_bf16 v[50:53], v[164:167], v[188:191], v[50:53]
	v_mfma_f32_16x16x32_bf16 v[54:57], v[126:129], v[196:199], v[54:57]
	v_mfma_f32_16x16x32_bf16 v[58:61], v[164:167], v[196:199], v[58:61]
	s_setprio 0
	s_barrier
	s_add_i32 s74, s72, s12
	s_mov_b64 s[80:81], 0x180
	s_add_i32 s72, s74, 0x2000
	v_lshl_add_u64 v[200:201], v[200:201], 0, s[80:81]
	s_mov_b32 m0, s74
	s_add_u32 s76, s18, 0xb0180
	ds_read_b128 v[168:171], v135 offset:49152
	ds_read_b128 v[172:175], v135 offset:50176
	ds_read_b128 v[176:179], v135 offset:51200
	ds_read_b128 v[180:183], v135 offset:52224
	ds_read_b128 v[184:187], v135 offset:53248
	ds_read_b128 v[188:191], v135 offset:54272
	ds_read_b128 v[192:195], v135 offset:55296
	ds_read_b128 v[196:199], v135 offset:56320
	global_load_lds_dwordx4 v[200:201], off
	v_lshl_add_u64 v[200:201], v[202:203], 0, s[80:81]
	s_mov_b32 m0, s72
	s_addc_u32 s77, s19, 0
	s_add_i32 s18, s78, s12
	global_load_lds_dwordx4 v[200:201], off
	v_lshl_add_u64 v[200:201], s[76:77], 0, v[0:1]
	s_mov_b32 m0, s18
	s_add_i32 s19, s18, 0x2000
	global_load_lds_dwordx4 v[200:201], off
	v_lshl_add_u64 v[200:201], s[76:77], 0, v[130:131]
	s_mov_b32 m0, s19
	s_nop 0
	global_load_lds_dwordx4 v[200:201], off
	v_lshl_add_u64 v[200:201], v[204:205], 0, s[80:81]
	s_mov_b32 m0, s26
	s_nop 0
	global_load_lds_dwordx4 v[200:201], off
	v_lshl_add_u64 v[200:201], v[206:207], 0, s[80:81]
	s_mov_b32 m0, s27
	s_nop 0
	global_load_lds_dwordx4 v[200:201], off
	s_waitcnt vmcnt(8)
	s_waitcnt lgkmcnt(0)
	s_barrier
	s_setprio 1
	s_waitcnt lgkmcnt(0)
	v_mfma_f32_16x16x32_bf16 v[2:5], v[26:29], v[192:195], v[2:5]
	v_mfma_f32_16x16x32_bf16 v[6:9], v[114:117], v[192:195], v[6:9]
	v_mfma_f32_16x16x32_bf16 v[136:139], v[26:29], v[168:171], v[136:139]
	v_mfma_f32_16x16x32_bf16 v[140:143], v[114:117], v[168:171], v[140:143]
	v_mfma_f32_16x16x32_bf16 v[144:147], v[26:29], v[176:179], v[144:147]
	v_mfma_f32_16x16x32_bf16 v[148:151], v[114:117], v[176:179], v[148:151]
	v_mfma_f32_16x16x32_bf16 v[152:155], v[26:29], v[184:187], v[152:155]
	v_mfma_f32_16x16x32_bf16 v[156:159], v[114:117], v[184:187], v[156:159]
	v_mfma_f32_16x16x32_bf16 v[2:5], v[30:33], v[196:199], v[2:5]
	v_mfma_f32_16x16x32_bf16 v[6:9], v[118:121], v[196:199], v[6:9]
	v_mfma_f32_16x16x32_bf16 v[136:139], v[30:33], v[172:175], v[136:139]
	v_mfma_f32_16x16x32_bf16 v[140:143], v[118:121], v[172:175], v[140:143]
	v_mfma_f32_16x16x32_bf16 v[144:147], v[30:33], v[180:183], v[144:147]
	v_mfma_f32_16x16x32_bf16 v[148:151], v[118:121], v[180:183], v[148:151]
	v_mfma_f32_16x16x32_bf16 v[152:155], v[30:33], v[188:191], v[152:155]
	v_mfma_f32_16x16x32_bf16 v[156:159], v[118:121], v[188:191], v[156:159]
	v_mfma_f32_16x16x32_bf16 v[10:13], v[122:125], v[168:171], v[10:13]
	v_mfma_f32_16x16x32_bf16 v[14:17], v[160:163], v[168:171], v[14:17]
	v_mfma_f32_16x16x32_bf16 v[26:29], v[122:125], v[176:179], v[62:65]
	v_mfma_f32_16x16x32_bf16 v[30:33], v[160:163], v[176:179], v[102:105]
	v_mfma_f32_16x16x32_bf16 v[62:65], v[122:125], v[184:187], v[106:109]
	v_mfma_f32_16x16x32_bf16 v[102:105], v[160:163], v[184:187], v[110:113]
	v_mfma_f32_16x16x32_bf16 v[18:21], v[122:125], v[192:195], v[18:21]
	v_mfma_f32_16x16x32_bf16 v[22:25], v[160:163], v[192:195], v[22:25]
	v_mfma_f32_16x16x32_bf16 v[10:13], v[126:129], v[172:175], v[10:13]
	v_mfma_f32_16x16x32_bf16 v[14:17], v[164:167], v[172:175], v[14:17]
	v_mfma_f32_16x16x32_bf16 v[26:29], v[126:129], v[180:183], v[26:29]
	v_mfma_f32_16x16x32_bf16 v[30:33], v[164:167], v[180:183], v[30:33]
	v_mfma_f32_16x16x32_bf16 v[62:65], v[126:129], v[188:191], v[62:65]
	v_mfma_f32_16x16x32_bf16 v[102:105], v[164:167], v[188:191], v[102:105]
	v_mfma_f32_16x16x32_bf16 v[18:21], v[126:129], v[196:199], v[18:21]
	v_mfma_f32_16x16x32_bf16 v[22:25], v[164:167], v[196:199], v[22:25]
	s_setprio 0
	s_barrier
	ds_read_b128 v[106:109], v214
	ds_read_b128 v[110:113], v214 offset:1024
	ds_read_b128 v[114:117], v214 offset:2048
	ds_read_b128 v[118:121], v214 offset:3072
	ds_read_b128 v[122:125], v215
	ds_read_b128 v[126:129], v215 offset:1024
	ds_read_b128 v[160:163], v215 offset:2048
	ds_read_b128 v[164:167], v215 offset:3072
	s_add_u32 s20, s20, 0xb0180
	s_addc_u32 s21, s21, 0
	s_mov_b32 m0, s73
	v_lshl_add_u64 v[200:201], s[20:21], 0, v[0:1]
	ds_read_b128 v[168:171], v135
	ds_read_b128 v[172:175], v135 offset:1024
	ds_read_b128 v[176:179], v135 offset:2048
	ds_read_b128 v[180:183], v135 offset:3072
	ds_read_b128 v[184:187], v135 offset:4096
	ds_read_b128 v[188:191], v135 offset:5120
	ds_read_b128 v[192:195], v135 offset:6144
	ds_read_b128 v[196:199], v135 offset:7168
	global_load_lds_dwordx4 v[200:201], off
	v_lshl_add_u64 v[200:201], s[20:21], 0, v[130:131]
	s_mov_b32 m0, s36
	s_nop 0
	global_load_lds_dwordx4 v[200:201], off
	s_waitcnt vmcnt(8)
	s_waitcnt lgkmcnt(0)
	s_barrier
	s_setprio 1
	s_waitcnt lgkmcnt(0)
	v_mfma_f32_16x16x32_bf16 v[66:69], v[106:109], v[168:171], v[66:69]
	v_mfma_f32_16x16x32_bf16 v[70:73], v[114:117], v[168:171], v[70:73]
	v_mfma_f32_16x16x32_bf16 v[74:77], v[106:109], v[176:179], v[74:77]
	v_mfma_f32_16x16x32_bf16 v[78:81], v[114:117], v[176:179], v[78:81]
	v_mfma_f32_16x16x32_bf16 v[82:85], v[106:109], v[184:187], v[82:85]
	v_mfma_f32_16x16x32_bf16 v[86:89], v[114:117], v[184:187], v[86:89]
	v_mfma_f32_16x16x32_bf16 v[90:93], v[106:109], v[192:195], v[90:93]
	v_mfma_f32_16x16x32_bf16 v[94:97], v[114:117], v[192:195], v[94:97]
	v_mfma_f32_16x16x32_bf16 v[66:69], v[110:113], v[172:175], v[66:69]
	v_mfma_f32_16x16x32_bf16 v[70:73], v[118:121], v[172:175], v[70:73]
	v_mfma_f32_16x16x32_bf16 v[74:77], v[110:113], v[180:183], v[74:77]
	v_mfma_f32_16x16x32_bf16 v[78:81], v[118:121], v[180:183], v[78:81]
	v_mfma_f32_16x16x32_bf16 v[82:85], v[110:113], v[188:191], v[82:85]
	v_mfma_f32_16x16x32_bf16 v[86:89], v[118:121], v[188:191], v[86:89]
	v_mfma_f32_16x16x32_bf16 v[90:93], v[110:113], v[196:199], v[90:93]
	v_mfma_f32_16x16x32_bf16 v[94:97], v[118:121], v[196:199], v[94:97]
	v_mfma_f32_16x16x32_bf16 v[34:37], v[160:163], v[168:171], v[34:37]
	v_mfma_f32_16x16x32_bf16 v[98:101], v[122:125], v[168:171], v[98:101]
	v_mfma_f32_16x16x32_bf16 v[168:171], v[164:167], v[172:175], v[34:37]
	v_mfma_f32_16x16x32_bf16 v[34:37], v[122:125], v[176:179], v[38:41]
	v_mfma_f32_16x16x32_bf16 v[98:101], v[126:129], v[172:175], v[98:101]
	v_mfma_f32_16x16x32_bf16 v[172:175], v[126:129], v[180:183], v[34:37]
	v_mfma_f32_16x16x32_bf16 v[34:37], v[160:163], v[176:179], v[42:45]
	v_mfma_f32_16x16x32_bf16 v[42:45], v[164:167], v[180:183], v[34:37]
	v_mfma_f32_16x16x32_bf16 v[34:37], v[122:125], v[184:187], v[46:49]
	v_mfma_f32_16x16x32_bf16 v[46:49], v[126:129], v[188:191], v[34:37]
	v_mfma_f32_16x16x32_bf16 v[34:37], v[160:163], v[184:187], v[50:53]
	v_mfma_f32_16x16x32_bf16 v[50:53], v[164:167], v[188:191], v[34:37]
	v_mfma_f32_16x16x32_bf16 v[34:37], v[122:125], v[192:195], v[54:57]
	v_mfma_f32_16x16x32_bf16 v[54:57], v[126:129], v[196:199], v[34:37]
	v_mfma_f32_16x16x32_bf16 v[34:37], v[160:163], v[192:195], v[58:61]
	v_mfma_f32_16x16x32_bf16 v[176:179], v[164:167], v[196:199], v[34:37]
	s_setprio 0
	s_barrier
	s_mov_b32 m0, s71
	v_lshl_add_u64 v[208:209], s[14:15], 0, v[0:1]
	s_add_u32 s20, s14, 0xb0000
	s_nop 1
	ds_read_b128 v[34:37], v135 offset:16384
	ds_read_b128 v[38:41], v135 offset:17408
	ds_read_b128 v[58:61], v135 offset:18432
	ds_read_b128 v[180:183], v135 offset:19456
	ds_read_b128 v[184:187], v135 offset:20480
	ds_read_b128 v[188:191], v135 offset:21504
	ds_read_b128 v[192:195], v135 offset:22528
	ds_read_b128 v[196:199], v135 offset:23552
	global_load_lds_dwordx4 v[208:209], off
	v_lshl_add_u64 v[226:227], s[14:15], 0, v[130:131]
	s_mov_b32 m0, s37
	s_addc_u32 s21, s15, 0
	global_load_lds_dwordx4 v[226:227], off
	v_lshl_add_u64 v[200:201], s[20:21], 0, v[0:1]
	s_mov_b32 m0, s38
	v_lshl_add_u64 v[228:229], s[10:11], 0, v[0:1]
	global_load_lds_dwordx4 v[200:201], off
	v_lshl_add_u64 v[200:201], s[20:21], 0, v[130:131]
	s_mov_b32 m0, s39
	v_lshl_add_u64 v[246:247], s[10:11], 0, v[130:131]
	global_load_lds_dwordx4 v[200:201], off
	s_mov_b32 m0, s22
	s_nop 0
	global_load_lds_dwordx4 v[228:229], off
	s_mov_b32 m0, s23
	s_nop 0
	global_load_lds_dwordx4 v[246:247], off
	s_waitcnt vmcnt(8)
	s_waitcnt lgkmcnt(0)
	s_barrier
	s_setprio 1
	s_waitcnt lgkmcnt(0)
	v_mfma_f32_16x16x32_bf16 v[136:139], v[106:109], v[34:37], v[136:139]
	v_mfma_f32_16x16x32_bf16 v[144:147], v[106:109], v[58:61], v[144:147]
	v_mfma_f32_16x16x32_bf16 v[152:155], v[106:109], v[184:187], v[152:155]
	v_mfma_f32_16x16x32_bf16 v[2:5], v[106:109], v[192:195], v[2:5]
	v_mfma_f32_16x16x32_bf16 v[136:139], v[110:113], v[38:41], v[136:139]
	v_mfma_f32_16x16x32_bf16 v[144:147], v[110:113], v[180:183], v[144:147]
	v_mfma_f32_16x16x32_bf16 v[152:155], v[110:113], v[188:191], v[152:155]
	v_mfma_f32_16x16x32_bf16 v[110:113], v[110:113], v[196:199], v[2:5]
	v_mfma_f32_16x16x32_bf16 v[2:5], v[114:117], v[192:195], v[6:9]
	v_mfma_f32_16x16x32_bf16 v[140:143], v[114:117], v[34:37], v[140:143]
	v_mfma_f32_16x16x32_bf16 v[148:151], v[114:117], v[58:61], v[148:151]
	v_mfma_f32_16x16x32_bf16 v[156:159], v[114:117], v[184:187], v[156:159]
	v_mfma_f32_16x16x32_bf16 v[114:117], v[118:121], v[196:199], v[2:5]
	v_mfma_f32_16x16x32_bf16 v[140:143], v[118:121], v[38:41], v[140:143]
	v_mfma_f32_16x16x32_bf16 v[148:151], v[118:121], v[180:183], v[148:151]
	v_mfma_f32_16x16x32_bf16 v[156:159], v[118:121], v[188:191], v[156:159]
	v_mfma_f32_16x16x32_bf16 v[2:5], v[122:125], v[34:37], v[10:13]
	v_mfma_f32_16x16x32_bf16 v[118:121], v[126:129], v[38:41], v[2:5]
	v_mfma_f32_16x16x32_bf16 v[2:5], v[160:163], v[34:37], v[14:17]
	v_mfma_f32_16x16x32_bf16 v[200:203], v[164:167], v[38:41], v[2:5]
	v_mfma_f32_16x16x32_bf16 v[2:5], v[122:125], v[58:61], v[26:29]
	v_mfma_f32_16x16x32_bf16 v[204:207], v[126:129], v[180:183], v[2:5]
	v_mfma_f32_16x16x32_bf16 v[2:5], v[160:163], v[58:61], v[30:33]
	v_mfma_f32_16x16x32_bf16 v[180:183], v[164:167], v[180:183], v[2:5]
	v_mfma_f32_16x16x32_bf16 v[2:5], v[122:125], v[184:187], v[62:65]
	v_mfma_f32_16x16x32_bf16 v[214:217], v[126:129], v[188:191], v[2:5]
	v_mfma_f32_16x16x32_bf16 v[2:5], v[160:163], v[184:187], v[102:105]
	v_mfma_f32_16x16x32_bf16 v[184:187], v[164:167], v[188:191], v[2:5]
	v_mfma_f32_16x16x32_bf16 v[2:5], v[122:125], v[192:195], v[18:21]
	v_mfma_f32_16x16x32_bf16 v[188:191], v[126:129], v[196:199], v[2:5]
	v_mfma_f32_16x16x32_bf16 v[2:5], v[160:163], v[192:195], v[22:25]
	v_mfma_f32_16x16x32_bf16 v[160:163], v[164:167], v[196:199], v[2:5]
	s_setprio 0
	s_barrier
	ds_read_b128 v[102:105], v218
	ds_read_b128 v[122:125], v218 offset:1024
	ds_read_b128 v[126:129], v218 offset:2048
	ds_read_b128 v[164:167], v218 offset:3072
	ds_read_b128 v[192:195], v230
	ds_read_b128 v[196:199], v230 offset:1024
	ds_read_b128 v[218:221], v230 offset:2048
	ds_read_b128 v[230:233], v230 offset:3072
	s_add_u32 s20, s10, 0xb0000
	s_addc_u32 s21, s11, 0
	s_mov_b32 m0, s24
	v_lshl_add_u64 v[2:3], s[20:21], 0, v[0:1]
	ds_read_b128 v[26:29], v135 offset:32768
	ds_read_b128 v[30:33], v135 offset:33792
	ds_read_b128 v[62:65], v135 offset:34816
	ds_read_b128 v[106:109], v135 offset:35840
	ds_read_b128 v[234:237], v135 offset:36864
	ds_read_b128 v[238:241], v135 offset:37888
	ds_read_b128 v[242:245], v135 offset:38912
	ds_read_b128 v[248:251], v135 offset:39936
	global_load_lds_dwordx4 v[2:3], off
	v_lshl_add_u64 v[2:3], s[20:21], 0, v[130:131]
	s_mov_b32 m0, s25
	s_nop 0
	global_load_lds_dwordx4 v[2:3], off
	s_waitcnt vmcnt(8)
	s_waitcnt lgkmcnt(0)
	s_barrier
	s_setprio 1
	s_waitcnt lgkmcnt(0)
	v_mfma_f32_16x16x32_bf16 v[2:5], v[102:105], v[26:29], v[66:69]
	v_mfma_f32_16x16x32_bf16 v[34:37], v[122:125], v[30:33], v[2:5]
	v_mfma_f32_16x16x32_bf16 v[2:5], v[126:129], v[26:29], v[70:73]
	v_mfma_f32_16x16x32_bf16 v[38:41], v[164:167], v[30:33], v[2:5]
	v_mfma_f32_16x16x32_bf16 v[2:5], v[102:105], v[62:65], v[74:77]
	v_mfma_f32_16x16x32_bf16 v[18:21], v[122:125], v[106:109], v[2:5]
	v_mfma_f32_16x16x32_bf16 v[2:5], v[126:129], v[62:65], v[78:81]
	v_mfma_f32_16x16x32_bf16 v[22:25], v[164:167], v[106:109], v[2:5]
	v_mfma_f32_16x16x32_bf16 v[2:5], v[102:105], v[234:237], v[82:85]
	v_mfma_f32_16x16x32_bf16 v[10:13], v[122:125], v[238:241], v[2:5]
	v_mfma_f32_16x16x32_bf16 v[2:5], v[126:129], v[234:237], v[86:89]
	v_mfma_f32_16x16x32_bf16 v[14:17], v[164:167], v[238:241], v[2:5]
	v_mfma_f32_16x16x32_bf16 v[2:5], v[102:105], v[242:245], v[90:93]
	v_mfma_f32_16x16x32_bf16 v[6:9], v[126:129], v[242:245], v[94:97]
	v_mfma_f32_16x16x32_bf16 v[2:5], v[122:125], v[248:251], v[2:5]
	v_mfma_f32_16x16x32_bf16 v[6:9], v[164:167], v[248:251], v[6:9]
	v_mfma_f32_16x16x32_bf16 v[58:61], v[192:195], v[26:29], v[98:101]
	v_mfma_f32_16x16x32_bf16 v[26:29], v[218:221], v[26:29], v[168:171]
	v_mfma_f32_16x16x32_bf16 v[78:81], v[230:233], v[30:33], v[26:29]
	v_mfma_f32_16x16x32_bf16 v[26:29], v[192:195], v[62:65], v[172:175]
	v_mfma_f32_16x16x32_bf16 v[70:73], v[196:199], v[30:33], v[58:61]
	v_mfma_f32_16x16x32_bf16 v[58:61], v[196:199], v[106:109], v[26:29]
	v_mfma_f32_16x16x32_bf16 v[26:29], v[218:221], v[62:65], v[42:45]
	v_mfma_f32_16x16x32_bf16 v[62:65], v[230:233], v[106:109], v[26:29]
	v_mfma_f32_16x16x32_bf16 v[26:29], v[192:195], v[234:237], v[46:49]
	v_mfma_f32_16x16x32_bf16 v[42:45], v[196:199], v[238:241], v[26:29]
	v_mfma_f32_16x16x32_bf16 v[26:29], v[218:221], v[234:237], v[50:53]
	v_mfma_f32_16x16x32_bf16 v[46:49], v[230:233], v[238:241], v[26:29]
	v_mfma_f32_16x16x32_bf16 v[26:29], v[192:195], v[242:245], v[54:57]
	v_mfma_f32_16x16x32_bf16 v[30:33], v[218:221], v[242:245], v[176:179]
	v_mfma_f32_16x16x32_bf16 v[26:29], v[196:199], v[248:251], v[26:29]
	v_mfma_f32_16x16x32_bf16 v[30:33], v[230:233], v[248:251], v[30:33]
	s_setprio 0
	s_barrier
	s_mov_b32 m0, s74
	v_lshl_add_u64 v[50:51], v[208:209], 0, s[50:51]
	s_add_u32 s20, s14, 0xb0080
	ds_read_b128 v[82:85], v135 offset:49152
	ds_read_b128 v[90:93], v135 offset:50176
	ds_read_b128 v[168:171], v135 offset:51200
	ds_read_b128 v[172:175], v135 offset:52224
	ds_read_b128 v[176:179], v135 offset:53248
	ds_read_b128 v[234:237], v135 offset:54272
	ds_read_b128 v[238:241], v135 offset:55296
	ds_read_b128 v[242:245], v135 offset:56320
	global_load_lds_dwordx4 v[50:51], off
	v_lshl_add_u64 v[50:51], v[226:227], 0, s[50:51]
	s_mov_b32 m0, s72
	s_addc_u32 s21, s15, 0
	global_load_lds_dwordx4 v[50:51], off
	v_lshl_add_u64 v[50:51], s[20:21], 0, v[0:1]
	s_mov_b32 m0, s18
	s_nop 0
	global_load_lds_dwordx4 v[50:51], off
	v_lshl_add_u64 v[50:51], s[20:21], 0, v[130:131]
	s_mov_b32 m0, s19
	s_nop 0
	global_load_lds_dwordx4 v[50:51], off
	v_lshl_add_u64 v[50:51], v[228:229], 0, s[50:51]
	s_mov_b32 m0, s26
	s_nop 0
	global_load_lds_dwordx4 v[50:51], off
	v_lshl_add_u64 v[50:51], v[246:247], 0, s[50:51]
	s_mov_b32 m0, s27
	s_nop 0
	global_load_lds_dwordx4 v[50:51], off
	s_waitcnt vmcnt(8)
	s_waitcnt lgkmcnt(0)
	s_barrier
	s_setprio 1
	s_waitcnt lgkmcnt(0)
	v_mfma_f32_16x16x32_bf16 v[50:53], v[102:105], v[82:85], v[136:139]
	v_mfma_f32_16x16x32_bf16 v[98:101], v[122:125], v[90:93], v[50:53]
	v_mfma_f32_16x16x32_bf16 v[50:53], v[126:129], v[82:85], v[140:143]
	v_mfma_f32_16x16x32_bf16 v[106:109], v[164:167], v[90:93], v[50:53]
	v_mfma_f32_16x16x32_bf16 v[50:53], v[102:105], v[168:171], v[144:147]
	v_mfma_f32_16x16x32_bf16 v[86:89], v[122:125], v[172:175], v[50:53]
	v_mfma_f32_16x16x32_bf16 v[50:53], v[126:129], v[168:171], v[148:151]
	v_mfma_f32_16x16x32_bf16 v[94:97], v[164:167], v[172:175], v[50:53]
	v_mfma_f32_16x16x32_bf16 v[50:53], v[102:105], v[176:179], v[152:155]
	v_mfma_f32_16x16x32_bf16 v[66:69], v[122:125], v[234:237], v[50:53]
	v_mfma_f32_16x16x32_bf16 v[50:53], v[126:129], v[176:179], v[156:159]
	v_mfma_f32_16x16x32_bf16 v[74:77], v[164:167], v[234:237], v[50:53]
	v_mfma_f32_16x16x32_bf16 v[50:53], v[102:105], v[238:241], v[110:113]
	v_mfma_f32_16x16x32_bf16 v[54:57], v[126:129], v[238:241], v[114:117]
	v_mfma_f32_16x16x32_bf16 v[50:53], v[122:125], v[242:245], v[50:53]
	v_mfma_f32_16x16x32_bf16 v[54:57], v[164:167], v[242:245], v[54:57]
	v_mfma_f32_16x16x32_bf16 v[102:105], v[192:195], v[82:85], v[118:121]
	v_mfma_f32_16x16x32_bf16 v[82:85], v[218:221], v[82:85], v[200:203]
	v_mfma_f32_16x16x32_bf16 v[126:129], v[230:233], v[90:93], v[82:85]
	v_mfma_f32_16x16x32_bf16 v[82:85], v[192:195], v[168:171], v[204:207]
	v_mfma_f32_16x16x32_bf16 v[114:117], v[196:199], v[172:175], v[82:85]
	v_mfma_f32_16x16x32_bf16 v[82:85], v[218:221], v[168:171], v[180:183]
	v_mfma_f32_16x16x32_bf16 v[118:121], v[230:233], v[172:175], v[82:85]
	v_mfma_f32_16x16x32_bf16 v[82:85], v[192:195], v[176:179], v[214:217]
	v_mfma_f32_16x16x32_bf16 v[122:125], v[196:199], v[90:93], v[102:105]
	v_mfma_f32_16x16x32_bf16 v[102:105], v[196:199], v[234:237], v[82:85]
	v_mfma_f32_16x16x32_bf16 v[82:85], v[218:221], v[176:179], v[184:187]
	v_mfma_f32_16x16x32_bf16 v[110:113], v[230:233], v[234:237], v[82:85]
	v_mfma_f32_16x16x32_bf16 v[82:85], v[192:195], v[238:241], v[188:191]
	v_mfma_f32_16x16x32_bf16 v[90:93], v[218:221], v[238:241], v[160:163]
	v_mfma_f32_16x16x32_bf16 v[82:85], v[196:199], v[242:245], v[82:85]
	v_mfma_f32_16x16x32_bf16 v[90:93], v[230:233], v[242:245], v[90:93]
	s_setprio 0
	s_barrier
	s_andn2_b64 vcc, exec, s[4:5]
	s_cbranch_vccnz .LBB0_1110
	s_barrier

.LBB0_1226:
	s_add_u32 s22, s16, s20
	s_addc_u32 s23, s17, s21
	s_add_u32 s22, s22, 0x100
	s_addc_u32 s23, s23, 0
	s_add_u32 s75, s72, s20
	s_addc_u32 s76, s73, s21
	s_add_i32 s77, 0, 0x10000
	s_cmpk_eq_i32 s20, 0x1500
	s_cselect_b32 s25, s19, s23
	s_cselect_b32 s24, s18, s22
	v_add_u32_e32 v147, s77, v131
	s_cselect_b32 s23, s9, s76
	s_cselect_b32 s22, s8, s75
	s_add_i32 s75, 0, 0x14000
	ds_read_b128 v[148:151], v147
	ds_read_b128 v[152:155], v147 offset:1024
	ds_read_b128 v[156:159], v147 offset:2048
	ds_read_b128 v[160:163], v147 offset:3072
	v_add_u32_e32 v147, s75, v131
	ds_read_b128 v[164:167], v147
	ds_read_b128 v[168:171], v147 offset:1024
	ds_read_b128 v[172:175], v147 offset:2048
	ds_read_b128 v[176:179], v147 offset:3072
	v_lshl_add_u64 v[208:209], v[144:145], 0, s[20:21]
	s_add_i32 m0, s29, 0xc000
	ds_read_b128 v[180:183], v146
	ds_read_b128 v[184:187], v146 offset:1024
	ds_read_b128 v[188:191], v146 offset:2048
	ds_read_b128 v[192:195], v146 offset:3072
	ds_read_b128 v[196:199], v146 offset:4096
	ds_read_b128 v[200:203], v146 offset:5120
	ds_read_b128 v[204:207], v146 offset:6144
	ds_read_b128 v[218:221], v146 offset:7168
	global_load_lds_dwordx4 v[208:209], off
	v_lshl_add_u64 v[208:209], v[142:143], 0, s[20:21]
	s_add_i32 m0, s29, 0xe000
	s_nop 0
	global_load_lds_dwordx4 v[208:209], off
	s_waitcnt vmcnt(8)
	s_waitcnt lgkmcnt(0)
	s_barrier
	s_setprio 1
	s_waitcnt lgkmcnt(0)
	v_mfma_f32_16x16x32_bf16 v[126:129], v[148:151], v[180:183], v[126:129]
	v_mfma_f32_16x16x32_bf16 v[122:125], v[156:159], v[180:183], v[122:125]
	v_mfma_f32_16x16x32_bf16 v[114:117], v[148:151], v[188:191], v[114:117]
	v_mfma_f32_16x16x32_bf16 v[106:109], v[156:159], v[188:191], v[106:109]
	v_mfma_f32_16x16x32_bf16 v[98:101], v[148:151], v[196:199], v[98:101]
	v_mfma_f32_16x16x32_bf16 v[90:93], v[156:159], v[196:199], v[90:93]
	v_mfma_f32_16x16x32_bf16 v[82:85], v[148:151], v[204:207], v[82:85]
	v_mfma_f32_16x16x32_bf16 v[74:77], v[156:159], v[204:207], v[74:77]
	v_mfma_f32_16x16x32_bf16 v[126:129], v[152:155], v[184:187], v[126:129]
	v_mfma_f32_16x16x32_bf16 v[122:125], v[160:163], v[184:187], v[122:125]
	v_mfma_f32_16x16x32_bf16 v[114:117], v[152:155], v[192:195], v[114:117]
	v_mfma_f32_16x16x32_bf16 v[106:109], v[160:163], v[192:195], v[106:109]
	v_mfma_f32_16x16x32_bf16 v[98:101], v[152:155], v[200:203], v[98:101]
	v_mfma_f32_16x16x32_bf16 v[90:93], v[160:163], v[200:203], v[90:93]
	v_mfma_f32_16x16x32_bf16 v[82:85], v[152:155], v[218:221], v[82:85]
	v_mfma_f32_16x16x32_bf16 v[74:77], v[160:163], v[218:221], v[74:77]
	v_mfma_f32_16x16x32_bf16 v[118:121], v[164:167], v[180:183], v[118:121]
	v_mfma_f32_16x16x32_bf16 v[110:113], v[172:175], v[180:183], v[110:113]
	v_mfma_f32_16x16x32_bf16 v[102:105], v[164:167], v[188:191], v[102:105]
	v_mfma_f32_16x16x32_bf16 v[94:97], v[172:175], v[188:191], v[94:97]
	v_mfma_f32_16x16x32_bf16 v[86:89], v[164:167], v[196:199], v[86:89]
	v_mfma_f32_16x16x32_bf16 v[78:81], v[172:175], v[196:199], v[78:81]
	v_mfma_f32_16x16x32_bf16 v[70:73], v[164:167], v[204:207], v[70:73]
	v_mfma_f32_16x16x32_bf16 v[66:69], v[172:175], v[204:207], v[66:69]
	v_mfma_f32_16x16x32_bf16 v[118:121], v[168:171], v[184:187], v[118:121]
	v_mfma_f32_16x16x32_bf16 v[110:113], v[176:179], v[184:187], v[110:113]
	v_mfma_f32_16x16x32_bf16 v[102:105], v[168:171], v[192:195], v[102:105]
	v_mfma_f32_16x16x32_bf16 v[94:97], v[176:179], v[192:195], v[94:97]
	v_mfma_f32_16x16x32_bf16 v[86:89], v[168:171], v[200:203], v[86:89]
	v_mfma_f32_16x16x32_bf16 v[78:81], v[176:179], v[200:203], v[78:81]
	v_mfma_f32_16x16x32_bf16 v[70:73], v[168:171], v[218:221], v[70:73]
	v_mfma_f32_16x16x32_bf16 v[66:69], v[176:179], v[218:221], v[66:69]
	s_setprio 0
	s_barrier
	s_add_i32 s76, s77, s28
	v_lshl_add_u64 v[208:209], s[22:23], 0, v[0:1]
	s_mov_b32 m0, s76
	ds_read_b128 v[180:183], v146 offset:16384
	ds_read_b128 v[184:187], v146 offset:17408
	ds_read_b128 v[188:191], v146 offset:18432
	ds_read_b128 v[192:195], v146 offset:19456
	ds_read_b128 v[196:199], v146 offset:20480
	ds_read_b128 v[200:203], v146 offset:21504
	ds_read_b128 v[204:207], v146 offset:22528
	ds_read_b128 v[218:221], v146 offset:23552
	global_load_lds_dwordx4 v[208:209], off
	s_add_i32 m0, s76, 0x2000
	s_add_u32 s76, s22, 0xb0000
	v_lshl_add_u64 v[214:215], s[22:23], 0, v[132:133]
	s_addc_u32 s77, s23, 0
	s_add_i32 s75, s75, s28
	global_load_lds_dwordx4 v[214:215], off
	v_lshl_add_u64 v[226:227], s[76:77], 0, v[0:1]
	s_mov_b32 m0, s75
	v_lshl_add_u64 v[228:229], s[24:25], 0, v[134:135]
	global_load_lds_dwordx4 v[226:227], off
	v_lshl_add_u64 v[226:227], s[76:77], 0, v[132:133]
	s_add_i32 m0, s75, 0x2000
	s_nop 0
	global_load_lds_dwordx4 v[226:227], off
	v_lshl_add_u64 v[226:227], s[24:25], 0, v[136:137]
	s_mov_b32 m0, s29
	s_nop 0
	global_load_lds_dwordx4 v[226:227], off
	s_mov_b32 m0, s30
	s_nop 0
	global_load_lds_dwordx4 v[228:229], off
	s_waitcnt vmcnt(8)
	s_waitcnt lgkmcnt(0)
	s_barrier
	s_setprio 1
	s_waitcnt lgkmcnt(0)
	v_mfma_f32_16x16x32_bf16 v[62:65], v[148:151], v[180:183], v[62:65]
	v_mfma_f32_16x16x32_bf16 v[58:61], v[156:159], v[180:183], v[58:61]
	v_mfma_f32_16x16x32_bf16 v[50:53], v[148:151], v[188:191], v[50:53]
	v_mfma_f32_16x16x32_bf16 v[42:45], v[156:159], v[188:191], v[42:45]
	v_mfma_f32_16x16x32_bf16 v[34:37], v[148:151], v[196:199], v[34:37]
	v_mfma_f32_16x16x32_bf16 v[26:29], v[156:159], v[196:199], v[26:29]
	v_mfma_f32_16x16x32_bf16 v[18:21], v[148:151], v[204:207], v[18:21]
	v_mfma_f32_16x16x32_bf16 v[10:13], v[156:159], v[204:207], v[10:13]
	v_mfma_f32_16x16x32_bf16 v[62:65], v[152:155], v[184:187], v[62:65]
	v_mfma_f32_16x16x32_bf16 v[58:61], v[160:163], v[184:187], v[58:61]
	v_mfma_f32_16x16x32_bf16 v[50:53], v[152:155], v[192:195], v[50:53]
	v_mfma_f32_16x16x32_bf16 v[42:45], v[160:163], v[192:195], v[42:45]
	v_mfma_f32_16x16x32_bf16 v[34:37], v[152:155], v[200:203], v[34:37]
	v_mfma_f32_16x16x32_bf16 v[26:29], v[160:163], v[200:203], v[26:29]
	v_mfma_f32_16x16x32_bf16 v[18:21], v[152:155], v[218:221], v[18:21]
	v_mfma_f32_16x16x32_bf16 v[10:13], v[160:163], v[218:221], v[10:13]
	v_mfma_f32_16x16x32_bf16 v[54:57], v[164:167], v[180:183], v[54:57]
	v_mfma_f32_16x16x32_bf16 v[46:49], v[172:175], v[180:183], v[46:49]
	v_mfma_f32_16x16x32_bf16 v[38:41], v[164:167], v[188:191], v[38:41]
	v_mfma_f32_16x16x32_bf16 v[30:33], v[172:175], v[188:191], v[30:33]
	v_mfma_f32_16x16x32_bf16 v[22:25], v[164:167], v[196:199], v[22:25]
	v_mfma_f32_16x16x32_bf16 v[14:17], v[172:175], v[196:199], v[14:17]
	v_mfma_f32_16x16x32_bf16 v[6:9], v[164:167], v[204:207], v[6:9]
	v_mfma_f32_16x16x32_bf16 v[2:5], v[172:175], v[204:207], v[2:5]
	v_mfma_f32_16x16x32_bf16 v[54:57], v[168:171], v[184:187], v[54:57]
	v_mfma_f32_16x16x32_bf16 v[46:49], v[176:179], v[184:187], v[46:49]
	v_mfma_f32_16x16x32_bf16 v[38:41], v[168:171], v[192:195], v[38:41]
	v_mfma_f32_16x16x32_bf16 v[30:33], v[176:179], v[192:195], v[30:33]
	v_mfma_f32_16x16x32_bf16 v[22:25], v[168:171], v[200:203], v[22:25]
	v_mfma_f32_16x16x32_bf16 v[14:17], v[176:179], v[200:203], v[14:17]
	v_mfma_f32_16x16x32_bf16 v[6:9], v[168:171], v[218:221], v[6:9]
	v_mfma_f32_16x16x32_bf16 v[2:5], v[176:179], v[218:221], v[2:5]
	s_setprio 0
	s_barrier
	s_add_i32 s75, 0, 0x18000
	v_add_u32_e32 v147, s75, v131
	s_add_i32 s76, 0, 0x1c000
	ds_read_b128 v[148:151], v147
	ds_read_b128 v[152:155], v147 offset:1024
	ds_read_b128 v[156:159], v147 offset:2048
	ds_read_b128 v[160:163], v147 offset:3072
	v_add_u32_e32 v147, s76, v131
	ds_read_b128 v[164:167], v147
	ds_read_b128 v[168:171], v147 offset:1024
	ds_read_b128 v[172:175], v147 offset:2048
	ds_read_b128 v[176:179], v147 offset:3072
	s_add_u32 s24, s24, 0xb0000
	s_addc_u32 s25, s25, 0
	s_mov_b32 m0, s31
	v_lshl_add_u64 v[230:231], s[24:25], 0, v[136:137]
	ds_read_b128 v[180:183], v146 offset:32768
	ds_read_b128 v[184:187], v146 offset:33792
	ds_read_b128 v[188:191], v146 offset:34816
	ds_read_b128 v[192:195], v146 offset:35840
	ds_read_b128 v[196:199], v146 offset:36864
	ds_read_b128 v[200:203], v146 offset:37888
	ds_read_b128 v[204:207], v146 offset:38912
	ds_read_b128 v[218:221], v146 offset:39936
	global_load_lds_dwordx4 v[230:231], off
	v_lshl_add_u64 v[230:231], s[24:25], 0, v[134:135]
	s_mov_b32 m0, s34
	s_nop 0
	global_load_lds_dwordx4 v[230:231], off
	s_waitcnt vmcnt(8)
	s_waitcnt lgkmcnt(0)
	s_barrier
	s_setprio 1
	s_waitcnt lgkmcnt(0)
	v_mfma_f32_16x16x32_bf16 v[126:129], v[148:151], v[180:183], v[126:129]
	v_mfma_f32_16x16x32_bf16 v[122:125], v[156:159], v[180:183], v[122:125]
	v_mfma_f32_16x16x32_bf16 v[114:117], v[148:151], v[188:191], v[114:117]
	v_mfma_f32_16x16x32_bf16 v[106:109], v[156:159], v[188:191], v[106:109]
	v_mfma_f32_16x16x32_bf16 v[98:101], v[148:151], v[196:199], v[98:101]
	v_mfma_f32_16x16x32_bf16 v[90:93], v[156:159], v[196:199], v[90:93]
	v_mfma_f32_16x16x32_bf16 v[82:85], v[148:151], v[204:207], v[82:85]
	v_mfma_f32_16x16x32_bf16 v[74:77], v[156:159], v[204:207], v[74:77]
	v_mfma_f32_16x16x32_bf16 v[126:129], v[152:155], v[184:187], v[126:129]
	v_mfma_f32_16x16x32_bf16 v[122:125], v[160:163], v[184:187], v[122:125]
	v_mfma_f32_16x16x32_bf16 v[114:117], v[152:155], v[192:195], v[114:117]
	v_mfma_f32_16x16x32_bf16 v[106:109], v[160:163], v[192:195], v[106:109]
	v_mfma_f32_16x16x32_bf16 v[98:101], v[152:155], v[200:203], v[98:101]
	v_mfma_f32_16x16x32_bf16 v[90:93], v[160:163], v[200:203], v[90:93]
	v_mfma_f32_16x16x32_bf16 v[82:85], v[152:155], v[218:221], v[82:85]
	v_mfma_f32_16x16x32_bf16 v[74:77], v[160:163], v[218:221], v[74:77]
	v_mfma_f32_16x16x32_bf16 v[118:121], v[164:167], v[180:183], v[118:121]
	v_mfma_f32_16x16x32_bf16 v[110:113], v[172:175], v[180:183], v[110:113]
	v_mfma_f32_16x16x32_bf16 v[102:105], v[164:167], v[188:191], v[102:105]
	v_mfma_f32_16x16x32_bf16 v[94:97], v[172:175], v[188:191], v[94:97]
	v_mfma_f32_16x16x32_bf16 v[86:89], v[164:167], v[196:199], v[86:89]
	v_mfma_f32_16x16x32_bf16 v[78:81], v[172:175], v[196:199], v[78:81]
	v_mfma_f32_16x16x32_bf16 v[70:73], v[164:167], v[204:207], v[70:73]
	v_mfma_f32_16x16x32_bf16 v[66:69], v[172:175], v[204:207], v[66:69]
	v_mfma_f32_16x16x32_bf16 v[118:121], v[168:171], v[184:187], v[118:121]
	v_mfma_f32_16x16x32_bf16 v[110:113], v[176:179], v[184:187], v[110:113]
	v_mfma_f32_16x16x32_bf16 v[102:105], v[168:171], v[192:195], v[102:105]
	v_mfma_f32_16x16x32_bf16 v[94:97], v[176:179], v[192:195], v[94:97]
	v_mfma_f32_16x16x32_bf16 v[86:89], v[168:171], v[200:203], v[86:89]
	v_mfma_f32_16x16x32_bf16 v[78:81], v[176:179], v[200:203], v[78:81]
	v_mfma_f32_16x16x32_bf16 v[70:73], v[168:171], v[218:221], v[70:73]
	v_mfma_f32_16x16x32_bf16 v[66:69], v[176:179], v[218:221], v[66:69]
	s_setprio 0
	s_barrier
	s_add_i32 s24, s75, s28
	v_lshl_add_u64 v[208:209], v[208:209], 0, s[50:51]
	s_mov_b32 m0, s24
	ds_read_b128 v[180:183], v146 offset:49152
	ds_read_b128 v[184:187], v146 offset:50176
	ds_read_b128 v[188:191], v146 offset:51200
	ds_read_b128 v[192:195], v146 offset:52224
	ds_read_b128 v[196:199], v146 offset:53248
	ds_read_b128 v[200:203], v146 offset:54272
	ds_read_b128 v[204:207], v146 offset:55296
	ds_read_b128 v[218:221], v146 offset:56320
	global_load_lds_dwordx4 v[208:209], off
	s_add_i32 m0, s24, 0x2000
	s_add_u32 s22, s22, 0xb0080
	v_lshl_add_u64 v[208:209], v[214:215], 0, s[50:51]
	s_addc_u32 s23, s23, 0
	s_add_i32 s24, s76, s28
	global_load_lds_dwordx4 v[208:209], off
	v_lshl_add_u64 v[208:209], s[22:23], 0, v[0:1]
	s_mov_b32 m0, s24
	s_nop 0
	global_load_lds_dwordx4 v[208:209], off
	v_lshl_add_u64 v[208:209], s[22:23], 0, v[132:133]
	s_add_i32 m0, s24, 0x2000
	s_nop 0
	global_load_lds_dwordx4 v[208:209], off
	v_lshl_add_u64 v[208:209], v[226:227], 0, s[50:51]
	s_mov_b32 m0, s35
	s_nop 0
	global_load_lds_dwordx4 v[208:209], off
	v_lshl_add_u64 v[208:209], v[228:229], 0, s[50:51]
	s_mov_b32 m0, s36
	s_nop 0
	global_load_lds_dwordx4 v[208:209], off
	s_waitcnt vmcnt(8)
	s_waitcnt lgkmcnt(0)
	s_barrier
	s_setprio 1
	s_waitcnt lgkmcnt(0)
	v_mfma_f32_16x16x32_bf16 v[62:65], v[148:151], v[180:183], v[62:65]
	v_mfma_f32_16x16x32_bf16 v[58:61], v[156:159], v[180:183], v[58:61]
	v_mfma_f32_16x16x32_bf16 v[50:53], v[148:151], v[188:191], v[50:53]
	v_mfma_f32_16x16x32_bf16 v[42:45], v[156:159], v[188:191], v[42:45]
	v_mfma_f32_16x16x32_bf16 v[34:37], v[148:151], v[196:199], v[34:37]
	v_mfma_f32_16x16x32_bf16 v[26:29], v[156:159], v[196:199], v[26:29]
	v_mfma_f32_16x16x32_bf16 v[18:21], v[148:151], v[204:207], v[18:21]
	v_mfma_f32_16x16x32_bf16 v[10:13], v[156:159], v[204:207], v[10:13]
	v_mfma_f32_16x16x32_bf16 v[62:65], v[152:155], v[184:187], v[62:65]
	v_mfma_f32_16x16x32_bf16 v[58:61], v[160:163], v[184:187], v[58:61]
	v_mfma_f32_16x16x32_bf16 v[50:53], v[152:155], v[192:195], v[50:53]
	v_mfma_f32_16x16x32_bf16 v[42:45], v[160:163], v[192:195], v[42:45]
	v_mfma_f32_16x16x32_bf16 v[34:37], v[152:155], v[200:203], v[34:37]
	v_mfma_f32_16x16x32_bf16 v[26:29], v[160:163], v[200:203], v[26:29]
	v_mfma_f32_16x16x32_bf16 v[18:21], v[152:155], v[218:221], v[18:21]
	v_mfma_f32_16x16x32_bf16 v[10:13], v[160:163], v[218:221], v[10:13]
	v_mfma_f32_16x16x32_bf16 v[54:57], v[164:167], v[180:183], v[54:57]
	v_mfma_f32_16x16x32_bf16 v[46:49], v[172:175], v[180:183], v[46:49]
	v_mfma_f32_16x16x32_bf16 v[38:41], v[164:167], v[188:191], v[38:41]
	v_mfma_f32_16x16x32_bf16 v[30:33], v[172:175], v[188:191], v[30:33]
	v_mfma_f32_16x16x32_bf16 v[22:25], v[164:167], v[196:199], v[22:25]
	v_mfma_f32_16x16x32_bf16 v[14:17], v[172:175], v[196:199], v[14:17]
	v_mfma_f32_16x16x32_bf16 v[6:9], v[164:167], v[204:207], v[6:9]
	v_mfma_f32_16x16x32_bf16 v[2:5], v[172:175], v[204:207], v[2:5]
	v_mfma_f32_16x16x32_bf16 v[54:57], v[168:171], v[184:187], v[54:57]
	v_mfma_f32_16x16x32_bf16 v[46:49], v[176:179], v[184:187], v[46:49]
	v_mfma_f32_16x16x32_bf16 v[38:41], v[168:171], v[192:195], v[38:41]
	v_mfma_f32_16x16x32_bf16 v[30:33], v[176:179], v[192:195], v[30:33]
	v_mfma_f32_16x16x32_bf16 v[22:25], v[168:171], v[200:203], v[22:25]
	v_mfma_f32_16x16x32_bf16 v[14:17], v[176:179], v[200:203], v[14:17]
	v_mfma_f32_16x16x32_bf16 v[6:9], v[168:171], v[218:221], v[6:9]
	v_mfma_f32_16x16x32_bf16 v[2:5], v[176:179], v[218:221], v[2:5]
	s_setprio 0
	s_barrier
	s_add_i32 s74, s74, 2
	s_add_u32 s20, s20, 0x100
	s_addc_u32 s21, s21, 0
	s_cmp_gt_u32 s74, 41
	s_cbranch_scc0 .LBB0_1226
	s_add_u32 s20, s72, 0xffffff00
	s_addc_u32 s21, s73, -1
	s_and_b64 vcc, exec, s[6:7]
	s_cbranch_vccnz .LBB0_1229
	v_mov_b32_e32 v2, 0
	s_mov_b32 s14, s38
	s_mov_b32 s10, s39
	s_mov_b64 s[16:17], s[18:19]
	s_mov_b32 s37, s71
	v_mov_b32_e32 v3, v2
	v_mov_b32_e32 v4, v2
	v_mov_b32_e32 v5, v2
	v_mov_b32_e32 v6, v2
	v_mov_b32_e32 v7, v2
	v_mov_b32_e32 v8, v2
	v_mov_b32_e32 v9, v2
	v_mov_b32_e32 v14, v2
	v_mov_b32_e32 v15, v2
	v_mov_b32_e32 v16, v2
	v_mov_b32_e32 v17, v2
	v_mov_b32_e32 v22, v2
	v_mov_b32_e32 v23, v2
	v_mov_b32_e32 v24, v2
	v_mov_b32_e32 v25, v2
	v_mov_b32_e32 v30, v2
	v_mov_b32_e32 v31, v2
	v_mov_b32_e32 v32, v2
	v_mov_b32_e32 v33, v2
	v_mov_b32_e32 v38, v2
	v_mov_b32_e32 v39, v2
	v_mov_b32_e32 v40, v2
	v_mov_b32_e32 v41, v2
	v_mov_b32_e32 v46, v2
	v_mov_b32_e32 v47, v2
	v_mov_b32_e32 v48, v2
	v_mov_b32_e32 v49, v2
	v_mov_b32_e32 v54, v2
	v_mov_b32_e32 v55, v2
	v_mov_b32_e32 v56, v2
	v_mov_b32_e32 v57, v2
	v_mov_b32_e32 v10, v2
	v_mov_b32_e32 v11, v2
	v_mov_b32_e32 v12, v2
	v_mov_b32_e32 v13, v2
	v_mov_b32_e32 v18, v2
	v_mov_b32_e32 v19, v2
	v_mov_b32_e32 v20, v2
	v_mov_b32_e32 v21, v2
	v_mov_b32_e32 v26, v2
	v_mov_b32_e32 v27, v2
	v_mov_b32_e32 v28, v2
	v_mov_b32_e32 v29, v2
	v_mov_b32_e32 v34, v2
	v_mov_b32_e32 v35, v2
	v_mov_b32_e32 v36, v2
	v_mov_b32_e32 v37, v2
	v_mov_b32_e32 v42, v2
	v_mov_b32_e32 v43, v2
	v_mov_b32_e32 v44, v2
	v_mov_b32_e32 v45, v2
	v_mov_b32_e32 v50, v2
	v_mov_b32_e32 v51, v2
	v_mov_b32_e32 v52, v2
	v_mov_b32_e32 v53, v2
	v_mov_b32_e32 v58, v2
	v_mov_b32_e32 v59, v2
	v_mov_b32_e32 v60, v2
	v_mov_b32_e32 v61, v2
	v_mov_b32_e32 v62, v2
	v_mov_b32_e32 v63, v2
	v_mov_b32_e32 v64, v2
	v_mov_b32_e32 v65, v2
	v_mov_b32_e32 v66, v2
	v_mov_b32_e32 v67, v2
	v_mov_b32_e32 v68, v2
	v_mov_b32_e32 v69, v2
	v_mov_b32_e32 v70, v2
	v_mov_b32_e32 v71, v2
	v_mov_b32_e32 v72, v2
	v_mov_b32_e32 v73, v2
	v_mov_b32_e32 v78, v2
	v_mov_b32_e32 v79, v2
	v_mov_b32_e32 v80, v2
	v_mov_b32_e32 v81, v2
	v_mov_b32_e32 v86, v2
	v_mov_b32_e32 v87, v2
	v_mov_b32_e32 v88, v2
	v_mov_b32_e32 v89, v2
	v_mov_b32_e32 v94, v2
	v_mov_b32_e32 v95, v2
	v_mov_b32_e32 v96, v2
	v_mov_b32_e32 v97, v2
	v_mov_b32_e32 v102, v2
	v_mov_b32_e32 v103, v2
	v_mov_b32_e32 v104, v2
	v_mov_b32_e32 v105, v2
	v_mov_b32_e32 v110, v2
	v_mov_b32_e32 v111, v2
	v_mov_b32_e32 v112, v2
	v_mov_b32_e32 v113, v2
	v_mov_b32_e32 v118, v2
	v_mov_b32_e32 v119, v2
	v_mov_b32_e32 v120, v2
	v_mov_b32_e32 v121, v2
	v_mov_b32_e32 v74, v2
	v_mov_b32_e32 v75, v2
	v_mov_b32_e32 v76, v2
	v_mov_b32_e32 v77, v2
	v_mov_b32_e32 v82, v2
	v_mov_b32_e32 v83, v2
	v_mov_b32_e32 v84, v2
	v_mov_b32_e32 v85, v2
	v_mov_b32_e32 v90, v2
	v_mov_b32_e32 v91, v2
	v_mov_b32_e32 v92, v2
	v_mov_b32_e32 v93, v2
	v_mov_b32_e32 v98, v2
	v_mov_b32_e32 v99, v2
	v_mov_b32_e32 v100, v2
	v_mov_b32_e32 v101, v2
	v_mov_b32_e32 v106, v2
	v_mov_b32_e32 v107, v2
	v_mov_b32_e32 v108, v2
	v_mov_b32_e32 v109, v2
	v_mov_b32_e32 v114, v2
	v_mov_b32_e32 v115, v2
	v_mov_b32_e32 v116, v2
	v_mov_b32_e32 v117, v2
	v_mov_b32_e32 v122, v2
	v_mov_b32_e32 v123, v2
	v_mov_b32_e32 v124, v2
	v_mov_b32_e32 v125, v2
	v_mov_b32_e32 v126, v2
	v_mov_b32_e32 v127, v2
	v_mov_b32_e32 v128, v2
	v_mov_b32_e32 v129, v2
	s_andn2_b64 vcc, exec, s[4:5]
	s_cbranch_vccnz .LBB0_1230
	s_branch .LBB0_1231
